# GEMM MFMA segments: mid-block s_setprio 0/1 pair and the redundant post-barrier lgkmcnt(0) removed
# speedup vs baseline: 1.0076x; 1.0023x over previous
.LBB0_170:
	ds_read_b128 v[148:151], v165
	ds_read_b128 v[152:155], v165 offset:1024
	ds_read_b128 v[156:159], v165 offset:2048
	ds_read_b128 v[160:163], v165 offset:3072
	ds_read_b128 v[170:173], v166
	ds_read_b128 v[174:177], v166 offset:1024
	ds_read_b128 v[178:181], v166 offset:2048
	ds_read_b128 v[182:185], v166 offset:3072
	s_add_u32 s28, s52, 0xfffc0080
	s_addc_u32 s29, s53, -1
	s_cmp_eq_u32 s73, 12
	s_cselect_b32 s31, s15, s29
	s_cselect_b32 s30, s69, s28
	s_cselect_b32 s29, s13, s72
	s_cselect_b32 s28, s70, s71
	s_add_i32 m0, s21, 0xc000
	ds_read_b128 v[186:189], v167
	ds_read_b128 v[190:193], v167 offset:1024
	ds_read_b128 v[194:197], v167 offset:2048
	ds_read_b128 v[198:201], v167 offset:3072
	ds_read_b128 v[202:205], v167 offset:4096
	ds_read_b128 v[206:209], v167 offset:5120
	ds_read_b128 v[210:213], v167 offset:6144
	ds_read_b128 v[214:217], v167 offset:7168
	global_load_lds_dwordx4 v140, s[52:53]
	s_add_i32 m0, s21, 0xe000
	s_nop 0
	global_load_lds_dwordx4 v142, s[52:53]
	s_waitcnt vmcnt(8)
	s_waitcnt lgkmcnt(0)
	s_barrier
	s_setprio 1
	v_mfma_f32_16x16x32_bf16 v[126:129], v[148:151], v[186:189], v[126:129]
	v_mfma_f32_16x16x32_bf16 v[118:121], v[156:159], v[186:189], v[118:121]
	v_mfma_f32_16x16x32_bf16 v[110:113], v[148:151], v[194:197], v[110:113]
	v_mfma_f32_16x16x32_bf16 v[102:105], v[156:159], v[194:197], v[102:105]
	v_mfma_f32_16x16x32_bf16 v[94:97], v[148:151], v[202:205], v[94:97]
	v_mfma_f32_16x16x32_bf16 v[86:89], v[156:159], v[202:205], v[86:89]
	v_mfma_f32_16x16x32_bf16 v[78:81], v[148:151], v[210:213], v[78:81]
	v_mfma_f32_16x16x32_bf16 v[70:73], v[156:159], v[210:213], v[70:73]
	v_mfma_f32_16x16x32_bf16 v[126:129], v[152:155], v[190:193], v[126:129]
	v_mfma_f32_16x16x32_bf16 v[118:121], v[160:163], v[190:193], v[118:121]
	v_mfma_f32_16x16x32_bf16 v[110:113], v[152:155], v[198:201], v[110:113]
	v_mfma_f32_16x16x32_bf16 v[102:105], v[160:163], v[198:201], v[102:105]
	v_mfma_f32_16x16x32_bf16 v[94:97], v[152:155], v[206:209], v[94:97]
	v_mfma_f32_16x16x32_bf16 v[86:89], v[160:163], v[206:209], v[86:89]
	v_mfma_f32_16x16x32_bf16 v[78:81], v[152:155], v[214:217], v[78:81]
	v_mfma_f32_16x16x32_bf16 v[70:73], v[160:163], v[214:217], v[70:73]
	v_mfma_f32_16x16x32_bf16 v[122:125], v[170:173], v[186:189], v[122:125]
	v_mfma_f32_16x16x32_bf16 v[114:117], v[178:181], v[186:189], v[114:117]
	v_mfma_f32_16x16x32_bf16 v[106:109], v[170:173], v[194:197], v[106:109]
	v_mfma_f32_16x16x32_bf16 v[98:101], v[178:181], v[194:197], v[98:101]
	v_mfma_f32_16x16x32_bf16 v[90:93], v[170:173], v[202:205], v[90:93]
	v_mfma_f32_16x16x32_bf16 v[82:85], v[178:181], v[202:205], v[82:85]
	v_mfma_f32_16x16x32_bf16 v[74:77], v[170:173], v[210:213], v[74:77]
	v_mfma_f32_16x16x32_bf16 v[66:69], v[178:181], v[210:213], v[66:69]
	v_mfma_f32_16x16x32_bf16 v[122:125], v[174:177], v[190:193], v[122:125]
	v_mfma_f32_16x16x32_bf16 v[114:117], v[182:185], v[190:193], v[114:117]
	v_mfma_f32_16x16x32_bf16 v[106:109], v[174:177], v[198:201], v[106:109]
	v_mfma_f32_16x16x32_bf16 v[98:101], v[182:185], v[198:201], v[98:101]
	v_mfma_f32_16x16x32_bf16 v[90:93], v[174:177], v[206:209], v[90:93]
	v_mfma_f32_16x16x32_bf16 v[82:85], v[182:185], v[206:209], v[82:85]
	v_mfma_f32_16x16x32_bf16 v[74:77], v[174:177], v[214:217], v[74:77]
	v_mfma_f32_16x16x32_bf16 v[66:69], v[182:185], v[214:217], v[66:69]
	s_setprio 0
	s_barrier
	s_add_i32 s74, s59, s24
	s_mov_b32 m0, s74
	ds_read_b128 v[186:189], v167 offset:16384
	ds_read_b128 v[190:193], v167 offset:17408
	ds_read_b128 v[194:197], v167 offset:18432
	ds_read_b128 v[198:201], v167 offset:19456
	ds_read_b128 v[202:205], v167 offset:20480
	ds_read_b128 v[206:209], v167 offset:21504
	ds_read_b128 v[210:213], v167 offset:22528
	ds_read_b128 v[214:217], v167 offset:23552
	global_load_lds_dwordx4 v134, s[28:29]
	s_add_i32 m0, s74, 0x2000
	s_add_u32 s74, s28, 0x40000
	s_addc_u32 s75, s29, 0
	s_add_i32 s76, s66, s24
	global_load_lds_dwordx4 v130, s[28:29]
	s_mov_b32 m0, s76
	s_nop 0
	global_load_lds_dwordx4 v134, s[74:75]
	s_add_i32 m0, s76, 0x2000
	s_nop 0
	global_load_lds_dwordx4 v130, s[74:75]
	s_mov_b32 m0, s21
	s_nop 0
	global_load_lds_dwordx4 v136, s[30:31]
	s_mov_b32 m0, s34
	s_nop 0
	global_load_lds_dwordx4 v132, s[30:31]
	s_waitcnt vmcnt(8)
	s_waitcnt lgkmcnt(0)
	s_barrier
	s_setprio 1
	v_mfma_f32_16x16x32_bf16 v[62:65], v[148:151], v[186:189], v[62:65]
	v_mfma_f32_16x16x32_bf16 v[54:57], v[156:159], v[186:189], v[54:57]
	v_mfma_f32_16x16x32_bf16 v[46:49], v[148:151], v[194:197], v[46:49]
	v_mfma_f32_16x16x32_bf16 v[38:41], v[156:159], v[194:197], v[38:41]
	v_mfma_f32_16x16x32_bf16 v[30:33], v[148:151], v[202:205], v[30:33]
	v_mfma_f32_16x16x32_bf16 v[22:25], v[156:159], v[202:205], v[22:25]
	v_mfma_f32_16x16x32_bf16 v[14:17], v[148:151], v[210:213], v[14:17]
	v_mfma_f32_16x16x32_bf16 v[6:9], v[156:159], v[210:213], v[6:9]
	v_mfma_f32_16x16x32_bf16 v[62:65], v[152:155], v[190:193], v[62:65]
	v_mfma_f32_16x16x32_bf16 v[54:57], v[160:163], v[190:193], v[54:57]
	v_mfma_f32_16x16x32_bf16 v[46:49], v[152:155], v[198:201], v[46:49]
	v_mfma_f32_16x16x32_bf16 v[38:41], v[160:163], v[198:201], v[38:41]
	v_mfma_f32_16x16x32_bf16 v[30:33], v[152:155], v[206:209], v[30:33]
	v_mfma_f32_16x16x32_bf16 v[22:25], v[160:163], v[206:209], v[22:25]
	v_mfma_f32_16x16x32_bf16 v[14:17], v[152:155], v[214:217], v[14:17]
	v_mfma_f32_16x16x32_bf16 v[6:9], v[160:163], v[214:217], v[6:9]
	v_mfma_f32_16x16x32_bf16 v[58:61], v[170:173], v[186:189], v[58:61]
	v_mfma_f32_16x16x32_bf16 v[50:53], v[178:181], v[186:189], v[50:53]
	v_mfma_f32_16x16x32_bf16 v[42:45], v[170:173], v[194:197], v[42:45]
	v_mfma_f32_16x16x32_bf16 v[34:37], v[178:181], v[194:197], v[34:37]
	v_mfma_f32_16x16x32_bf16 v[26:29], v[170:173], v[202:205], v[26:29]
	v_mfma_f32_16x16x32_bf16 v[18:21], v[178:181], v[202:205], v[18:21]
	v_mfma_f32_16x16x32_bf16 v[10:13], v[170:173], v[210:213], v[10:13]
	v_mfma_f32_16x16x32_bf16 v[2:5], v[178:181], v[210:213], v[2:5]
	v_mfma_f32_16x16x32_bf16 v[58:61], v[174:177], v[190:193], v[58:61]
	v_mfma_f32_16x16x32_bf16 v[50:53], v[182:185], v[190:193], v[50:53]
	v_mfma_f32_16x16x32_bf16 v[42:45], v[174:177], v[198:201], v[42:45]
	v_mfma_f32_16x16x32_bf16 v[34:37], v[182:185], v[198:201], v[34:37]
	v_mfma_f32_16x16x32_bf16 v[26:29], v[174:177], v[206:209], v[26:29]
	v_mfma_f32_16x16x32_bf16 v[18:21], v[182:185], v[206:209], v[18:21]
	v_mfma_f32_16x16x32_bf16 v[10:13], v[174:177], v[214:217], v[10:13]
	v_mfma_f32_16x16x32_bf16 v[2:5], v[182:185], v[214:217], v[2:5]
	s_setprio 0
	s_barrier
	s_add_i32 s74, 0, 0x18000
	s_add_i32 s75, 0, 0x1c000
	v_add_u32_e32 v160, s74, v139
	v_add_u32_e32 v169, s75, v139
	ds_read_b128 v[148:151], v160
	ds_read_b128 v[152:155], v160 offset:1024
	ds_read_b128 v[156:159], v160 offset:2048
	ds_read_b128 v[160:163], v160 offset:3072
	ds_read_b128 v[170:173], v169
	ds_read_b128 v[174:177], v169 offset:1024
	ds_read_b128 v[178:181], v169 offset:2048
	ds_read_b128 v[182:185], v169 offset:3072
	s_add_u32 s98, s30, 0x40000
	s_addc_u32 s99, s31, 0
	s_mov_b32 m0, s35
	ds_read_b128 v[186:189], v167 offset:32768
	ds_read_b128 v[190:193], v167 offset:33792
	ds_read_b128 v[194:197], v167 offset:34816
	ds_read_b128 v[198:201], v167 offset:35840
	ds_read_b128 v[202:205], v167 offset:36864
	ds_read_b128 v[206:209], v167 offset:37888
	ds_read_b128 v[210:213], v167 offset:38912
	ds_read_b128 v[214:217], v167 offset:39936
	global_load_lds_dwordx4 v136, s[98:99]
	s_mov_b32 m0, s54
	s_nop 0
	global_load_lds_dwordx4 v132, s[98:99]
	s_waitcnt vmcnt(8)
	s_waitcnt lgkmcnt(0)
	s_barrier
	s_setprio 1
	v_mfma_f32_16x16x32_bf16 v[126:129], v[148:151], v[186:189], v[126:129]
	v_mfma_f32_16x16x32_bf16 v[118:121], v[156:159], v[186:189], v[118:121]
	v_mfma_f32_16x16x32_bf16 v[110:113], v[148:151], v[194:197], v[110:113]
	v_mfma_f32_16x16x32_bf16 v[102:105], v[156:159], v[194:197], v[102:105]
	v_mfma_f32_16x16x32_bf16 v[94:97], v[148:151], v[202:205], v[94:97]
	v_mfma_f32_16x16x32_bf16 v[86:89], v[156:159], v[202:205], v[86:89]
	v_mfma_f32_16x16x32_bf16 v[78:81], v[148:151], v[210:213], v[78:81]
	v_mfma_f32_16x16x32_bf16 v[70:73], v[156:159], v[210:213], v[70:73]
	v_mfma_f32_16x16x32_bf16 v[126:129], v[152:155], v[190:193], v[126:129]
	v_mfma_f32_16x16x32_bf16 v[118:121], v[160:163], v[190:193], v[118:121]
	v_mfma_f32_16x16x32_bf16 v[110:113], v[152:155], v[198:201], v[110:113]
	v_mfma_f32_16x16x32_bf16 v[102:105], v[160:163], v[198:201], v[102:105]
	v_mfma_f32_16x16x32_bf16 v[94:97], v[152:155], v[206:209], v[94:97]
	v_mfma_f32_16x16x32_bf16 v[86:89], v[160:163], v[206:209], v[86:89]
	v_mfma_f32_16x16x32_bf16 v[78:81], v[152:155], v[214:217], v[78:81]
	v_mfma_f32_16x16x32_bf16 v[70:73], v[160:163], v[214:217], v[70:73]
	v_mfma_f32_16x16x32_bf16 v[122:125], v[170:173], v[186:189], v[122:125]
	v_mfma_f32_16x16x32_bf16 v[114:117], v[178:181], v[186:189], v[114:117]
	v_mfma_f32_16x16x32_bf16 v[106:109], v[170:173], v[194:197], v[106:109]
	v_mfma_f32_16x16x32_bf16 v[98:101], v[178:181], v[194:197], v[98:101]
	v_mfma_f32_16x16x32_bf16 v[90:93], v[170:173], v[202:205], v[90:93]
	v_mfma_f32_16x16x32_bf16 v[82:85], v[178:181], v[202:205], v[82:85]
	v_mfma_f32_16x16x32_bf16 v[74:77], v[170:173], v[210:213], v[74:77]
	v_mfma_f32_16x16x32_bf16 v[66:69], v[178:181], v[210:213], v[66:69]
	v_mfma_f32_16x16x32_bf16 v[122:125], v[174:177], v[190:193], v[122:125]
	v_mfma_f32_16x16x32_bf16 v[114:117], v[182:185], v[190:193], v[114:117]
	v_mfma_f32_16x16x32_bf16 v[106:109], v[174:177], v[198:201], v[106:109]
	v_mfma_f32_16x16x32_bf16 v[98:101], v[182:185], v[198:201], v[98:101]
	v_mfma_f32_16x16x32_bf16 v[90:93], v[174:177], v[206:209], v[90:93]
	v_mfma_f32_16x16x32_bf16 v[82:85], v[182:185], v[206:209], v[82:85]
	v_mfma_f32_16x16x32_bf16 v[74:77], v[174:177], v[214:217], v[74:77]
	v_mfma_f32_16x16x32_bf16 v[66:69], v[182:185], v[214:217], v[66:69]
	s_setprio 0
	s_barrier
	s_add_i32 s98, s74, s24
	s_add_i32 m0, s98, 0xffffff80
	ds_read_b128 v[186:189], v167 offset:49152
	ds_read_b128 v[190:193], v167 offset:50176
	ds_read_b128 v[194:197], v167 offset:51200
	ds_read_b128 v[198:201], v167 offset:52224
	ds_read_b128 v[202:205], v167 offset:53248
	ds_read_b128 v[206:209], v167 offset:54272
	ds_read_b128 v[210:213], v167 offset:55296
	ds_read_b128 v[214:217], v167 offset:56320
	global_load_lds_dwordx4 v134, s[28:29] offset:128
	s_add_i32 m0, s98, 0x1f80
	s_add_i32 s98, s75, s24
	global_load_lds_dwordx4 v130, s[28:29] offset:128
	s_add_u32 s28, s28, 0x40080
	s_addc_u32 s29, s29, 0
	s_mov_b32 m0, s98
	s_nop 0
	global_load_lds_dwordx4 v134, s[28:29]
	s_add_i32 m0, s98, 0x2000
	s_nop 0
	global_load_lds_dwordx4 v130, s[28:29]
	s_add_i32 m0, s56, 0xffffff80
	s_nop 0
	global_load_lds_dwordx4 v136, s[30:31] offset:128
	s_add_i32 m0, s57, 0xffffff80
	s_nop 0
	global_load_lds_dwordx4 v132, s[30:31] offset:128
	s_waitcnt vmcnt(8)
	s_waitcnt lgkmcnt(0)
	s_barrier
	s_setprio 1
	v_mfma_f32_16x16x32_bf16 v[62:65], v[148:151], v[186:189], v[62:65]
	v_mfma_f32_16x16x32_bf16 v[54:57], v[156:159], v[186:189], v[54:57]
	v_mfma_f32_16x16x32_bf16 v[46:49], v[148:151], v[194:197], v[46:49]
	v_mfma_f32_16x16x32_bf16 v[38:41], v[156:159], v[194:197], v[38:41]
	v_mfma_f32_16x16x32_bf16 v[30:33], v[148:151], v[202:205], v[30:33]
	v_mfma_f32_16x16x32_bf16 v[22:25], v[156:159], v[202:205], v[22:25]
	v_mfma_f32_16x16x32_bf16 v[14:17], v[148:151], v[210:213], v[14:17]
	v_mfma_f32_16x16x32_bf16 v[6:9], v[156:159], v[210:213], v[6:9]
	v_mfma_f32_16x16x32_bf16 v[62:65], v[152:155], v[190:193], v[62:65]
	v_mfma_f32_16x16x32_bf16 v[54:57], v[160:163], v[190:193], v[54:57]
	v_mfma_f32_16x16x32_bf16 v[46:49], v[152:155], v[198:201], v[46:49]
	v_mfma_f32_16x16x32_bf16 v[38:41], v[160:163], v[198:201], v[38:41]
	v_mfma_f32_16x16x32_bf16 v[30:33], v[152:155], v[206:209], v[30:33]
	v_mfma_f32_16x16x32_bf16 v[22:25], v[160:163], v[206:209], v[22:25]
	v_mfma_f32_16x16x32_bf16 v[14:17], v[152:155], v[214:217], v[14:17]
	v_mfma_f32_16x16x32_bf16 v[6:9], v[160:163], v[214:217], v[6:9]
	v_mfma_f32_16x16x32_bf16 v[58:61], v[170:173], v[186:189], v[58:61]
	v_mfma_f32_16x16x32_bf16 v[50:53], v[178:181], v[186:189], v[50:53]
	v_mfma_f32_16x16x32_bf16 v[42:45], v[170:173], v[194:197], v[42:45]
	v_mfma_f32_16x16x32_bf16 v[34:37], v[178:181], v[194:197], v[34:37]
	v_mfma_f32_16x16x32_bf16 v[26:29], v[170:173], v[202:205], v[26:29]
	v_mfma_f32_16x16x32_bf16 v[18:21], v[178:181], v[202:205], v[18:21]
	v_mfma_f32_16x16x32_bf16 v[10:13], v[170:173], v[210:213], v[10:13]
	v_mfma_f32_16x16x32_bf16 v[2:5], v[178:181], v[210:213], v[2:5]
	v_mfma_f32_16x16x32_bf16 v[58:61], v[174:177], v[190:193], v[58:61]
	v_mfma_f32_16x16x32_bf16 v[50:53], v[182:185], v[190:193], v[50:53]
	v_mfma_f32_16x16x32_bf16 v[42:45], v[174:177], v[198:201], v[42:45]
	v_mfma_f32_16x16x32_bf16 v[34:37], v[182:185], v[198:201], v[34:37]
	v_mfma_f32_16x16x32_bf16 v[26:29], v[174:177], v[206:209], v[26:29]
	v_mfma_f32_16x16x32_bf16 v[18:21], v[182:185], v[206:209], v[18:21]
	v_mfma_f32_16x16x32_bf16 v[10:13], v[174:177], v[214:217], v[10:13]
	v_mfma_f32_16x16x32_bf16 v[2:5], v[182:185], v[214:217], v[2:5]
	s_setprio 0
	s_barrier
	s_add_i32 s73, s73, 2
	s_add_u32 s52, s52, 0x100
	s_addc_u32 s53, s53, 0
	s_add_u32 s71, s71, 0x100
	s_addc_u32 s72, s72, 0
	s_cmp_gt_u32 s73, 13
	s_cbranch_scc0 .LBB0_170
	s_and_b64 vcc, exec, s[10:11]
	s_cbranch_vccz .LBB0_173
	s_barrier

.LBB0_730:
	v_add_u32_e32 v155, s58, v153
	ds_read_b128 v[156:159], v155
	ds_read_b128 v[160:163], v155 offset:1024
	ds_read_b128 v[164:167], v155 offset:2048
	ds_read_b128 v[168:171], v155 offset:3072
	v_add_u32_e32 v155, s59, v153
	s_add_u32 s20, s10, s18
	ds_read_b128 v[172:175], v155
	ds_read_b128 v[176:179], v155 offset:1024
	ds_read_b128 v[180:183], v155 offset:2048
	ds_read_b128 v[184:187], v155 offset:3072
	s_addc_u32 s21, s11, s19
	s_add_u32 s20, s20, 0x100
	s_addc_u32 s21, s21, 0
	s_add_u32 s64, s15, s18
	s_addc_u32 s65, s62, s19
	s_cmpk_eq_i32 s18, 0x1500
	s_cselect_b32 s29, s17, s21
	s_cselect_b32 s28, s16, s20
	s_cselect_b32 s21, s1, s65
	s_cselect_b32 s20, s0, s64
	v_lshl_add_u64 v[220:221], v[148:149], 0, s[18:19]
	s_add_i32 m0, s51, 0xc000
	ds_read_b128 v[188:191], v154
	ds_read_b128 v[192:195], v154 offset:1024
	ds_read_b128 v[196:199], v154 offset:2048
	ds_read_b128 v[200:203], v154 offset:3072
	ds_read_b128 v[204:207], v154 offset:4096
	ds_read_b128 v[208:211], v154 offset:5120
	ds_read_b128 v[212:215], v154 offset:6144
	ds_read_b128 v[216:219], v154 offset:7168
	global_load_lds_dwordx4 v[220:221], off
	v_lshl_add_u64 v[220:221], v[150:151], 0, s[18:19]
	s_add_i32 m0, s51, 0xe000
	s_nop 0
	global_load_lds_dwordx4 v[220:221], off
	s_waitcnt vmcnt(8)
	s_waitcnt lgkmcnt(0)
	s_barrier
	s_setprio 1
	v_mfma_f32_16x16x32_bf16 v[126:129], v[156:159], v[188:191], v[126:129]
	v_mfma_f32_16x16x32_bf16 v[122:125], v[164:167], v[188:191], v[122:125]
	v_mfma_f32_16x16x32_bf16 v[110:113], v[156:159], v[196:199], v[110:113]
	v_mfma_f32_16x16x32_bf16 v[106:109], v[164:167], v[196:199], v[106:109]
	v_mfma_f32_16x16x32_bf16 v[94:97], v[156:159], v[204:207], v[94:97]
	v_mfma_f32_16x16x32_bf16 v[90:93], v[164:167], v[204:207], v[90:93]
	v_mfma_f32_16x16x32_bf16 v[78:81], v[156:159], v[212:215], v[78:81]
	v_mfma_f32_16x16x32_bf16 v[74:77], v[164:167], v[212:215], v[74:77]
	v_mfma_f32_16x16x32_bf16 v[126:129], v[160:163], v[192:195], v[126:129]
	v_mfma_f32_16x16x32_bf16 v[122:125], v[168:171], v[192:195], v[122:125]
	v_mfma_f32_16x16x32_bf16 v[110:113], v[160:163], v[200:203], v[110:113]
	v_mfma_f32_16x16x32_bf16 v[106:109], v[168:171], v[200:203], v[106:109]
	v_mfma_f32_16x16x32_bf16 v[94:97], v[160:163], v[208:211], v[94:97]
	v_mfma_f32_16x16x32_bf16 v[90:93], v[168:171], v[208:211], v[90:93]
	v_mfma_f32_16x16x32_bf16 v[78:81], v[160:163], v[216:219], v[78:81]
	v_mfma_f32_16x16x32_bf16 v[74:77], v[168:171], v[216:219], v[74:77]
	v_mfma_f32_16x16x32_bf16 v[118:121], v[172:175], v[188:191], v[118:121]
	v_mfma_f32_16x16x32_bf16 v[114:117], v[180:183], v[188:191], v[114:117]
	v_mfma_f32_16x16x32_bf16 v[102:105], v[172:175], v[196:199], v[102:105]
	v_mfma_f32_16x16x32_bf16 v[98:101], v[180:183], v[196:199], v[98:101]
	v_mfma_f32_16x16x32_bf16 v[86:89], v[172:175], v[204:207], v[86:89]
	v_mfma_f32_16x16x32_bf16 v[82:85], v[180:183], v[204:207], v[82:85]
	v_mfma_f32_16x16x32_bf16 v[70:73], v[172:175], v[212:215], v[70:73]
	v_mfma_f32_16x16x32_bf16 v[66:69], v[180:183], v[212:215], v[66:69]
	v_mfma_f32_16x16x32_bf16 v[118:121], v[176:179], v[192:195], v[118:121]
	v_mfma_f32_16x16x32_bf16 v[114:117], v[184:187], v[192:195], v[114:117]
	v_mfma_f32_16x16x32_bf16 v[102:105], v[176:179], v[200:203], v[102:105]
	v_mfma_f32_16x16x32_bf16 v[98:101], v[184:187], v[200:203], v[98:101]
	v_mfma_f32_16x16x32_bf16 v[86:89], v[176:179], v[208:211], v[86:89]
	v_mfma_f32_16x16x32_bf16 v[82:85], v[184:187], v[208:211], v[82:85]
	v_mfma_f32_16x16x32_bf16 v[70:73], v[176:179], v[216:219], v[70:73]
	v_mfma_f32_16x16x32_bf16 v[66:69], v[184:187], v[216:219], v[66:69]
	s_setprio 0
	s_barrier
	s_add_i32 s64, s58, s35
	s_mov_b32 m0, s64
	ds_read_b128 v[188:191], v154 offset:16384
	ds_read_b128 v[192:195], v154 offset:17408
	ds_read_b128 v[196:199], v154 offset:18432
	ds_read_b128 v[200:203], v154 offset:19456
	ds_read_b128 v[204:207], v154 offset:20480
	ds_read_b128 v[208:211], v154 offset:21504
	ds_read_b128 v[212:215], v154 offset:22528
	ds_read_b128 v[216:219], v154 offset:23552
	global_load_lds_dwordx4 v132, s[20:21]
	s_add_i32 m0, s64, 0x2000
	s_add_u32 s64, s20, 0xb0000
	s_addc_u32 s65, s21, 0
	s_add_i32 s66, s59, s35
	global_load_lds_dwordx4 v136, s[20:21]
	s_mov_b32 m0, s66
	s_nop 0
	global_load_lds_dwordx4 v132, s[64:65]
	s_add_i32 m0, s66, 0x2000
	s_nop 0
	global_load_lds_dwordx4 v136, s[64:65]
	s_mov_b32 m0, s51
	s_nop 0
	global_load_lds_dwordx4 v130, s[28:29]
	s_mov_b32 m0, s52
	s_nop 0
	global_load_lds_dwordx4 v134, s[28:29]
	s_waitcnt vmcnt(8)
	s_waitcnt lgkmcnt(0)
	s_barrier
	s_setprio 1
	v_mfma_f32_16x16x32_bf16 v[62:65], v[156:159], v[188:191], v[62:65]
	v_mfma_f32_16x16x32_bf16 v[58:61], v[164:167], v[188:191], v[58:61]
	v_mfma_f32_16x16x32_bf16 v[46:49], v[156:159], v[196:199], v[46:49]
	v_mfma_f32_16x16x32_bf16 v[42:45], v[164:167], v[196:199], v[42:45]
	v_mfma_f32_16x16x32_bf16 v[30:33], v[156:159], v[204:207], v[30:33]
	v_mfma_f32_16x16x32_bf16 v[26:29], v[164:167], v[204:207], v[26:29]
	v_mfma_f32_16x16x32_bf16 v[14:17], v[156:159], v[212:215], v[14:17]
	v_mfma_f32_16x16x32_bf16 v[10:13], v[164:167], v[212:215], v[10:13]
	v_mfma_f32_16x16x32_bf16 v[62:65], v[160:163], v[192:195], v[62:65]
	v_mfma_f32_16x16x32_bf16 v[58:61], v[168:171], v[192:195], v[58:61]
	v_mfma_f32_16x16x32_bf16 v[46:49], v[160:163], v[200:203], v[46:49]
	v_mfma_f32_16x16x32_bf16 v[42:45], v[168:171], v[200:203], v[42:45]
	v_mfma_f32_16x16x32_bf16 v[30:33], v[160:163], v[208:211], v[30:33]
	v_mfma_f32_16x16x32_bf16 v[26:29], v[168:171], v[208:211], v[26:29]
	v_mfma_f32_16x16x32_bf16 v[14:17], v[160:163], v[216:219], v[14:17]
	v_mfma_f32_16x16x32_bf16 v[10:13], v[168:171], v[216:219], v[10:13]
	v_mfma_f32_16x16x32_bf16 v[54:57], v[172:175], v[188:191], v[54:57]
	v_mfma_f32_16x16x32_bf16 v[50:53], v[180:183], v[188:191], v[50:53]
	v_mfma_f32_16x16x32_bf16 v[38:41], v[172:175], v[196:199], v[38:41]
	v_mfma_f32_16x16x32_bf16 v[34:37], v[180:183], v[196:199], v[34:37]
	v_mfma_f32_16x16x32_bf16 v[22:25], v[172:175], v[204:207], v[22:25]
	v_mfma_f32_16x16x32_bf16 v[18:21], v[180:183], v[204:207], v[18:21]
	v_mfma_f32_16x16x32_bf16 v[6:9], v[172:175], v[212:215], v[6:9]
	v_mfma_f32_16x16x32_bf16 v[2:5], v[180:183], v[212:215], v[2:5]
	v_mfma_f32_16x16x32_bf16 v[54:57], v[176:179], v[192:195], v[54:57]
	v_mfma_f32_16x16x32_bf16 v[50:53], v[184:187], v[192:195], v[50:53]
	v_mfma_f32_16x16x32_bf16 v[38:41], v[176:179], v[200:203], v[38:41]
	v_mfma_f32_16x16x32_bf16 v[34:37], v[184:187], v[200:203], v[34:37]
	v_mfma_f32_16x16x32_bf16 v[22:25], v[176:179], v[208:211], v[22:25]
	v_mfma_f32_16x16x32_bf16 v[18:21], v[184:187], v[208:211], v[18:21]
	v_mfma_f32_16x16x32_bf16 v[6:9], v[176:179], v[216:219], v[6:9]
	v_mfma_f32_16x16x32_bf16 v[2:5], v[184:187], v[216:219], v[2:5]
	s_setprio 0
	s_barrier
	s_add_i32 s64, 0, 0x18000
	v_add_u32_e32 v155, s64, v153
	s_add_i32 s65, 0, 0x1c000
	ds_read_b128 v[156:159], v155
	ds_read_b128 v[160:163], v155 offset:1024
	ds_read_b128 v[164:167], v155 offset:2048
	ds_read_b128 v[168:171], v155 offset:3072
	v_add_u32_e32 v155, s65, v153
	ds_read_b128 v[172:175], v155
	ds_read_b128 v[176:179], v155 offset:1024
	ds_read_b128 v[180:183], v155 offset:2048
	ds_read_b128 v[184:187], v155 offset:3072
	s_add_u32 s98, s28, 0xb0000
	s_addc_u32 s99, s29, 0
	s_mov_b32 m0, s53
	ds_read_b128 v[188:191], v154 offset:32768
	ds_read_b128 v[192:195], v154 offset:33792
	ds_read_b128 v[196:199], v154 offset:34816
	ds_read_b128 v[200:203], v154 offset:35840
	ds_read_b128 v[204:207], v154 offset:36864
	ds_read_b128 v[208:211], v154 offset:37888
	ds_read_b128 v[212:215], v154 offset:38912
	ds_read_b128 v[216:219], v154 offset:39936
	global_load_lds_dwordx4 v130, s[98:99]
	s_mov_b32 m0, s54
	s_nop 0
	global_load_lds_dwordx4 v134, s[98:99]
	s_waitcnt vmcnt(8)
	s_waitcnt lgkmcnt(0)
	s_barrier
	s_setprio 1
	v_mfma_f32_16x16x32_bf16 v[126:129], v[156:159], v[188:191], v[126:129]
	v_mfma_f32_16x16x32_bf16 v[122:125], v[164:167], v[188:191], v[122:125]
	v_mfma_f32_16x16x32_bf16 v[110:113], v[156:159], v[196:199], v[110:113]
	v_mfma_f32_16x16x32_bf16 v[106:109], v[164:167], v[196:199], v[106:109]
	v_mfma_f32_16x16x32_bf16 v[94:97], v[156:159], v[204:207], v[94:97]
	v_mfma_f32_16x16x32_bf16 v[90:93], v[164:167], v[204:207], v[90:93]
	v_mfma_f32_16x16x32_bf16 v[78:81], v[156:159], v[212:215], v[78:81]
	v_mfma_f32_16x16x32_bf16 v[74:77], v[164:167], v[212:215], v[74:77]
	v_mfma_f32_16x16x32_bf16 v[126:129], v[160:163], v[192:195], v[126:129]
	v_mfma_f32_16x16x32_bf16 v[122:125], v[168:171], v[192:195], v[122:125]
	v_mfma_f32_16x16x32_bf16 v[110:113], v[160:163], v[200:203], v[110:113]
	v_mfma_f32_16x16x32_bf16 v[106:109], v[168:171], v[200:203], v[106:109]
	v_mfma_f32_16x16x32_bf16 v[94:97], v[160:163], v[208:211], v[94:97]
	v_mfma_f32_16x16x32_bf16 v[90:93], v[168:171], v[208:211], v[90:93]
	v_mfma_f32_16x16x32_bf16 v[78:81], v[160:163], v[216:219], v[78:81]
	v_mfma_f32_16x16x32_bf16 v[74:77], v[168:171], v[216:219], v[74:77]
	v_mfma_f32_16x16x32_bf16 v[118:121], v[172:175], v[188:191], v[118:121]
	v_mfma_f32_16x16x32_bf16 v[114:117], v[180:183], v[188:191], v[114:117]
	v_mfma_f32_16x16x32_bf16 v[102:105], v[172:175], v[196:199], v[102:105]
	v_mfma_f32_16x16x32_bf16 v[98:101], v[180:183], v[196:199], v[98:101]
	v_mfma_f32_16x16x32_bf16 v[86:89], v[172:175], v[204:207], v[86:89]
	v_mfma_f32_16x16x32_bf16 v[82:85], v[180:183], v[204:207], v[82:85]
	v_mfma_f32_16x16x32_bf16 v[70:73], v[172:175], v[212:215], v[70:73]
	v_mfma_f32_16x16x32_bf16 v[66:69], v[180:183], v[212:215], v[66:69]
	v_mfma_f32_16x16x32_bf16 v[118:121], v[176:179], v[192:195], v[118:121]
	v_mfma_f32_16x16x32_bf16 v[114:117], v[184:187], v[192:195], v[114:117]
	v_mfma_f32_16x16x32_bf16 v[102:105], v[176:179], v[200:203], v[102:105]
	v_mfma_f32_16x16x32_bf16 v[98:101], v[184:187], v[200:203], v[98:101]
	v_mfma_f32_16x16x32_bf16 v[86:89], v[176:179], v[208:211], v[86:89]
	v_mfma_f32_16x16x32_bf16 v[82:85], v[184:187], v[208:211], v[82:85]
	v_mfma_f32_16x16x32_bf16 v[70:73], v[176:179], v[216:219], v[70:73]
	v_mfma_f32_16x16x32_bf16 v[66:69], v[184:187], v[216:219], v[66:69]
	s_setprio 0
	s_barrier
	s_add_i32 s98, s64, s35
	s_add_i32 m0, s98, 0xffffff80
	ds_read_b128 v[188:191], v154 offset:49152
	ds_read_b128 v[192:195], v154 offset:50176
	ds_read_b128 v[196:199], v154 offset:51200
	ds_read_b128 v[200:203], v154 offset:52224
	ds_read_b128 v[204:207], v154 offset:53248
	ds_read_b128 v[208:211], v154 offset:54272
	ds_read_b128 v[212:215], v154 offset:55296
	ds_read_b128 v[216:219], v154 offset:56320
	global_load_lds_dwordx4 v132, s[20:21] offset:128
	s_add_i32 m0, s98, 0x1f80
	s_add_i32 s98, s65, s35
	global_load_lds_dwordx4 v136, s[20:21] offset:128
	s_add_u32 s20, s20, 0xb0080
	s_addc_u32 s21, s21, 0
	s_mov_b32 m0, s98
	s_nop 0
	global_load_lds_dwordx4 v132, s[20:21]
	s_add_i32 m0, s98, 0x2000
	s_nop 0
	global_load_lds_dwordx4 v136, s[20:21]
	s_add_i32 m0, s56, 0xffffff80
	s_nop 0
	global_load_lds_dwordx4 v130, s[28:29] offset:128
	s_add_i32 m0, s57, 0xffffff80
	s_nop 0
	global_load_lds_dwordx4 v134, s[28:29] offset:128
	s_waitcnt vmcnt(8)
	s_waitcnt lgkmcnt(0)
	s_barrier
	s_setprio 1
	v_mfma_f32_16x16x32_bf16 v[62:65], v[156:159], v[188:191], v[62:65]
	v_mfma_f32_16x16x32_bf16 v[58:61], v[164:167], v[188:191], v[58:61]
	v_mfma_f32_16x16x32_bf16 v[46:49], v[156:159], v[196:199], v[46:49]
	v_mfma_f32_16x16x32_bf16 v[42:45], v[164:167], v[196:199], v[42:45]
	v_mfma_f32_16x16x32_bf16 v[30:33], v[156:159], v[204:207], v[30:33]
	v_mfma_f32_16x16x32_bf16 v[26:29], v[164:167], v[204:207], v[26:29]
	v_mfma_f32_16x16x32_bf16 v[14:17], v[156:159], v[212:215], v[14:17]
	v_mfma_f32_16x16x32_bf16 v[10:13], v[164:167], v[212:215], v[10:13]
	v_mfma_f32_16x16x32_bf16 v[62:65], v[160:163], v[192:195], v[62:65]
	v_mfma_f32_16x16x32_bf16 v[58:61], v[168:171], v[192:195], v[58:61]
	v_mfma_f32_16x16x32_bf16 v[46:49], v[160:163], v[200:203], v[46:49]
	v_mfma_f32_16x16x32_bf16 v[42:45], v[168:171], v[200:203], v[42:45]
	v_mfma_f32_16x16x32_bf16 v[30:33], v[160:163], v[208:211], v[30:33]
	v_mfma_f32_16x16x32_bf16 v[26:29], v[168:171], v[208:211], v[26:29]
	v_mfma_f32_16x16x32_bf16 v[14:17], v[160:163], v[216:219], v[14:17]
	v_mfma_f32_16x16x32_bf16 v[10:13], v[168:171], v[216:219], v[10:13]
	v_mfma_f32_16x16x32_bf16 v[54:57], v[172:175], v[188:191], v[54:57]
	v_mfma_f32_16x16x32_bf16 v[50:53], v[180:183], v[188:191], v[50:53]
	v_mfma_f32_16x16x32_bf16 v[38:41], v[172:175], v[196:199], v[38:41]
	v_mfma_f32_16x16x32_bf16 v[34:37], v[180:183], v[196:199], v[34:37]
	v_mfma_f32_16x16x32_bf16 v[22:25], v[172:175], v[204:207], v[22:25]
	v_mfma_f32_16x16x32_bf16 v[18:21], v[180:183], v[204:207], v[18:21]
	v_mfma_f32_16x16x32_bf16 v[6:9], v[172:175], v[212:215], v[6:9]
	v_mfma_f32_16x16x32_bf16 v[2:5], v[180:183], v[212:215], v[2:5]
	v_mfma_f32_16x16x32_bf16 v[54:57], v[176:179], v[192:195], v[54:57]
	v_mfma_f32_16x16x32_bf16 v[50:53], v[184:187], v[192:195], v[50:53]
	v_mfma_f32_16x16x32_bf16 v[38:41], v[176:179], v[200:203], v[38:41]
	v_mfma_f32_16x16x32_bf16 v[34:37], v[184:187], v[200:203], v[34:37]
	v_mfma_f32_16x16x32_bf16 v[22:25], v[176:179], v[208:211], v[22:25]
	v_mfma_f32_16x16x32_bf16 v[18:21], v[184:187], v[208:211], v[18:21]
	v_mfma_f32_16x16x32_bf16 v[6:9], v[176:179], v[216:219], v[6:9]
	v_mfma_f32_16x16x32_bf16 v[2:5], v[184:187], v[216:219], v[2:5]
	s_setprio 0
	s_barrier
	s_add_i32 s63, s63, 2
	s_add_u32 s18, s18, 0x100
	s_addc_u32 s19, s19, 0
	s_cmp_gt_u32 s63, 41
	s_cbranch_scc0 .LBB0_730
	s_add_u32 s18, s15, 0xffffff00
	s_addc_u32 s19, s62, -1
	s_and_b64 vcc, exec, s[4:5]
	s_cbranch_vccnz .LBB0_733
	v_mov_b32_e32 v2, 0
	v_mov_b32_e32 v3, 0
	v_mov_b64_e32 v[4:5], v[2:3]
	v_mov_b64_e32 v[6:7], v[2:3]
	v_mov_b64_e32 v[8:9], v[2:3]
	v_mov_b64_e32 v[10:11], v[2:3]
	v_mov_b64_e32 v[12:13], v[2:3]
	v_mov_b64_e32 v[14:15], v[2:3]
	v_mov_b64_e32 v[16:17], v[2:3]
	v_mov_b64_e32 v[18:19], v[2:3]
	v_mov_b64_e32 v[20:21], v[2:3]
	v_mov_b64_e32 v[22:23], v[2:3]
	v_mov_b64_e32 v[24:25], v[2:3]
	v_mov_b64_e32 v[26:27], v[2:3]
	v_mov_b64_e32 v[28:29], v[2:3]
	v_mov_b64_e32 v[30:31], v[2:3]
	v_mov_b64_e32 v[32:33], v[2:3]
	v_mov_b64_e32 v[34:35], v[2:3]
	v_mov_b64_e32 v[36:37], v[2:3]
	v_mov_b64_e32 v[38:39], v[2:3]
	v_mov_b64_e32 v[40:41], v[2:3]
	v_mov_b64_e32 v[42:43], v[2:3]
	v_mov_b64_e32 v[44:45], v[2:3]
	v_mov_b64_e32 v[46:47], v[2:3]
	v_mov_b64_e32 v[48:49], v[2:3]
	v_mov_b64_e32 v[50:51], v[2:3]
	v_mov_b64_e32 v[52:53], v[2:3]
	v_mov_b64_e32 v[54:55], v[2:3]
	v_mov_b64_e32 v[56:57], v[2:3]
	v_mov_b64_e32 v[58:59], v[2:3]
	v_mov_b64_e32 v[60:61], v[2:3]
	v_mov_b64_e32 v[62:63], v[2:3]
	v_mov_b64_e32 v[64:65], v[2:3]
	v_mov_b64_e32 v[66:67], v[2:3]
	v_mov_b64_e32 v[68:69], v[2:3]
	v_mov_b64_e32 v[70:71], v[2:3]
	v_mov_b64_e32 v[72:73], v[2:3]
	v_mov_b64_e32 v[74:75], v[2:3]
	v_mov_b64_e32 v[76:77], v[2:3]
	v_mov_b64_e32 v[78:79], v[2:3]
	v_mov_b64_e32 v[80:81], v[2:3]
	v_mov_b64_e32 v[82:83], v[2:3]
	v_mov_b64_e32 v[84:85], v[2:3]
	v_mov_b64_e32 v[86:87], v[2:3]
	v_mov_b64_e32 v[88:89], v[2:3]
	v_mov_b64_e32 v[90:91], v[2:3]
	v_mov_b64_e32 v[92:93], v[2:3]
	v_mov_b64_e32 v[94:95], v[2:3]
	v_mov_b64_e32 v[96:97], v[2:3]
	v_mov_b64_e32 v[98:99], v[2:3]
	v_mov_b64_e32 v[100:101], v[2:3]
	v_mov_b64_e32 v[102:103], v[2:3]
	v_mov_b64_e32 v[104:105], v[2:3]
	v_mov_b64_e32 v[106:107], v[2:3]
	v_mov_b64_e32 v[108:109], v[2:3]
	v_mov_b64_e32 v[110:111], v[2:3]
	v_mov_b64_e32 v[112:113], v[2:3]
	v_mov_b64_e32 v[114:115], v[2:3]
	v_mov_b64_e32 v[116:117], v[2:3]
	v_mov_b64_e32 v[118:119], v[2:3]
	v_mov_b64_e32 v[120:121], v[2:3]
	v_mov_b64_e32 v[122:123], v[2:3]
	v_mov_b64_e32 v[124:125], v[2:3]
	v_mov_b64_e32 v[126:127], v[2:3]
	v_mov_b64_e32 v[128:129], v[2:3]
	s_mov_b32 s8, s60
	s_mov_b32 s50, s61
	s_mov_b64 s[10:11], s[16:17]
	s_mov_b32 s55, s14
	s_branch .LBB0_734

.LBB0_862:
	ds_read_b128 v[154:157], v141
	ds_read_b128 v[158:161], v141 offset:1024
	ds_read_b128 v[162:165], v141 offset:2048
	ds_read_b128 v[166:169], v141 offset:3072
	ds_read_b128 v[170:173], v182
	ds_read_b128 v[174:177], v182 offset:1024
	ds_read_b128 v[178:181], v182 offset:2048
	ds_read_b128 v[186:189], v182 offset:3072
	s_add_u32 s28, s12, 0xfffc0080
	s_addc_u32 s29, s13, -1
	s_cmp_eq_u32 s34, 12
	s_cselect_b32 s31, s9, s29
	s_cselect_b32 s30, s11, s28
	s_cselect_b32 s29, s14, s24
	s_cselect_b32 s28, s22, s23
	s_add_i32 m0, s87, 0xc000
	ds_read_b128 v[190:193], v183
	ds_read_b128 v[194:197], v183 offset:1024
	ds_read_b128 v[198:201], v183 offset:2048
	ds_read_b128 v[202:205], v183 offset:3072
	ds_read_b128 v[206:209], v183 offset:4096
	ds_read_b128 v[210:213], v183 offset:5120
	ds_read_b128 v[214:217], v183 offset:6144
	ds_read_b128 v[218:221], v183 offset:7168
	global_load_lds_dwordx4 v146, s[12:13]
	s_add_i32 m0, s87, 0xe000
	s_nop 0
	global_load_lds_dwordx4 v148, s[12:13]
	s_waitcnt vmcnt(8)
	s_waitcnt lgkmcnt(0)
	s_barrier
	s_setprio 1
	v_mfma_f32_16x16x32_bf16 v[126:129], v[154:157], v[190:193], v[126:129]
	v_mfma_f32_16x16x32_bf16 v[122:125], v[162:165], v[190:193], v[122:125]
	v_mfma_f32_16x16x32_bf16 v[118:121], v[154:157], v[198:201], v[118:121]
	v_mfma_f32_16x16x32_bf16 v[114:117], v[162:165], v[198:201], v[114:117]
	v_mfma_f32_16x16x32_bf16 v[110:113], v[154:157], v[206:209], v[110:113]
	v_mfma_f32_16x16x32_bf16 v[106:109], v[162:165], v[206:209], v[106:109]
	v_mfma_f32_16x16x32_bf16 v[102:105], v[154:157], v[214:217], v[102:105]
	v_mfma_f32_16x16x32_bf16 v[98:101], v[162:165], v[214:217], v[98:101]
	v_mfma_f32_16x16x32_bf16 v[126:129], v[158:161], v[194:197], v[126:129]
	v_mfma_f32_16x16x32_bf16 v[122:125], v[166:169], v[194:197], v[122:125]
	v_mfma_f32_16x16x32_bf16 v[118:121], v[158:161], v[202:205], v[118:121]
	v_mfma_f32_16x16x32_bf16 v[114:117], v[166:169], v[202:205], v[114:117]
	v_mfma_f32_16x16x32_bf16 v[110:113], v[158:161], v[210:213], v[110:113]
	v_mfma_f32_16x16x32_bf16 v[106:109], v[166:169], v[210:213], v[106:109]
	v_mfma_f32_16x16x32_bf16 v[102:105], v[158:161], v[218:221], v[102:105]
	v_mfma_f32_16x16x32_bf16 v[98:101], v[166:169], v[218:221], v[98:101]
	v_mfma_f32_16x16x32_bf16 v[62:65], v[170:173], v[190:193], v[62:65]
	v_mfma_f32_16x16x32_bf16 v[58:61], v[178:181], v[190:193], v[58:61]
	v_mfma_f32_16x16x32_bf16 v[54:57], v[170:173], v[198:201], v[54:57]
	v_mfma_f32_16x16x32_bf16 v[50:53], v[178:181], v[198:201], v[50:53]
	v_mfma_f32_16x16x32_bf16 v[46:49], v[170:173], v[206:209], v[46:49]
	v_mfma_f32_16x16x32_bf16 v[42:45], v[178:181], v[206:209], v[42:45]
	v_mfma_f32_16x16x32_bf16 v[38:41], v[170:173], v[214:217], v[38:41]
	v_mfma_f32_16x16x32_bf16 v[34:37], v[178:181], v[214:217], v[34:37]
	v_mfma_f32_16x16x32_bf16 v[62:65], v[174:177], v[194:197], v[62:65]
	v_mfma_f32_16x16x32_bf16 v[58:61], v[186:189], v[194:197], v[58:61]
	v_mfma_f32_16x16x32_bf16 v[54:57], v[174:177], v[202:205], v[54:57]
	v_mfma_f32_16x16x32_bf16 v[50:53], v[186:189], v[202:205], v[50:53]
	v_mfma_f32_16x16x32_bf16 v[46:49], v[174:177], v[210:213], v[46:49]
	v_mfma_f32_16x16x32_bf16 v[42:45], v[186:189], v[210:213], v[42:45]
	v_mfma_f32_16x16x32_bf16 v[38:41], v[174:177], v[218:221], v[38:41]
	v_mfma_f32_16x16x32_bf16 v[34:37], v[186:189], v[218:221], v[34:37]
	s_setprio 0
	s_barrier
	s_add_i32 s35, s97, s77
	s_mov_b32 m0, s35
	ds_read_b128 v[190:193], v183 offset:16384
	ds_read_b128 v[194:197], v183 offset:17408
	ds_read_b128 v[198:201], v183 offset:18432
	ds_read_b128 v[202:205], v183 offset:19456
	ds_read_b128 v[206:209], v183 offset:20480
	ds_read_b128 v[210:213], v183 offset:21504
	ds_read_b128 v[214:217], v183 offset:22528
	ds_read_b128 v[218:221], v183 offset:23552
	global_load_lds_dwordx4 v132, s[28:29]
	s_add_i32 m0, s35, 0x2000
	s_add_u32 s68, s28, 0x40000
	s_addc_u32 s69, s29, 0
	s_add_i32 s35, s74, s77
	global_load_lds_dwordx4 v136, s[28:29]
	s_mov_b32 m0, s35
	s_nop 0
	global_load_lds_dwordx4 v132, s[68:69]
	s_add_i32 m0, s35, 0x2000
	s_nop 0
	global_load_lds_dwordx4 v136, s[68:69]
	s_mov_b32 m0, s87
	s_nop 0
	global_load_lds_dwordx4 v130, s[30:31]
	s_mov_b32 m0, s88
	s_nop 0
	global_load_lds_dwordx4 v134, s[30:31]
	s_waitcnt vmcnt(8)
	s_waitcnt lgkmcnt(0)
	s_barrier
	s_setprio 1
	v_mfma_f32_16x16x32_bf16 v[94:97], v[154:157], v[190:193], v[94:97]
	v_mfma_f32_16x16x32_bf16 v[90:93], v[162:165], v[190:193], v[90:93]
	v_mfma_f32_16x16x32_bf16 v[86:89], v[154:157], v[198:201], v[86:89]
	v_mfma_f32_16x16x32_bf16 v[82:85], v[162:165], v[198:201], v[82:85]
	v_mfma_f32_16x16x32_bf16 v[78:81], v[154:157], v[206:209], v[78:81]
	v_mfma_f32_16x16x32_bf16 v[74:77], v[162:165], v[206:209], v[74:77]
	v_mfma_f32_16x16x32_bf16 v[70:73], v[154:157], v[214:217], v[70:73]
	v_mfma_f32_16x16x32_bf16 v[66:69], v[162:165], v[214:217], v[66:69]
	v_mfma_f32_16x16x32_bf16 v[94:97], v[158:161], v[194:197], v[94:97]
	v_mfma_f32_16x16x32_bf16 v[90:93], v[166:169], v[194:197], v[90:93]
	v_mfma_f32_16x16x32_bf16 v[86:89], v[158:161], v[202:205], v[86:89]
	v_mfma_f32_16x16x32_bf16 v[82:85], v[166:169], v[202:205], v[82:85]
	v_mfma_f32_16x16x32_bf16 v[78:81], v[158:161], v[210:213], v[78:81]
	v_mfma_f32_16x16x32_bf16 v[74:77], v[166:169], v[210:213], v[74:77]
	v_mfma_f32_16x16x32_bf16 v[70:73], v[158:161], v[218:221], v[70:73]
	v_mfma_f32_16x16x32_bf16 v[66:69], v[166:169], v[218:221], v[66:69]
	v_mfma_f32_16x16x32_bf16 v[30:33], v[170:173], v[190:193], v[30:33]
	v_mfma_f32_16x16x32_bf16 v[26:29], v[178:181], v[190:193], v[26:29]
	v_mfma_f32_16x16x32_bf16 v[22:25], v[170:173], v[198:201], v[22:25]
	v_mfma_f32_16x16x32_bf16 v[18:21], v[178:181], v[198:201], v[18:21]
	v_mfma_f32_16x16x32_bf16 v[14:17], v[170:173], v[206:209], v[14:17]
	v_mfma_f32_16x16x32_bf16 v[10:13], v[178:181], v[206:209], v[10:13]
	v_mfma_f32_16x16x32_bf16 v[6:9], v[170:173], v[214:217], v[6:9]
	v_mfma_f32_16x16x32_bf16 v[2:5], v[178:181], v[214:217], v[2:5]
	v_mfma_f32_16x16x32_bf16 v[30:33], v[174:177], v[194:197], v[30:33]
	v_mfma_f32_16x16x32_bf16 v[26:29], v[186:189], v[194:197], v[26:29]
	v_mfma_f32_16x16x32_bf16 v[22:25], v[174:177], v[202:205], v[22:25]
	v_mfma_f32_16x16x32_bf16 v[18:21], v[186:189], v[202:205], v[18:21]
	v_mfma_f32_16x16x32_bf16 v[14:17], v[174:177], v[210:213], v[14:17]
	v_mfma_f32_16x16x32_bf16 v[10:13], v[186:189], v[210:213], v[10:13]
	v_mfma_f32_16x16x32_bf16 v[6:9], v[174:177], v[218:221], v[6:9]
	v_mfma_f32_16x16x32_bf16 v[2:5], v[186:189], v[218:221], v[2:5]
	s_setprio 0
	s_barrier
	s_add_i32 s35, 0, 0x18000
	s_add_i32 s63, 0, 0x1c000
	v_add_u32_e32 v166, s35, v139
	v_add_u32_e32 v185, s63, v139
	ds_read_b128 v[154:157], v166
	ds_read_b128 v[158:161], v166 offset:1024
	ds_read_b128 v[162:165], v166 offset:2048
	ds_read_b128 v[166:169], v166 offset:3072
	ds_read_b128 v[170:173], v185
	ds_read_b128 v[174:177], v185 offset:1024
	ds_read_b128 v[178:181], v185 offset:2048
	ds_read_b128 v[186:189], v185 offset:3072
	s_add_u32 s98, s30, 0x40000
	s_addc_u32 s99, s31, 0
	s_mov_b32 m0, s89
	ds_read_b128 v[190:193], v183 offset:32768
	ds_read_b128 v[194:197], v183 offset:33792
	ds_read_b128 v[198:201], v183 offset:34816
	ds_read_b128 v[202:205], v183 offset:35840
	ds_read_b128 v[206:209], v183 offset:36864
	ds_read_b128 v[210:213], v183 offset:37888
	ds_read_b128 v[214:217], v183 offset:38912
	ds_read_b128 v[218:221], v183 offset:39936
	global_load_lds_dwordx4 v130, s[98:99]
	s_mov_b32 m0, s90
	s_nop 0
	global_load_lds_dwordx4 v134, s[98:99]
	s_waitcnt vmcnt(8)
	s_waitcnt lgkmcnt(0)
	s_barrier
	s_setprio 1
	v_mfma_f32_16x16x32_bf16 v[126:129], v[154:157], v[190:193], v[126:129]
	v_mfma_f32_16x16x32_bf16 v[122:125], v[162:165], v[190:193], v[122:125]
	v_mfma_f32_16x16x32_bf16 v[118:121], v[154:157], v[198:201], v[118:121]
	v_mfma_f32_16x16x32_bf16 v[114:117], v[162:165], v[198:201], v[114:117]
	v_mfma_f32_16x16x32_bf16 v[110:113], v[154:157], v[206:209], v[110:113]
	v_mfma_f32_16x16x32_bf16 v[106:109], v[162:165], v[206:209], v[106:109]
	v_mfma_f32_16x16x32_bf16 v[102:105], v[154:157], v[214:217], v[102:105]
	v_mfma_f32_16x16x32_bf16 v[98:101], v[162:165], v[214:217], v[98:101]
	v_mfma_f32_16x16x32_bf16 v[126:129], v[158:161], v[194:197], v[126:129]
	v_mfma_f32_16x16x32_bf16 v[122:125], v[166:169], v[194:197], v[122:125]
	v_mfma_f32_16x16x32_bf16 v[118:121], v[158:161], v[202:205], v[118:121]
	v_mfma_f32_16x16x32_bf16 v[114:117], v[166:169], v[202:205], v[114:117]
	v_mfma_f32_16x16x32_bf16 v[110:113], v[158:161], v[210:213], v[110:113]
	v_mfma_f32_16x16x32_bf16 v[106:109], v[166:169], v[210:213], v[106:109]
	v_mfma_f32_16x16x32_bf16 v[102:105], v[158:161], v[218:221], v[102:105]
	v_mfma_f32_16x16x32_bf16 v[98:101], v[166:169], v[218:221], v[98:101]
	v_mfma_f32_16x16x32_bf16 v[62:65], v[170:173], v[190:193], v[62:65]
	v_mfma_f32_16x16x32_bf16 v[58:61], v[178:181], v[190:193], v[58:61]
	v_mfma_f32_16x16x32_bf16 v[54:57], v[170:173], v[198:201], v[54:57]
	v_mfma_f32_16x16x32_bf16 v[50:53], v[178:181], v[198:201], v[50:53]
	v_mfma_f32_16x16x32_bf16 v[46:49], v[170:173], v[206:209], v[46:49]
	v_mfma_f32_16x16x32_bf16 v[42:45], v[178:181], v[206:209], v[42:45]
	v_mfma_f32_16x16x32_bf16 v[38:41], v[170:173], v[214:217], v[38:41]
	v_mfma_f32_16x16x32_bf16 v[34:37], v[178:181], v[214:217], v[34:37]
	v_mfma_f32_16x16x32_bf16 v[62:65], v[174:177], v[194:197], v[62:65]
	v_mfma_f32_16x16x32_bf16 v[58:61], v[186:189], v[194:197], v[58:61]
	v_mfma_f32_16x16x32_bf16 v[54:57], v[174:177], v[202:205], v[54:57]
	v_mfma_f32_16x16x32_bf16 v[50:53], v[186:189], v[202:205], v[50:53]
	v_mfma_f32_16x16x32_bf16 v[46:49], v[174:177], v[210:213], v[46:49]
	v_mfma_f32_16x16x32_bf16 v[42:45], v[186:189], v[210:213], v[42:45]
	v_mfma_f32_16x16x32_bf16 v[38:41], v[174:177], v[218:221], v[38:41]
	v_mfma_f32_16x16x32_bf16 v[34:37], v[186:189], v[218:221], v[34:37]
	s_setprio 0
	s_barrier
	s_add_i32 s98, s35, s77
	s_add_i32 m0, s98, 0xffffff80
	ds_read_b128 v[190:193], v183 offset:49152
	ds_read_b128 v[194:197], v183 offset:50176
	ds_read_b128 v[198:201], v183 offset:51200
	ds_read_b128 v[202:205], v183 offset:52224
	ds_read_b128 v[206:209], v183 offset:53248
	ds_read_b128 v[210:213], v183 offset:54272
	ds_read_b128 v[214:217], v183 offset:55296
	ds_read_b128 v[218:221], v183 offset:56320
	global_load_lds_dwordx4 v132, s[28:29] offset:128
	s_add_i32 m0, s98, 0x1f80
	s_add_i32 s98, s63, s77
	global_load_lds_dwordx4 v136, s[28:29] offset:128
	s_add_u32 s28, s28, 0x40080
	s_addc_u32 s29, s29, 0
	s_mov_b32 m0, s98
	s_nop 0
	global_load_lds_dwordx4 v132, s[28:29]
	s_add_i32 m0, s98, 0x2000
	s_nop 0
	global_load_lds_dwordx4 v136, s[28:29]
	s_add_i32 m0, s92, 0xffffff80
	s_nop 0
	global_load_lds_dwordx4 v130, s[30:31] offset:128
	s_add_i32 m0, s93, 0xffffff80
	s_nop 0
	global_load_lds_dwordx4 v134, s[30:31] offset:128
	s_waitcnt vmcnt(8)
	s_waitcnt lgkmcnt(0)
	s_barrier
	s_setprio 1
	v_mfma_f32_16x16x32_bf16 v[94:97], v[154:157], v[190:193], v[94:97]
	v_mfma_f32_16x16x32_bf16 v[90:93], v[162:165], v[190:193], v[90:93]
	v_mfma_f32_16x16x32_bf16 v[86:89], v[154:157], v[198:201], v[86:89]
	v_mfma_f32_16x16x32_bf16 v[82:85], v[162:165], v[198:201], v[82:85]
	v_mfma_f32_16x16x32_bf16 v[78:81], v[154:157], v[206:209], v[78:81]
	v_mfma_f32_16x16x32_bf16 v[74:77], v[162:165], v[206:209], v[74:77]
	v_mfma_f32_16x16x32_bf16 v[70:73], v[154:157], v[214:217], v[70:73]
	v_mfma_f32_16x16x32_bf16 v[66:69], v[162:165], v[214:217], v[66:69]
	v_mfma_f32_16x16x32_bf16 v[94:97], v[158:161], v[194:197], v[94:97]
	v_mfma_f32_16x16x32_bf16 v[90:93], v[166:169], v[194:197], v[90:93]
	v_mfma_f32_16x16x32_bf16 v[86:89], v[158:161], v[202:205], v[86:89]
	v_mfma_f32_16x16x32_bf16 v[82:85], v[166:169], v[202:205], v[82:85]
	v_mfma_f32_16x16x32_bf16 v[78:81], v[158:161], v[210:213], v[78:81]
	v_mfma_f32_16x16x32_bf16 v[74:77], v[166:169], v[210:213], v[74:77]
	v_mfma_f32_16x16x32_bf16 v[70:73], v[158:161], v[218:221], v[70:73]
	v_mfma_f32_16x16x32_bf16 v[66:69], v[166:169], v[218:221], v[66:69]
	v_mfma_f32_16x16x32_bf16 v[30:33], v[170:173], v[190:193], v[30:33]
	v_mfma_f32_16x16x32_bf16 v[26:29], v[178:181], v[190:193], v[26:29]
	v_mfma_f32_16x16x32_bf16 v[22:25], v[170:173], v[198:201], v[22:25]
	v_mfma_f32_16x16x32_bf16 v[18:21], v[178:181], v[198:201], v[18:21]
	v_mfma_f32_16x16x32_bf16 v[14:17], v[170:173], v[206:209], v[14:17]
	v_mfma_f32_16x16x32_bf16 v[10:13], v[178:181], v[206:209], v[10:13]
	v_mfma_f32_16x16x32_bf16 v[6:9], v[170:173], v[214:217], v[6:9]
	v_mfma_f32_16x16x32_bf16 v[2:5], v[178:181], v[214:217], v[2:5]
	v_mfma_f32_16x16x32_bf16 v[30:33], v[174:177], v[194:197], v[30:33]
	v_mfma_f32_16x16x32_bf16 v[26:29], v[186:189], v[194:197], v[26:29]
	v_mfma_f32_16x16x32_bf16 v[22:25], v[174:177], v[202:205], v[22:25]
	v_mfma_f32_16x16x32_bf16 v[18:21], v[186:189], v[202:205], v[18:21]
	v_mfma_f32_16x16x32_bf16 v[14:17], v[174:177], v[210:213], v[14:17]
	v_mfma_f32_16x16x32_bf16 v[10:13], v[186:189], v[210:213], v[10:13]
	v_mfma_f32_16x16x32_bf16 v[6:9], v[174:177], v[218:221], v[6:9]
	v_mfma_f32_16x16x32_bf16 v[2:5], v[186:189], v[218:221], v[2:5]
	s_setprio 0
	s_barrier
	s_add_i32 s34, s34, 2
	s_add_u32 s12, s12, 0x100
	s_addc_u32 s13, s13, 0
	s_add_u32 s23, s23, 0x100
	s_addc_u32 s24, s24, 0
	s_cmp_gt_u32 s34, 13
	s_cbranch_scc0 .LBB0_862
	s_and_b64 vcc, exec, s[54:55]
	s_cbranch_vccz .LBB0_865
	s_barrier

.LBB0_1654:
	ds_read_b128 v[152:155], v131
	ds_read_b128 v[156:159], v131 offset:1024
	ds_read_b128 v[160:163], v131 offset:2048
	ds_read_b128 v[180:183], v131 offset:3072
	ds_read_b128 v[184:187], v176
	ds_read_b128 v[188:191], v176 offset:1024
	ds_read_b128 v[192:195], v176 offset:2048
	ds_read_b128 v[196:199], v176 offset:3072
	s_add_u32 s28, s36, 0xfffc0080
	s_addc_u32 s29, s37, -1
	s_cmp_eq_u32 s51, 12
	s_cselect_b32 s31, s15, s29
	s_cselect_b32 s30, s47, s28
	s_cselect_b32 s29, s13, s50
	s_cselect_b32 s28, s48, s49
	s_add_i32 m0, s33, 0xc000
	ds_read_b128 v[200:203], v177
	ds_read_b128 v[204:207], v177 offset:1024
	ds_read_b128 v[208:211], v177 offset:2048
	ds_read_b128 v[212:215], v177 offset:3072
	ds_read_b128 v[216:219], v177 offset:4096
	ds_read_b128 v[220:223], v177 offset:5120
	ds_read_b128 v[224:227], v177 offset:6144
	ds_read_b128 v[228:231], v177 offset:7168
	global_load_lds_dwordx4 v144, s[36:37]
	s_add_i32 m0, s33, 0xe000
	s_nop 0
	global_load_lds_dwordx4 v146, s[36:37]
	s_waitcnt vmcnt(8)
	s_waitcnt lgkmcnt(0)
	s_barrier
	s_setprio 1
	v_mfma_f32_16x16x32_bf16 v[126:129], v[152:155], v[200:203], v[126:129]
	v_mfma_f32_16x16x32_bf16 v[122:125], v[160:163], v[200:203], v[122:125]
	v_mfma_f32_16x16x32_bf16 v[110:113], v[152:155], v[208:211], v[110:113]
	v_mfma_f32_16x16x32_bf16 v[106:109], v[160:163], v[208:211], v[106:109]
	v_mfma_f32_16x16x32_bf16 v[94:97], v[152:155], v[216:219], v[94:97]
	v_mfma_f32_16x16x32_bf16 v[90:93], v[160:163], v[216:219], v[90:93]
	v_mfma_f32_16x16x32_bf16 v[78:81], v[152:155], v[224:227], v[78:81]
	v_mfma_f32_16x16x32_bf16 v[74:77], v[160:163], v[224:227], v[74:77]
	v_mfma_f32_16x16x32_bf16 v[126:129], v[156:159], v[204:207], v[126:129]
	v_mfma_f32_16x16x32_bf16 v[122:125], v[180:183], v[204:207], v[122:125]
	v_mfma_f32_16x16x32_bf16 v[110:113], v[156:159], v[212:215], v[110:113]
	v_mfma_f32_16x16x32_bf16 v[106:109], v[180:183], v[212:215], v[106:109]
	v_mfma_f32_16x16x32_bf16 v[94:97], v[156:159], v[220:223], v[94:97]
	v_mfma_f32_16x16x32_bf16 v[90:93], v[180:183], v[220:223], v[90:93]
	v_mfma_f32_16x16x32_bf16 v[78:81], v[156:159], v[228:231], v[78:81]
	v_mfma_f32_16x16x32_bf16 v[74:77], v[180:183], v[228:231], v[74:77]
	v_mfma_f32_16x16x32_bf16 v[118:121], v[184:187], v[200:203], v[118:121]
	v_mfma_f32_16x16x32_bf16 v[114:117], v[192:195], v[200:203], v[114:117]
	v_mfma_f32_16x16x32_bf16 v[102:105], v[184:187], v[208:211], v[102:105]
	v_mfma_f32_16x16x32_bf16 v[98:101], v[192:195], v[208:211], v[98:101]
	v_mfma_f32_16x16x32_bf16 v[86:89], v[184:187], v[216:219], v[86:89]
	v_mfma_f32_16x16x32_bf16 v[82:85], v[192:195], v[216:219], v[82:85]
	v_mfma_f32_16x16x32_bf16 v[70:73], v[184:187], v[224:227], v[70:73]
	v_mfma_f32_16x16x32_bf16 v[66:69], v[192:195], v[224:227], v[66:69]
	v_mfma_f32_16x16x32_bf16 v[118:121], v[188:191], v[204:207], v[118:121]
	v_mfma_f32_16x16x32_bf16 v[114:117], v[196:199], v[204:207], v[114:117]
	v_mfma_f32_16x16x32_bf16 v[102:105], v[188:191], v[212:215], v[102:105]
	v_mfma_f32_16x16x32_bf16 v[98:101], v[196:199], v[212:215], v[98:101]
	v_mfma_f32_16x16x32_bf16 v[86:89], v[188:191], v[220:223], v[86:89]
	v_mfma_f32_16x16x32_bf16 v[82:85], v[196:199], v[220:223], v[82:85]
	v_mfma_f32_16x16x32_bf16 v[70:73], v[188:191], v[228:231], v[70:73]
	v_mfma_f32_16x16x32_bf16 v[66:69], v[196:199], v[228:231], v[66:69]
	s_setprio 0
	s_barrier
	s_add_i32 s52, s45, s25
	s_mov_b32 m0, s52
	ds_read_b128 v[200:203], v177 offset:16384
	ds_read_b128 v[204:207], v177 offset:17408
	ds_read_b128 v[208:211], v177 offset:18432
	ds_read_b128 v[212:215], v177 offset:19456
	ds_read_b128 v[216:219], v177 offset:20480
	ds_read_b128 v[220:223], v177 offset:21504
	ds_read_b128 v[224:227], v177 offset:22528
	ds_read_b128 v[228:231], v177 offset:23552
	global_load_lds_dwordx4 v134, s[28:29]
	s_add_i32 m0, s52, 0x2000
	s_add_u32 s52, s28, 0x40000
	s_addc_u32 s53, s29, 0
	s_add_i32 s54, s46, s25
	global_load_lds_dwordx4 v140, s[28:29]
	s_mov_b32 m0, s54
	s_nop 0
	global_load_lds_dwordx4 v134, s[52:53]
	s_add_i32 m0, s54, 0x2000
	s_nop 0
	global_load_lds_dwordx4 v140, s[52:53]
	s_mov_b32 m0, s33
	s_nop 0
	global_load_lds_dwordx4 v132, s[30:31]
	s_mov_b32 m0, s34
	s_nop 0
	global_load_lds_dwordx4 v136, s[30:31]
	s_waitcnt vmcnt(8)
	s_waitcnt lgkmcnt(0)
	s_barrier
	s_setprio 1
	v_mfma_f32_16x16x32_bf16 v[62:65], v[152:155], v[200:203], v[62:65]
	v_mfma_f32_16x16x32_bf16 v[58:61], v[160:163], v[200:203], v[58:61]
	v_mfma_f32_16x16x32_bf16 v[46:49], v[152:155], v[208:211], v[46:49]
	v_mfma_f32_16x16x32_bf16 v[42:45], v[160:163], v[208:211], v[42:45]
	v_mfma_f32_16x16x32_bf16 v[30:33], v[152:155], v[216:219], v[30:33]
	v_mfma_f32_16x16x32_bf16 v[26:29], v[160:163], v[216:219], v[26:29]
	v_mfma_f32_16x16x32_bf16 v[14:17], v[152:155], v[224:227], v[14:17]
	v_mfma_f32_16x16x32_bf16 v[10:13], v[160:163], v[224:227], v[10:13]
	v_mfma_f32_16x16x32_bf16 v[62:65], v[156:159], v[204:207], v[62:65]
	v_mfma_f32_16x16x32_bf16 v[58:61], v[180:183], v[204:207], v[58:61]
	v_mfma_f32_16x16x32_bf16 v[46:49], v[156:159], v[212:215], v[46:49]
	v_mfma_f32_16x16x32_bf16 v[42:45], v[180:183], v[212:215], v[42:45]
	v_mfma_f32_16x16x32_bf16 v[30:33], v[156:159], v[220:223], v[30:33]
	v_mfma_f32_16x16x32_bf16 v[26:29], v[180:183], v[220:223], v[26:29]
	v_mfma_f32_16x16x32_bf16 v[14:17], v[156:159], v[228:231], v[14:17]
	v_mfma_f32_16x16x32_bf16 v[10:13], v[180:183], v[228:231], v[10:13]
	v_mfma_f32_16x16x32_bf16 v[54:57], v[184:187], v[200:203], v[54:57]
	v_mfma_f32_16x16x32_bf16 v[50:53], v[192:195], v[200:203], v[50:53]
	v_mfma_f32_16x16x32_bf16 v[38:41], v[184:187], v[208:211], v[38:41]
	v_mfma_f32_16x16x32_bf16 v[34:37], v[192:195], v[208:211], v[34:37]
	v_mfma_f32_16x16x32_bf16 v[22:25], v[184:187], v[216:219], v[22:25]
	v_mfma_f32_16x16x32_bf16 v[18:21], v[192:195], v[216:219], v[18:21]
	v_mfma_f32_16x16x32_bf16 v[6:9], v[184:187], v[224:227], v[6:9]
	v_mfma_f32_16x16x32_bf16 v[2:5], v[192:195], v[224:227], v[2:5]
	v_mfma_f32_16x16x32_bf16 v[54:57], v[188:191], v[204:207], v[54:57]
	v_mfma_f32_16x16x32_bf16 v[50:53], v[196:199], v[204:207], v[50:53]
	v_mfma_f32_16x16x32_bf16 v[38:41], v[188:191], v[212:215], v[38:41]
	v_mfma_f32_16x16x32_bf16 v[34:37], v[196:199], v[212:215], v[34:37]
	v_mfma_f32_16x16x32_bf16 v[22:25], v[188:191], v[220:223], v[22:25]
	v_mfma_f32_16x16x32_bf16 v[18:21], v[196:199], v[220:223], v[18:21]
	v_mfma_f32_16x16x32_bf16 v[6:9], v[188:191], v[228:231], v[6:9]
	v_mfma_f32_16x16x32_bf16 v[2:5], v[196:199], v[228:231], v[2:5]
	s_setprio 0
	s_barrier
	s_add_i32 s52, 0, 0x18000
	v_add_u32_e32 v179, s52, v175
	s_add_i32 s53, 0, 0x1c000
	ds_read_b128 v[152:155], v179
	ds_read_b128 v[156:159], v179 offset:1024
	ds_read_b128 v[160:163], v179 offset:2048
	ds_read_b128 v[180:183], v179 offset:3072
	v_add_u32_e32 v179, s53, v175
	ds_read_b128 v[184:187], v179
	ds_read_b128 v[188:191], v179 offset:1024
	ds_read_b128 v[192:195], v179 offset:2048
	ds_read_b128 v[196:199], v179 offset:3072
	s_add_u32 s98, s30, 0x40000
	s_addc_u32 s99, s31, 0
	s_mov_b32 m0, s35
	ds_read_b128 v[200:203], v177 offset:32768
	ds_read_b128 v[204:207], v177 offset:33792
	ds_read_b128 v[208:211], v177 offset:34816
	ds_read_b128 v[212:215], v177 offset:35840
	ds_read_b128 v[216:219], v177 offset:36864
	ds_read_b128 v[220:223], v177 offset:37888
	ds_read_b128 v[224:227], v177 offset:38912
	ds_read_b128 v[228:231], v177 offset:39936
	global_load_lds_dwordx4 v132, s[98:99]
	s_mov_b32 m0, s38
	s_nop 0
	global_load_lds_dwordx4 v136, s[98:99]
	s_waitcnt vmcnt(8)
	s_waitcnt lgkmcnt(0)
	s_barrier
	s_setprio 1
	v_mfma_f32_16x16x32_bf16 v[126:129], v[152:155], v[200:203], v[126:129]
	v_mfma_f32_16x16x32_bf16 v[122:125], v[160:163], v[200:203], v[122:125]
	v_mfma_f32_16x16x32_bf16 v[110:113], v[152:155], v[208:211], v[110:113]
	v_mfma_f32_16x16x32_bf16 v[106:109], v[160:163], v[208:211], v[106:109]
	v_mfma_f32_16x16x32_bf16 v[94:97], v[152:155], v[216:219], v[94:97]
	v_mfma_f32_16x16x32_bf16 v[90:93], v[160:163], v[216:219], v[90:93]
	v_mfma_f32_16x16x32_bf16 v[78:81], v[152:155], v[224:227], v[78:81]
	v_mfma_f32_16x16x32_bf16 v[74:77], v[160:163], v[224:227], v[74:77]
	v_mfma_f32_16x16x32_bf16 v[126:129], v[156:159], v[204:207], v[126:129]
	v_mfma_f32_16x16x32_bf16 v[122:125], v[180:183], v[204:207], v[122:125]
	v_mfma_f32_16x16x32_bf16 v[110:113], v[156:159], v[212:215], v[110:113]
	v_mfma_f32_16x16x32_bf16 v[106:109], v[180:183], v[212:215], v[106:109]
	v_mfma_f32_16x16x32_bf16 v[94:97], v[156:159], v[220:223], v[94:97]
	v_mfma_f32_16x16x32_bf16 v[90:93], v[180:183], v[220:223], v[90:93]
	v_mfma_f32_16x16x32_bf16 v[78:81], v[156:159], v[228:231], v[78:81]
	v_mfma_f32_16x16x32_bf16 v[74:77], v[180:183], v[228:231], v[74:77]
	v_mfma_f32_16x16x32_bf16 v[118:121], v[184:187], v[200:203], v[118:121]
	v_mfma_f32_16x16x32_bf16 v[114:117], v[192:195], v[200:203], v[114:117]
	v_mfma_f32_16x16x32_bf16 v[102:105], v[184:187], v[208:211], v[102:105]
	v_mfma_f32_16x16x32_bf16 v[98:101], v[192:195], v[208:211], v[98:101]
	v_mfma_f32_16x16x32_bf16 v[86:89], v[184:187], v[216:219], v[86:89]
	v_mfma_f32_16x16x32_bf16 v[82:85], v[192:195], v[216:219], v[82:85]
	v_mfma_f32_16x16x32_bf16 v[70:73], v[184:187], v[224:227], v[70:73]
	v_mfma_f32_16x16x32_bf16 v[66:69], v[192:195], v[224:227], v[66:69]
	v_mfma_f32_16x16x32_bf16 v[118:121], v[188:191], v[204:207], v[118:121]
	v_mfma_f32_16x16x32_bf16 v[114:117], v[196:199], v[204:207], v[114:117]
	v_mfma_f32_16x16x32_bf16 v[102:105], v[188:191], v[212:215], v[102:105]
	v_mfma_f32_16x16x32_bf16 v[98:101], v[196:199], v[212:215], v[98:101]
	v_mfma_f32_16x16x32_bf16 v[86:89], v[188:191], v[220:223], v[86:89]
	v_mfma_f32_16x16x32_bf16 v[82:85], v[196:199], v[220:223], v[82:85]
	v_mfma_f32_16x16x32_bf16 v[70:73], v[188:191], v[228:231], v[70:73]
	v_mfma_f32_16x16x32_bf16 v[66:69], v[196:199], v[228:231], v[66:69]
	s_setprio 0
	s_barrier
	s_add_i32 s98, s52, s25
	s_add_i32 m0, s98, 0xffffff80
	ds_read_b128 v[200:203], v177 offset:49152
	ds_read_b128 v[204:207], v177 offset:50176
	ds_read_b128 v[208:211], v177 offset:51200
	ds_read_b128 v[212:215], v177 offset:52224
	ds_read_b128 v[216:219], v177 offset:53248
	ds_read_b128 v[220:223], v177 offset:54272
	ds_read_b128 v[224:227], v177 offset:55296
	ds_read_b128 v[228:231], v177 offset:56320
	global_load_lds_dwordx4 v134, s[28:29] offset:128
	s_add_i32 m0, s98, 0x1f80
	s_add_i32 s98, s53, s25
	global_load_lds_dwordx4 v140, s[28:29] offset:128
	s_add_u32 s28, s28, 0x40080
	s_addc_u32 s29, s29, 0
	s_mov_b32 m0, s98
	s_nop 0
	global_load_lds_dwordx4 v134, s[28:29]
	s_add_i32 m0, s98, 0x2000
	s_nop 0
	global_load_lds_dwordx4 v140, s[28:29]
	s_add_i32 m0, s42, 0xffffff80
	s_nop 0
	global_load_lds_dwordx4 v132, s[30:31] offset:128
	s_add_i32 m0, s43, 0xffffff80
	s_nop 0
	global_load_lds_dwordx4 v136, s[30:31] offset:128
	s_waitcnt vmcnt(8)
	s_waitcnt lgkmcnt(0)
	s_barrier
	s_setprio 1
	v_mfma_f32_16x16x32_bf16 v[62:65], v[152:155], v[200:203], v[62:65]
	v_mfma_f32_16x16x32_bf16 v[58:61], v[160:163], v[200:203], v[58:61]
	v_mfma_f32_16x16x32_bf16 v[46:49], v[152:155], v[208:211], v[46:49]
	v_mfma_f32_16x16x32_bf16 v[42:45], v[160:163], v[208:211], v[42:45]
	v_mfma_f32_16x16x32_bf16 v[30:33], v[152:155], v[216:219], v[30:33]
	v_mfma_f32_16x16x32_bf16 v[26:29], v[160:163], v[216:219], v[26:29]
	v_mfma_f32_16x16x32_bf16 v[14:17], v[152:155], v[224:227], v[14:17]
	v_mfma_f32_16x16x32_bf16 v[10:13], v[160:163], v[224:227], v[10:13]
	v_mfma_f32_16x16x32_bf16 v[62:65], v[156:159], v[204:207], v[62:65]
	v_mfma_f32_16x16x32_bf16 v[58:61], v[180:183], v[204:207], v[58:61]
	v_mfma_f32_16x16x32_bf16 v[46:49], v[156:159], v[212:215], v[46:49]
	v_mfma_f32_16x16x32_bf16 v[42:45], v[180:183], v[212:215], v[42:45]
	v_mfma_f32_16x16x32_bf16 v[30:33], v[156:159], v[220:223], v[30:33]
	v_mfma_f32_16x16x32_bf16 v[26:29], v[180:183], v[220:223], v[26:29]
	v_mfma_f32_16x16x32_bf16 v[14:17], v[156:159], v[228:231], v[14:17]
	v_mfma_f32_16x16x32_bf16 v[10:13], v[180:183], v[228:231], v[10:13]
	v_mfma_f32_16x16x32_bf16 v[54:57], v[184:187], v[200:203], v[54:57]
	v_mfma_f32_16x16x32_bf16 v[50:53], v[192:195], v[200:203], v[50:53]
	v_mfma_f32_16x16x32_bf16 v[38:41], v[184:187], v[208:211], v[38:41]
	v_mfma_f32_16x16x32_bf16 v[34:37], v[192:195], v[208:211], v[34:37]
	v_mfma_f32_16x16x32_bf16 v[22:25], v[184:187], v[216:219], v[22:25]
	v_mfma_f32_16x16x32_bf16 v[18:21], v[192:195], v[216:219], v[18:21]
	v_mfma_f32_16x16x32_bf16 v[6:9], v[184:187], v[224:227], v[6:9]
	v_mfma_f32_16x16x32_bf16 v[2:5], v[192:195], v[224:227], v[2:5]
	v_mfma_f32_16x16x32_bf16 v[54:57], v[188:191], v[204:207], v[54:57]
	v_mfma_f32_16x16x32_bf16 v[50:53], v[196:199], v[204:207], v[50:53]
	v_mfma_f32_16x16x32_bf16 v[38:41], v[188:191], v[212:215], v[38:41]
	v_mfma_f32_16x16x32_bf16 v[34:37], v[196:199], v[212:215], v[34:37]
	v_mfma_f32_16x16x32_bf16 v[22:25], v[188:191], v[220:223], v[22:25]
	v_mfma_f32_16x16x32_bf16 v[18:21], v[196:199], v[220:223], v[18:21]
	v_mfma_f32_16x16x32_bf16 v[6:9], v[188:191], v[228:231], v[6:9]
	v_mfma_f32_16x16x32_bf16 v[2:5], v[196:199], v[228:231], v[2:5]
	s_setprio 0
	s_barrier
	s_add_i32 s51, s51, 2
	s_add_u32 s36, s36, 0x100
	s_addc_u32 s37, s37, 0
	s_add_u32 s49, s49, 0x100
	s_addc_u32 s50, s50, 0
	s_cmp_gt_u32 s51, 13
	s_cbranch_scc0 .LBB0_1654
	s_and_b64 vcc, exec, s[10:11]
	s_cbranch_vccz .LBB0_1657
	s_barrier

.LBB0_1687:
	ds_read_b128 v[150:153], v131
	ds_read_b128 v[154:157], v131 offset:1024
	ds_read_b128 v[158:161], v131 offset:2048
	ds_read_b128 v[162:165], v131 offset:3072
	ds_read_b128 v[170:173], v146
	ds_read_b128 v[174:177], v146 offset:1024
	ds_read_b128 v[178:181], v146 offset:2048
	ds_read_b128 v[182:185], v146 offset:3072
	s_add_u32 s14, s10, s12
	s_addc_u32 s15, s11, s13
	s_add_u32 s14, s14, 0xd600100
	s_addc_u32 s15, s15, 0
	s_add_u32 s51, s38, s12
	s_addc_u32 s52, s39, s13
	s_cmpk_eq_i32 s12, 0x300
	s_cselect_b32 s17, s7, s15
	s_cselect_b32 s16, s6, s14
	s_cselect_b32 s15, s5, s52
	s_cselect_b32 s14, s4, s51
	s_mov_b32 m0, s41
	v_lshl_add_u64 v[166:167], v[142:143], 0, s[12:13]
	ds_read_b128 v[186:189], v147
	ds_read_b128 v[190:193], v147 offset:1024
	ds_read_b128 v[194:197], v147 offset:2048
	ds_read_b128 v[198:201], v147 offset:3072
	ds_read_b128 v[202:205], v147 offset:4096
	ds_read_b128 v[206:209], v147 offset:5120
	ds_read_b128 v[210:213], v147 offset:6144
	ds_read_b128 v[214:217], v147 offset:7168
	global_load_lds_dwordx4 v[166:167], off
	v_lshl_add_u64 v[166:167], v[144:145], 0, s[12:13]
	s_mov_b32 m0, s42
	s_nop 0
	global_load_lds_dwordx4 v[166:167], off
	s_waitcnt vmcnt(8)
	s_waitcnt lgkmcnt(0)
	s_barrier
	s_setprio 1
	v_mfma_f32_16x16x32_bf16 v[50:53], v[150:153], v[186:189], v[50:53]
	v_mfma_f32_16x16x32_bf16 v[54:57], v[158:161], v[186:189], v[54:57]
	v_mfma_f32_16x16x32_bf16 v[82:85], v[150:153], v[194:197], v[82:85]
	v_mfma_f32_16x16x32_bf16 v[86:89], v[158:161], v[194:197], v[86:89]
	v_mfma_f32_16x16x32_bf16 v[114:117], v[150:153], v[202:205], v[114:117]
	v_mfma_f32_16x16x32_bf16 v[118:121], v[158:161], v[202:205], v[118:121]
	v_mfma_f32_16x16x32_bf16 v[110:113], v[150:153], v[210:213], v[110:113]
	v_mfma_f32_16x16x32_bf16 v[106:109], v[158:161], v[210:213], v[106:109]
	v_mfma_f32_16x16x32_bf16 v[50:53], v[154:157], v[190:193], v[50:53]
	v_mfma_f32_16x16x32_bf16 v[54:57], v[162:165], v[190:193], v[54:57]
	v_mfma_f32_16x16x32_bf16 v[82:85], v[154:157], v[198:201], v[82:85]
	v_mfma_f32_16x16x32_bf16 v[86:89], v[162:165], v[198:201], v[86:89]
	v_mfma_f32_16x16x32_bf16 v[114:117], v[154:157], v[206:209], v[114:117]
	v_mfma_f32_16x16x32_bf16 v[118:121], v[162:165], v[206:209], v[118:121]
	v_mfma_f32_16x16x32_bf16 v[110:113], v[154:157], v[214:217], v[110:113]
	v_mfma_f32_16x16x32_bf16 v[106:109], v[162:165], v[214:217], v[106:109]
	v_mfma_f32_16x16x32_bf16 v[58:61], v[170:173], v[186:189], v[58:61]
	v_mfma_f32_16x16x32_bf16 v[62:65], v[178:181], v[186:189], v[62:65]
	v_mfma_f32_16x16x32_bf16 v[90:93], v[170:173], v[194:197], v[90:93]
	v_mfma_f32_16x16x32_bf16 v[98:101], v[178:181], v[194:197], v[98:101]
	v_mfma_f32_16x16x32_bf16 v[122:125], v[170:173], v[202:205], v[122:125]
	v_mfma_f32_16x16x32_bf16 v[126:129], v[178:181], v[202:205], v[126:129]
	v_mfma_f32_16x16x32_bf16 v[102:105], v[170:173], v[210:213], v[102:105]
	v_mfma_f32_16x16x32_bf16 v[94:97], v[178:181], v[210:213], v[94:97]
	v_mfma_f32_16x16x32_bf16 v[58:61], v[174:177], v[190:193], v[58:61]
	v_mfma_f32_16x16x32_bf16 v[62:65], v[182:185], v[190:193], v[62:65]
	v_mfma_f32_16x16x32_bf16 v[90:93], v[174:177], v[198:201], v[90:93]
	v_mfma_f32_16x16x32_bf16 v[98:101], v[182:185], v[198:201], v[98:101]
	v_mfma_f32_16x16x32_bf16 v[122:125], v[174:177], v[206:209], v[122:125]
	v_mfma_f32_16x16x32_bf16 v[126:129], v[182:185], v[206:209], v[126:129]
	v_mfma_f32_16x16x32_bf16 v[102:105], v[174:177], v[214:217], v[102:105]
	v_mfma_f32_16x16x32_bf16 v[94:97], v[182:185], v[214:217], v[94:97]
	s_setprio 0
	s_barrier
	s_mov_b32 m0, s43
	v_lshl_add_u64 v[166:167], s[14:15], 0, v[136:137]
	s_add_u32 s52, s14, 0x30000
	ds_read_b128 v[186:189], v147 offset:16384
	ds_read_b128 v[190:193], v147 offset:17408
	ds_read_b128 v[194:197], v147 offset:18432
	ds_read_b128 v[198:201], v147 offset:19456
	ds_read_b128 v[202:205], v147 offset:20480
	ds_read_b128 v[206:209], v147 offset:21504
	ds_read_b128 v[210:213], v147 offset:22528
	ds_read_b128 v[214:217], v147 offset:23552
	global_load_lds_dwordx4 v[166:167], off
	v_lshl_add_u64 v[218:219], s[14:15], 0, v[140:141]
	s_mov_b32 m0, s44
	s_addc_u32 s53, s15, 0
	global_load_lds_dwordx4 v[218:219], off
	v_lshl_add_u64 v[220:221], s[52:53], 0, v[136:137]
	s_mov_b32 m0, s45
	v_lshl_add_u64 v[222:223], s[16:17], 0, v[134:135]
	global_load_lds_dwordx4 v[220:221], off
	v_lshl_add_u64 v[220:221], s[52:53], 0, v[140:141]
	s_mov_b32 m0, s46
	s_nop 0
	global_load_lds_dwordx4 v[220:221], off
	v_lshl_add_u64 v[220:221], s[16:17], 0, v[132:133]
	s_mov_b32 m0, s29
	s_nop 0
	global_load_lds_dwordx4 v[220:221], off
	s_mov_b32 m0, s30
	s_nop 0
	global_load_lds_dwordx4 v[222:223], off
	s_waitcnt vmcnt(8)
	s_waitcnt lgkmcnt(0)
	s_barrier
	s_setprio 1
	v_mfma_f32_16x16x32_bf16 v[78:81], v[150:153], v[186:189], v[78:81]
	v_mfma_f32_16x16x32_bf16 v[74:77], v[158:161], v[186:189], v[74:77]
	v_mfma_f32_16x16x32_bf16 v[46:49], v[150:153], v[194:197], v[46:49]
	v_mfma_f32_16x16x32_bf16 v[42:45], v[158:161], v[194:197], v[42:45]
	v_mfma_f32_16x16x32_bf16 v[30:33], v[150:153], v[202:205], v[30:33]
	v_mfma_f32_16x16x32_bf16 v[26:29], v[158:161], v[202:205], v[26:29]
	v_mfma_f32_16x16x32_bf16 v[14:17], v[150:153], v[210:213], v[14:17]
	v_mfma_f32_16x16x32_bf16 v[10:13], v[158:161], v[210:213], v[10:13]
	v_mfma_f32_16x16x32_bf16 v[78:81], v[154:157], v[190:193], v[78:81]
	v_mfma_f32_16x16x32_bf16 v[74:77], v[162:165], v[190:193], v[74:77]
	v_mfma_f32_16x16x32_bf16 v[46:49], v[154:157], v[198:201], v[46:49]
	v_mfma_f32_16x16x32_bf16 v[42:45], v[162:165], v[198:201], v[42:45]
	v_mfma_f32_16x16x32_bf16 v[30:33], v[154:157], v[206:209], v[30:33]
	v_mfma_f32_16x16x32_bf16 v[26:29], v[162:165], v[206:209], v[26:29]
	v_mfma_f32_16x16x32_bf16 v[14:17], v[154:157], v[214:217], v[14:17]
	v_mfma_f32_16x16x32_bf16 v[10:13], v[162:165], v[214:217], v[10:13]
	v_mfma_f32_16x16x32_bf16 v[70:73], v[170:173], v[186:189], v[70:73]
	v_mfma_f32_16x16x32_bf16 v[66:69], v[178:181], v[186:189], v[66:69]
	v_mfma_f32_16x16x32_bf16 v[38:41], v[170:173], v[194:197], v[38:41]
	v_mfma_f32_16x16x32_bf16 v[34:37], v[178:181], v[194:197], v[34:37]
	v_mfma_f32_16x16x32_bf16 v[22:25], v[170:173], v[202:205], v[22:25]
	v_mfma_f32_16x16x32_bf16 v[18:21], v[178:181], v[202:205], v[18:21]
	v_mfma_f32_16x16x32_bf16 v[6:9], v[170:173], v[210:213], v[6:9]
	v_mfma_f32_16x16x32_bf16 v[2:5], v[178:181], v[210:213], v[2:5]
	v_mfma_f32_16x16x32_bf16 v[70:73], v[174:177], v[190:193], v[70:73]
	v_mfma_f32_16x16x32_bf16 v[66:69], v[182:185], v[190:193], v[66:69]
	v_mfma_f32_16x16x32_bf16 v[38:41], v[174:177], v[198:201], v[38:41]
	v_mfma_f32_16x16x32_bf16 v[34:37], v[182:185], v[198:201], v[34:37]
	v_mfma_f32_16x16x32_bf16 v[22:25], v[174:177], v[206:209], v[22:25]
	v_mfma_f32_16x16x32_bf16 v[18:21], v[182:185], v[206:209], v[18:21]
	v_mfma_f32_16x16x32_bf16 v[6:9], v[174:177], v[214:217], v[6:9]
	v_mfma_f32_16x16x32_bf16 v[2:5], v[182:185], v[214:217], v[2:5]
	s_setprio 0
	s_barrier
	ds_read_b128 v[150:153], v148
	ds_read_b128 v[154:157], v148 offset:1024
	ds_read_b128 v[158:161], v148 offset:2048
	ds_read_b128 v[162:165], v148 offset:3072
	ds_read_b128 v[170:173], v149
	ds_read_b128 v[174:177], v149 offset:1024
	ds_read_b128 v[178:181], v149 offset:2048
	ds_read_b128 v[182:185], v149 offset:3072
	s_add_u32 s16, s16, 0x30000
	s_addc_u32 s17, s17, 0
	s_mov_b32 m0, s31
	v_lshl_add_u64 v[224:225], s[16:17], 0, v[132:133]
	ds_read_b128 v[186:189], v147 offset:32768
	ds_read_b128 v[190:193], v147 offset:33792
	ds_read_b128 v[194:197], v147 offset:34816
	ds_read_b128 v[198:201], v147 offset:35840
	ds_read_b128 v[202:205], v147 offset:36864
	ds_read_b128 v[206:209], v147 offset:37888
	ds_read_b128 v[210:213], v147 offset:38912
	ds_read_b128 v[214:217], v147 offset:39936
	global_load_lds_dwordx4 v[224:225], off
	v_lshl_add_u64 v[224:225], s[16:17], 0, v[134:135]
	s_mov_b32 m0, s33
	s_nop 0
	global_load_lds_dwordx4 v[224:225], off
	s_waitcnt vmcnt(8)
	s_waitcnt lgkmcnt(0)
	s_barrier
	s_setprio 1
	v_mfma_f32_16x16x32_bf16 v[50:53], v[150:153], v[186:189], v[50:53]
	v_mfma_f32_16x16x32_bf16 v[54:57], v[158:161], v[186:189], v[54:57]
	v_mfma_f32_16x16x32_bf16 v[82:85], v[150:153], v[194:197], v[82:85]
	v_mfma_f32_16x16x32_bf16 v[86:89], v[158:161], v[194:197], v[86:89]
	v_mfma_f32_16x16x32_bf16 v[114:117], v[150:153], v[202:205], v[114:117]
	v_mfma_f32_16x16x32_bf16 v[118:121], v[158:161], v[202:205], v[118:121]
	v_mfma_f32_16x16x32_bf16 v[110:113], v[150:153], v[210:213], v[110:113]
	v_mfma_f32_16x16x32_bf16 v[106:109], v[158:161], v[210:213], v[106:109]
	v_mfma_f32_16x16x32_bf16 v[50:53], v[154:157], v[190:193], v[50:53]
	v_mfma_f32_16x16x32_bf16 v[54:57], v[162:165], v[190:193], v[54:57]
	v_mfma_f32_16x16x32_bf16 v[82:85], v[154:157], v[198:201], v[82:85]
	v_mfma_f32_16x16x32_bf16 v[86:89], v[162:165], v[198:201], v[86:89]
	v_mfma_f32_16x16x32_bf16 v[114:117], v[154:157], v[206:209], v[114:117]
	v_mfma_f32_16x16x32_bf16 v[118:121], v[162:165], v[206:209], v[118:121]
	v_mfma_f32_16x16x32_bf16 v[110:113], v[154:157], v[214:217], v[110:113]
	v_mfma_f32_16x16x32_bf16 v[106:109], v[162:165], v[214:217], v[106:109]
	v_mfma_f32_16x16x32_bf16 v[58:61], v[170:173], v[186:189], v[58:61]
	v_mfma_f32_16x16x32_bf16 v[62:65], v[178:181], v[186:189], v[62:65]
	v_mfma_f32_16x16x32_bf16 v[90:93], v[170:173], v[194:197], v[90:93]
	v_mfma_f32_16x16x32_bf16 v[98:101], v[178:181], v[194:197], v[98:101]
	v_mfma_f32_16x16x32_bf16 v[122:125], v[170:173], v[202:205], v[122:125]
	v_mfma_f32_16x16x32_bf16 v[126:129], v[178:181], v[202:205], v[126:129]
	v_mfma_f32_16x16x32_bf16 v[102:105], v[170:173], v[210:213], v[102:105]
	v_mfma_f32_16x16x32_bf16 v[94:97], v[178:181], v[210:213], v[94:97]
	v_mfma_f32_16x16x32_bf16 v[58:61], v[174:177], v[190:193], v[58:61]
	v_mfma_f32_16x16x32_bf16 v[62:65], v[182:185], v[190:193], v[62:65]
	v_mfma_f32_16x16x32_bf16 v[90:93], v[174:177], v[198:201], v[90:93]
	v_mfma_f32_16x16x32_bf16 v[98:101], v[182:185], v[198:201], v[98:101]
	v_mfma_f32_16x16x32_bf16 v[122:125], v[174:177], v[206:209], v[122:125]
	v_mfma_f32_16x16x32_bf16 v[126:129], v[182:185], v[206:209], v[126:129]
	v_mfma_f32_16x16x32_bf16 v[102:105], v[174:177], v[214:217], v[102:105]
	v_mfma_f32_16x16x32_bf16 v[94:97], v[182:185], v[214:217], v[94:97]
	s_setprio 0
	s_barrier
	s_mov_b32 m0, s47
	v_lshl_add_u64 v[166:167], v[166:167], 0, s[8:9]
	s_add_u32 s14, s14, 0x30080
	ds_read_b128 v[186:189], v147 offset:49152
	ds_read_b128 v[190:193], v147 offset:50176
	ds_read_b128 v[194:197], v147 offset:51200
	ds_read_b128 v[198:201], v147 offset:52224
	ds_read_b128 v[202:205], v147 offset:53248
	ds_read_b128 v[206:209], v147 offset:54272
	ds_read_b128 v[210:213], v147 offset:55296
	ds_read_b128 v[214:217], v147 offset:56320
	global_load_lds_dwordx4 v[166:167], off
	v_lshl_add_u64 v[166:167], v[218:219], 0, s[8:9]
	s_mov_b32 m0, s48
	s_addc_u32 s15, s15, 0
	global_load_lds_dwordx4 v[166:167], off
	v_lshl_add_u64 v[166:167], s[14:15], 0, v[136:137]
	s_mov_b32 m0, s49
	s_nop 0
	global_load_lds_dwordx4 v[166:167], off
	v_lshl_add_u64 v[166:167], s[14:15], 0, v[140:141]
	s_mov_b32 m0, s50
	s_nop 0
	global_load_lds_dwordx4 v[166:167], off
	v_lshl_add_u64 v[166:167], v[220:221], 0, s[8:9]
	s_mov_b32 m0, s36
	s_nop 0
	global_load_lds_dwordx4 v[166:167], off
	v_lshl_add_u64 v[166:167], v[222:223], 0, s[8:9]
	s_mov_b32 m0, s37
	s_nop 0
	global_load_lds_dwordx4 v[166:167], off
	s_waitcnt vmcnt(8)
	s_waitcnt lgkmcnt(0)
	s_barrier
	s_setprio 1
	v_mfma_f32_16x16x32_bf16 v[78:81], v[150:153], v[186:189], v[78:81]
	v_mfma_f32_16x16x32_bf16 v[74:77], v[158:161], v[186:189], v[74:77]
	v_mfma_f32_16x16x32_bf16 v[46:49], v[150:153], v[194:197], v[46:49]
	v_mfma_f32_16x16x32_bf16 v[42:45], v[158:161], v[194:197], v[42:45]
	v_mfma_f32_16x16x32_bf16 v[30:33], v[150:153], v[202:205], v[30:33]
	v_mfma_f32_16x16x32_bf16 v[26:29], v[158:161], v[202:205], v[26:29]
	v_mfma_f32_16x16x32_bf16 v[14:17], v[150:153], v[210:213], v[14:17]
	v_mfma_f32_16x16x32_bf16 v[10:13], v[158:161], v[210:213], v[10:13]
	v_mfma_f32_16x16x32_bf16 v[78:81], v[154:157], v[190:193], v[78:81]
	v_mfma_f32_16x16x32_bf16 v[74:77], v[162:165], v[190:193], v[74:77]
	v_mfma_f32_16x16x32_bf16 v[46:49], v[154:157], v[198:201], v[46:49]
	v_mfma_f32_16x16x32_bf16 v[42:45], v[162:165], v[198:201], v[42:45]
	v_mfma_f32_16x16x32_bf16 v[30:33], v[154:157], v[206:209], v[30:33]
	v_mfma_f32_16x16x32_bf16 v[26:29], v[162:165], v[206:209], v[26:29]
	v_mfma_f32_16x16x32_bf16 v[14:17], v[154:157], v[214:217], v[14:17]
	v_mfma_f32_16x16x32_bf16 v[10:13], v[162:165], v[214:217], v[10:13]
	v_mfma_f32_16x16x32_bf16 v[70:73], v[170:173], v[186:189], v[70:73]
	v_mfma_f32_16x16x32_bf16 v[66:69], v[178:181], v[186:189], v[66:69]
	v_mfma_f32_16x16x32_bf16 v[38:41], v[170:173], v[194:197], v[38:41]
	v_mfma_f32_16x16x32_bf16 v[34:37], v[178:181], v[194:197], v[34:37]
	v_mfma_f32_16x16x32_bf16 v[22:25], v[170:173], v[202:205], v[22:25]
	v_mfma_f32_16x16x32_bf16 v[18:21], v[178:181], v[202:205], v[18:21]
	v_mfma_f32_16x16x32_bf16 v[6:9], v[170:173], v[210:213], v[6:9]
	v_mfma_f32_16x16x32_bf16 v[2:5], v[178:181], v[210:213], v[2:5]
	v_mfma_f32_16x16x32_bf16 v[70:73], v[174:177], v[190:193], v[70:73]
	v_mfma_f32_16x16x32_bf16 v[66:69], v[182:185], v[190:193], v[66:69]
	v_mfma_f32_16x16x32_bf16 v[38:41], v[174:177], v[198:201], v[38:41]
	v_mfma_f32_16x16x32_bf16 v[34:37], v[182:185], v[198:201], v[34:37]
	v_mfma_f32_16x16x32_bf16 v[22:25], v[174:177], v[206:209], v[22:25]
	v_mfma_f32_16x16x32_bf16 v[18:21], v[182:185], v[206:209], v[18:21]
	v_mfma_f32_16x16x32_bf16 v[6:9], v[174:177], v[214:217], v[6:9]
	v_mfma_f32_16x16x32_bf16 v[2:5], v[182:185], v[214:217], v[2:5]
	s_setprio 0
	s_barrier
	s_add_i32 s40, s40, 2
	s_add_u32 s12, s12, 0x100
	s_addc_u32 s13, s13, 0
	s_cmp_lt_u32 s40, 6
	s_cbranch_scc1 .LBB0_1687
	s_waitcnt vmcnt(0)
	s_cmpk_gt_u32 s28, 0xff
	s_cbranch_scc1 .LBB0_1690
	s_barrier

.LBB0_1692:
	s_lshl_b32 s11, s11, 5
	s_lshl_b32 s9, s10, 6
	s_lshl_b32 s23, s10, 13
	s_and_b32 s10, s11, 0x60
	s_add_i32 s11, s24, s28
	s_mov_b64 s[14:15], 0x80
	v_lshl_add_u64 v[142:143], v[156:157], 0, s[14:15]
	s_mov_b32 m0, s11
	s_add_i32 s13, s11, 0x2000
	s_lshl_b32 s29, s10, 7
	s_waitcnt vmcnt(2)
	s_barrier
	global_load_lds_dwordx4 v[142:143], off
	v_lshl_add_u64 v[144:145], v[158:159], 0, s[14:15]
	s_mov_b32 m0, s13
	v_lshl_add_u64 v[130:131], v[164:165], 0, s[14:15]
	s_add_i32 s12, s22, 0x8000
	v_lshl_add_u64 v[146:147], v[166:167], 0, s[14:15]
	s_add_i32 s14, s22, 0xa000
	global_load_lds_dwordx4 v[144:145], off
	s_mov_b32 m0, s12
	s_add_u32 s30, s4, 0x30080
	global_load_lds_dwordx4 v[130:131], off
	s_mov_b32 m0, s14
	s_addc_u32 s31, s5, 0
	s_add_i32 s15, s25, s28
	global_load_lds_dwordx4 v[146:147], off
	v_lshl_add_u64 v[148:149], s[30:31], 0, v[136:137]
	s_mov_b32 m0, s15
	s_add_i32 s16, s15, 0x2000
	global_load_lds_dwordx4 v[148:149], off
	v_lshl_add_u64 v[150:151], s[30:31], 0, v[140:141]
	s_mov_b32 m0, s16
	v_bfe_u32 v170, v0, 4, 2
	global_load_lds_dwordx4 v[150:151], off
	v_lshlrev_b32_e32 v171, 4, v170
	v_or_b32_e32 v139, v171, v139
	v_bitop3_b32 v139, s29, v139, v168 bitop3:0xf6
	v_lshl_or_b32 v204, v1, 6, v171
	v_add_u32_e32 v171, s19, v139
	s_waitcnt vmcnt(6)
	s_barrier
	v_add_u32_e32 v236, s18, v139
	ds_read_b128 v[172:175], v171
	ds_read_b128 v[176:179], v171 offset:1024
	ds_read_b128 v[180:183], v171 offset:2048
	ds_read_b128 v[184:187], v171 offset:3072
	ds_read_b128 v[188:191], v236
	ds_read_b128 v[192:195], v236 offset:1024
	ds_read_b128 v[196:199], v236 offset:2048
	ds_read_b128 v[200:203], v236 offset:3072
	v_bitop3_b32 v168, v204, s23, v169 bitop3:0xde
	v_add_u32_e32 v252, 0, v168
	v_add_u32_e32 v240, s24, v139
	v_add_u32_e32 v139, s25, v139
	s_add_u32 s30, s2, 0x30080
	s_addc_u32 s31, s3, 0
	s_add_i32 s25, s22, 0xc000
	v_lshl_add_u64 v[168:169], s[30:31], 0, v[132:133]
	s_mov_b32 m0, s25
	s_add_i32 s23, s22, 0xe000
	ds_read_b128 v[204:207], v252
	ds_read_b128 v[208:211], v252 offset:1024
	ds_read_b128 v[212:215], v252 offset:2048
	ds_read_b128 v[216:219], v252 offset:3072
	ds_read_b128 v[220:223], v252 offset:4096
	ds_read_b128 v[224:227], v252 offset:5120
	ds_read_b128 v[228:231], v252 offset:6144
	ds_read_b128 v[232:235], v252 offset:7168
	global_load_lds_dwordx4 v[168:169], off
	v_lshl_add_u64 v[168:169], s[30:31], 0, v[134:135]
	s_mov_b32 m0, s23
	s_nop 0
	global_load_lds_dwordx4 v[168:169], off
	s_waitcnt vmcnt(8)
	s_waitcnt lgkmcnt(0)
	s_barrier
	s_setprio 1
	v_mfma_f32_16x16x32_bf16 v[50:53], v[172:175], v[204:207], v[50:53]
	v_mfma_f32_16x16x32_bf16 v[54:57], v[180:183], v[204:207], v[54:57]
	v_mfma_f32_16x16x32_bf16 v[82:85], v[172:175], v[212:215], v[82:85]
	v_mfma_f32_16x16x32_bf16 v[86:89], v[180:183], v[212:215], v[86:89]
	v_mfma_f32_16x16x32_bf16 v[114:117], v[172:175], v[220:223], v[114:117]
	v_mfma_f32_16x16x32_bf16 v[118:121], v[180:183], v[220:223], v[118:121]
	v_mfma_f32_16x16x32_bf16 v[110:113], v[172:175], v[228:231], v[110:113]
	v_mfma_f32_16x16x32_bf16 v[106:109], v[180:183], v[228:231], v[106:109]
	v_mfma_f32_16x16x32_bf16 v[50:53], v[176:179], v[208:211], v[50:53]
	v_mfma_f32_16x16x32_bf16 v[54:57], v[184:187], v[208:211], v[54:57]
	v_mfma_f32_16x16x32_bf16 v[82:85], v[176:179], v[216:219], v[82:85]
	v_mfma_f32_16x16x32_bf16 v[86:89], v[184:187], v[216:219], v[86:89]
	v_mfma_f32_16x16x32_bf16 v[114:117], v[176:179], v[224:227], v[114:117]
	v_mfma_f32_16x16x32_bf16 v[118:121], v[184:187], v[224:227], v[118:121]
	v_mfma_f32_16x16x32_bf16 v[110:113], v[176:179], v[232:235], v[110:113]
	v_mfma_f32_16x16x32_bf16 v[106:109], v[184:187], v[232:235], v[106:109]
	v_mfma_f32_16x16x32_bf16 v[58:61], v[188:191], v[204:207], v[58:61]
	v_mfma_f32_16x16x32_bf16 v[62:65], v[196:199], v[204:207], v[62:65]
	v_mfma_f32_16x16x32_bf16 v[90:93], v[188:191], v[212:215], v[90:93]
	v_mfma_f32_16x16x32_bf16 v[98:101], v[196:199], v[212:215], v[98:101]
	v_mfma_f32_16x16x32_bf16 v[122:125], v[188:191], v[220:223], v[122:125]
	v_mfma_f32_16x16x32_bf16 v[126:129], v[196:199], v[220:223], v[126:129]
	v_mfma_f32_16x16x32_bf16 v[102:105], v[188:191], v[228:231], v[102:105]
	v_mfma_f32_16x16x32_bf16 v[94:97], v[196:199], v[228:231], v[94:97]
	v_mfma_f32_16x16x32_bf16 v[58:61], v[192:195], v[208:211], v[58:61]
	v_mfma_f32_16x16x32_bf16 v[62:65], v[200:203], v[208:211], v[62:65]
	v_mfma_f32_16x16x32_bf16 v[90:93], v[192:195], v[216:219], v[90:93]
	v_mfma_f32_16x16x32_bf16 v[98:101], v[200:203], v[216:219], v[98:101]
	v_mfma_f32_16x16x32_bf16 v[122:125], v[192:195], v[224:227], v[122:125]
	v_mfma_f32_16x16x32_bf16 v[126:129], v[200:203], v[224:227], v[126:129]
	v_mfma_f32_16x16x32_bf16 v[102:105], v[192:195], v[232:235], v[102:105]
	v_mfma_f32_16x16x32_bf16 v[94:97], v[200:203], v[232:235], v[94:97]
	s_setprio 0
	s_barrier
	s_add_i32 s19, s19, s28
	s_mov_b64 s[30:31], 0x100
	s_add_i32 s24, s19, 0x2000
	v_lshl_add_u64 v[168:169], v[156:157], 0, s[30:31]
	s_mov_b32 m0, s19
	s_add_u32 s34, s4, 0x30100
	ds_read_b128 v[204:207], v252 offset:16384
	ds_read_b128 v[208:211], v252 offset:17408
	ds_read_b128 v[212:215], v252 offset:18432
	ds_read_b128 v[216:219], v252 offset:19456
	ds_read_b128 v[220:223], v252 offset:20480
	ds_read_b128 v[224:227], v252 offset:21504
	ds_read_b128 v[228:231], v252 offset:22528
	ds_read_b128 v[232:235], v252 offset:23552
	global_load_lds_dwordx4 v[168:169], off
	v_lshl_add_u64 v[168:169], v[158:159], 0, s[30:31]
	s_mov_b32 m0, s24
	s_addc_u32 s35, s5, 0
	s_add_i32 s18, s18, s28
	global_load_lds_dwordx4 v[168:169], off
	v_lshl_add_u64 v[168:169], s[34:35], 0, v[136:137]
	s_mov_b32 m0, s18
	s_add_i32 s28, s18, 0x2000
	global_load_lds_dwordx4 v[168:169], off
	v_lshl_add_u64 v[168:169], s[34:35], 0, v[140:141]
	s_mov_b32 m0, s28
	s_nop 0
	global_load_lds_dwordx4 v[168:169], off
	v_lshl_add_u64 v[168:169], v[164:165], 0, s[30:31]
	s_mov_b32 m0, s22
	s_nop 0
	global_load_lds_dwordx4 v[168:169], off
	v_lshl_add_u64 v[168:169], v[166:167], 0, s[30:31]
	s_mov_b32 m0, s21
	s_nop 0
	global_load_lds_dwordx4 v[168:169], off
	s_waitcnt vmcnt(8)
	s_waitcnt lgkmcnt(0)
	s_barrier
	s_setprio 1
	v_mfma_f32_16x16x32_bf16 v[46:49], v[172:175], v[212:215], v[46:49]
	v_mfma_f32_16x16x32_bf16 v[42:45], v[180:183], v[212:215], v[42:45]
	v_mfma_f32_16x16x32_bf16 v[30:33], v[172:175], v[220:223], v[30:33]
	v_mfma_f32_16x16x32_bf16 v[26:29], v[180:183], v[220:223], v[26:29]
	v_mfma_f32_16x16x32_bf16 v[14:17], v[172:175], v[228:231], v[14:17]
	v_mfma_f32_16x16x32_bf16 v[10:13], v[180:183], v[228:231], v[10:13]
	v_mfma_f32_16x16x32_bf16 v[78:81], v[172:175], v[204:207], v[78:81]
	v_mfma_f32_16x16x32_bf16 v[74:77], v[180:183], v[204:207], v[74:77]
	v_mfma_f32_16x16x32_bf16 v[46:49], v[176:179], v[216:219], v[46:49]
	v_mfma_f32_16x16x32_bf16 v[42:45], v[184:187], v[216:219], v[42:45]
	v_mfma_f32_16x16x32_bf16 v[30:33], v[176:179], v[224:227], v[30:33]
	v_mfma_f32_16x16x32_bf16 v[26:29], v[184:187], v[224:227], v[26:29]
	v_mfma_f32_16x16x32_bf16 v[14:17], v[176:179], v[232:235], v[14:17]
	v_mfma_f32_16x16x32_bf16 v[10:13], v[184:187], v[232:235], v[10:13]
	v_mfma_f32_16x16x32_bf16 v[78:81], v[176:179], v[208:211], v[78:81]
	v_mfma_f32_16x16x32_bf16 v[74:77], v[184:187], v[208:211], v[74:77]
	v_mfma_f32_16x16x32_bf16 v[70:73], v[188:191], v[204:207], v[70:73]
	v_mfma_f32_16x16x32_bf16 v[66:69], v[196:199], v[204:207], v[66:69]
	v_mfma_f32_16x16x32_bf16 v[38:41], v[188:191], v[212:215], v[38:41]
	v_mfma_f32_16x16x32_bf16 v[34:37], v[196:199], v[212:215], v[34:37]
	v_mfma_f32_16x16x32_bf16 v[22:25], v[188:191], v[220:223], v[22:25]
	v_mfma_f32_16x16x32_bf16 v[18:21], v[196:199], v[220:223], v[18:21]
	v_mfma_f32_16x16x32_bf16 v[6:9], v[188:191], v[228:231], v[6:9]
	v_mfma_f32_16x16x32_bf16 v[2:5], v[196:199], v[228:231], v[2:5]
	v_mfma_f32_16x16x32_bf16 v[70:73], v[192:195], v[208:211], v[70:73]
	v_mfma_f32_16x16x32_bf16 v[66:69], v[200:203], v[208:211], v[66:69]
	v_mfma_f32_16x16x32_bf16 v[38:41], v[192:195], v[216:219], v[38:41]
	v_mfma_f32_16x16x32_bf16 v[34:37], v[200:203], v[216:219], v[34:37]
	v_mfma_f32_16x16x32_bf16 v[22:25], v[192:195], v[224:227], v[22:25]
	v_mfma_f32_16x16x32_bf16 v[18:21], v[200:203], v[224:227], v[18:21]
	v_mfma_f32_16x16x32_bf16 v[6:9], v[192:195], v[232:235], v[6:9]
	v_mfma_f32_16x16x32_bf16 v[2:5], v[200:203], v[232:235], v[2:5]
	s_setprio 0
	s_barrier
	ds_read_b128 v[172:175], v240
	ds_read_b128 v[176:179], v240 offset:1024
	ds_read_b128 v[180:183], v240 offset:2048
	ds_read_b128 v[184:187], v240 offset:3072
	ds_read_b128 v[188:191], v139
	ds_read_b128 v[192:195], v139 offset:1024
	ds_read_b128 v[196:199], v139 offset:2048
	ds_read_b128 v[200:203], v139 offset:3072
	s_add_u32 s30, s2, 0x30100
	s_addc_u32 s31, s3, 0
	s_mov_b32 m0, s17
	v_lshl_add_u64 v[168:169], s[30:31], 0, v[132:133]
	ds_read_b128 v[204:207], v252 offset:32768
	ds_read_b128 v[208:211], v252 offset:33792
	ds_read_b128 v[212:215], v252 offset:34816
	ds_read_b128 v[216:219], v252 offset:35840
	ds_read_b128 v[220:223], v252 offset:36864
	ds_read_b128 v[224:227], v252 offset:37888
	ds_read_b128 v[228:231], v252 offset:38912
	ds_read_b128 v[232:235], v252 offset:39936
	global_load_lds_dwordx4 v[168:169], off
	v_lshl_add_u64 v[168:169], s[30:31], 0, v[134:135]
	s_mov_b32 m0, s20
	s_nop 0
	global_load_lds_dwordx4 v[168:169], off
	s_waitcnt vmcnt(8)
	s_waitcnt lgkmcnt(0)
	s_barrier
	s_setprio 1
	v_mfma_f32_16x16x32_bf16 v[50:53], v[172:175], v[204:207], v[50:53]
	v_mfma_f32_16x16x32_bf16 v[54:57], v[180:183], v[204:207], v[54:57]
	v_mfma_f32_16x16x32_bf16 v[82:85], v[172:175], v[212:215], v[82:85]
	v_mfma_f32_16x16x32_bf16 v[86:89], v[180:183], v[212:215], v[86:89]
	v_mfma_f32_16x16x32_bf16 v[114:117], v[172:175], v[220:223], v[114:117]
	v_mfma_f32_16x16x32_bf16 v[118:121], v[180:183], v[220:223], v[118:121]
	v_mfma_f32_16x16x32_bf16 v[110:113], v[172:175], v[228:231], v[110:113]
	v_mfma_f32_16x16x32_bf16 v[106:109], v[180:183], v[228:231], v[106:109]
	v_mfma_f32_16x16x32_bf16 v[50:53], v[176:179], v[208:211], v[50:53]
	v_mfma_f32_16x16x32_bf16 v[54:57], v[184:187], v[208:211], v[54:57]
	v_mfma_f32_16x16x32_bf16 v[82:85], v[176:179], v[216:219], v[82:85]
	v_mfma_f32_16x16x32_bf16 v[86:89], v[184:187], v[216:219], v[86:89]
	v_mfma_f32_16x16x32_bf16 v[114:117], v[176:179], v[224:227], v[114:117]
	v_mfma_f32_16x16x32_bf16 v[118:121], v[184:187], v[224:227], v[118:121]
	v_mfma_f32_16x16x32_bf16 v[110:113], v[176:179], v[232:235], v[110:113]
	v_mfma_f32_16x16x32_bf16 v[106:109], v[184:187], v[232:235], v[106:109]
	v_mfma_f32_16x16x32_bf16 v[58:61], v[188:191], v[204:207], v[58:61]
	v_mfma_f32_16x16x32_bf16 v[62:65], v[196:199], v[204:207], v[62:65]
	v_mfma_f32_16x16x32_bf16 v[90:93], v[188:191], v[212:215], v[90:93]
	v_mfma_f32_16x16x32_bf16 v[98:101], v[196:199], v[212:215], v[98:101]
	v_mfma_f32_16x16x32_bf16 v[122:125], v[188:191], v[220:223], v[122:125]
	v_mfma_f32_16x16x32_bf16 v[126:129], v[196:199], v[220:223], v[126:129]
	v_mfma_f32_16x16x32_bf16 v[102:105], v[188:191], v[228:231], v[102:105]
	v_mfma_f32_16x16x32_bf16 v[94:97], v[196:199], v[228:231], v[94:97]
	v_mfma_f32_16x16x32_bf16 v[58:61], v[192:195], v[208:211], v[58:61]
	v_mfma_f32_16x16x32_bf16 v[62:65], v[200:203], v[208:211], v[62:65]
	v_mfma_f32_16x16x32_bf16 v[90:93], v[192:195], v[216:219], v[90:93]
	v_mfma_f32_16x16x32_bf16 v[98:101], v[200:203], v[216:219], v[98:101]
	v_mfma_f32_16x16x32_bf16 v[122:125], v[192:195], v[224:227], v[122:125]
	v_mfma_f32_16x16x32_bf16 v[126:129], v[200:203], v[224:227], v[126:129]
	v_mfma_f32_16x16x32_bf16 v[102:105], v[192:195], v[232:235], v[102:105]
	v_mfma_f32_16x16x32_bf16 v[94:97], v[200:203], v[232:235], v[94:97]
	s_setprio 0
	s_barrier
	s_mov_b64 s[30:31], 0x180
	s_mov_b32 m0, s11
	v_lshl_add_u64 v[168:169], v[156:157], 0, s[30:31]
	s_add_u32 s4, s4, 0x30180
	ds_read_b128 v[204:207], v252 offset:49152
	ds_read_b128 v[208:211], v252 offset:50176
	ds_read_b128 v[212:215], v252 offset:51200
	ds_read_b128 v[216:219], v252 offset:52224
	ds_read_b128 v[220:223], v252 offset:53248
	ds_read_b128 v[224:227], v252 offset:54272
	ds_read_b128 v[228:231], v252 offset:55296
	ds_read_b128 v[232:235], v252 offset:56320
	global_load_lds_dwordx4 v[168:169], off
	v_lshl_add_u64 v[168:169], v[158:159], 0, s[30:31]
	s_mov_b32 m0, s13
	s_addc_u32 s5, s5, 0
	global_load_lds_dwordx4 v[168:169], off
	v_lshl_add_u64 v[136:137], s[4:5], 0, v[136:137]
	s_mov_b32 m0, s15
	s_nop 0
	global_load_lds_dwordx4 v[136:137], off
	v_lshl_add_u64 v[136:137], s[4:5], 0, v[140:141]
	s_mov_b32 m0, s16
	s_nop 0
	global_load_lds_dwordx4 v[136:137], off
	v_lshl_add_u64 v[136:137], v[164:165], 0, s[30:31]
	s_mov_b32 m0, s12
	s_nop 0
	global_load_lds_dwordx4 v[136:137], off
	v_lshl_add_u64 v[136:137], v[166:167], 0, s[30:31]
	s_mov_b32 m0, s14
	s_nop 0
	global_load_lds_dwordx4 v[136:137], off
	s_waitcnt vmcnt(8)
	s_waitcnt lgkmcnt(0)
	s_barrier
	s_setprio 1
	v_mfma_f32_16x16x32_bf16 v[46:49], v[172:175], v[212:215], v[46:49]
	v_mfma_f32_16x16x32_bf16 v[42:45], v[180:183], v[212:215], v[42:45]
	v_mfma_f32_16x16x32_bf16 v[30:33], v[172:175], v[220:223], v[30:33]
	v_mfma_f32_16x16x32_bf16 v[26:29], v[180:183], v[220:223], v[26:29]
	v_mfma_f32_16x16x32_bf16 v[14:17], v[172:175], v[228:231], v[14:17]
	v_mfma_f32_16x16x32_bf16 v[10:13], v[180:183], v[228:231], v[10:13]
	v_mfma_f32_16x16x32_bf16 v[78:81], v[172:175], v[204:207], v[78:81]
	v_mfma_f32_16x16x32_bf16 v[74:77], v[180:183], v[204:207], v[74:77]
	v_mfma_f32_16x16x32_bf16 v[46:49], v[176:179], v[216:219], v[46:49]
	v_mfma_f32_16x16x32_bf16 v[42:45], v[184:187], v[216:219], v[42:45]
	v_mfma_f32_16x16x32_bf16 v[30:33], v[176:179], v[224:227], v[30:33]
	v_mfma_f32_16x16x32_bf16 v[26:29], v[184:187], v[224:227], v[26:29]
	v_mfma_f32_16x16x32_bf16 v[14:17], v[176:179], v[232:235], v[14:17]
	v_mfma_f32_16x16x32_bf16 v[10:13], v[184:187], v[232:235], v[10:13]
	v_mfma_f32_16x16x32_bf16 v[78:81], v[176:179], v[208:211], v[78:81]
	v_mfma_f32_16x16x32_bf16 v[74:77], v[184:187], v[208:211], v[74:77]
	v_mfma_f32_16x16x32_bf16 v[70:73], v[188:191], v[204:207], v[70:73]
	v_mfma_f32_16x16x32_bf16 v[66:69], v[196:199], v[204:207], v[66:69]
	v_mfma_f32_16x16x32_bf16 v[38:41], v[188:191], v[212:215], v[38:41]
	v_mfma_f32_16x16x32_bf16 v[34:37], v[196:199], v[212:215], v[34:37]
	v_mfma_f32_16x16x32_bf16 v[22:25], v[188:191], v[220:223], v[22:25]
	v_mfma_f32_16x16x32_bf16 v[18:21], v[196:199], v[220:223], v[18:21]
	v_mfma_f32_16x16x32_bf16 v[6:9], v[188:191], v[228:231], v[6:9]
	v_mfma_f32_16x16x32_bf16 v[2:5], v[196:199], v[228:231], v[2:5]
	v_mfma_f32_16x16x32_bf16 v[70:73], v[192:195], v[208:211], v[70:73]
	v_mfma_f32_16x16x32_bf16 v[66:69], v[200:203], v[208:211], v[66:69]
	v_mfma_f32_16x16x32_bf16 v[38:41], v[192:195], v[216:219], v[38:41]
	v_mfma_f32_16x16x32_bf16 v[34:37], v[200:203], v[216:219], v[34:37]
	v_mfma_f32_16x16x32_bf16 v[22:25], v[192:195], v[224:227], v[22:25]
	v_mfma_f32_16x16x32_bf16 v[18:21], v[200:203], v[224:227], v[18:21]
	v_mfma_f32_16x16x32_bf16 v[6:9], v[192:195], v[232:235], v[6:9]
	v_mfma_f32_16x16x32_bf16 v[2:5], v[200:203], v[232:235], v[2:5]
	s_setprio 0
	s_barrier
	ds_read_b128 v[172:175], v171
	ds_read_b128 v[176:179], v171 offset:1024
	ds_read_b128 v[180:183], v171 offset:2048
	ds_read_b128 v[184:187], v171 offset:3072
	ds_read_b128 v[188:191], v236
	ds_read_b128 v[192:195], v236 offset:1024
	ds_read_b128 v[196:199], v236 offset:2048
	ds_read_b128 v[200:203], v236 offset:3072
	s_add_u32 s2, s2, 0x30180
	s_addc_u32 s3, s3, 0
	s_mov_b32 m0, s25
	v_lshl_add_u64 v[132:133], s[2:3], 0, v[132:133]
	ds_read_b128 v[204:207], v252
	ds_read_b128 v[208:211], v252 offset:1024
	ds_read_b128 v[212:215], v252 offset:2048
	ds_read_b128 v[216:219], v252 offset:3072
	ds_read_b128 v[220:223], v252 offset:4096
	ds_read_b128 v[224:227], v252 offset:5120
	ds_read_b128 v[228:231], v252 offset:6144
	ds_read_b128 v[232:235], v252 offset:7168
	global_load_lds_dwordx4 v[132:133], off
	v_lshl_add_u64 v[132:133], s[2:3], 0, v[134:135]
	s_mov_b32 m0, s23
	s_nop 0
	global_load_lds_dwordx4 v[132:133], off
	s_waitcnt vmcnt(8)
	s_waitcnt lgkmcnt(0)
	s_barrier
	s_setprio 1
	v_mfma_f32_16x16x32_bf16 v[50:53], v[172:175], v[204:207], v[50:53]
	v_mfma_f32_16x16x32_bf16 v[54:57], v[180:183], v[204:207], v[54:57]
	v_mfma_f32_16x16x32_bf16 v[82:85], v[172:175], v[212:215], v[82:85]
	v_mfma_f32_16x16x32_bf16 v[86:89], v[180:183], v[212:215], v[86:89]
	v_mfma_f32_16x16x32_bf16 v[114:117], v[172:175], v[220:223], v[114:117]
	v_mfma_f32_16x16x32_bf16 v[118:121], v[180:183], v[220:223], v[118:121]
	v_mfma_f32_16x16x32_bf16 v[106:109], v[180:183], v[228:231], v[106:109]
	v_mfma_f32_16x16x32_bf16 v[50:53], v[176:179], v[208:211], v[50:53]
	v_mfma_f32_16x16x32_bf16 v[54:57], v[184:187], v[208:211], v[54:57]
	v_mfma_f32_16x16x32_bf16 v[82:85], v[176:179], v[216:219], v[82:85]
	v_mfma_f32_16x16x32_bf16 v[86:89], v[184:187], v[216:219], v[86:89]
	v_mfma_f32_16x16x32_bf16 v[114:117], v[176:179], v[224:227], v[114:117]
	v_mfma_f32_16x16x32_bf16 v[118:121], v[184:187], v[224:227], v[118:121]
	v_mfma_f32_16x16x32_bf16 v[110:113], v[172:175], v[228:231], v[110:113]
	v_mfma_f32_16x16x32_bf16 v[236:239], v[184:187], v[232:235], v[106:109]
	v_mfma_f32_16x16x32_bf16 v[132:135], v[176:179], v[232:235], v[110:113]
	v_mfma_f32_16x16x32_bf16 v[90:93], v[188:191], v[212:215], v[90:93]
	v_mfma_f32_16x16x32_bf16 v[58:61], v[188:191], v[204:207], v[58:61]
	v_mfma_f32_16x16x32_bf16 v[62:65], v[196:199], v[204:207], v[62:65]
	v_mfma_f32_16x16x32_bf16 v[204:207], v[192:195], v[216:219], v[90:93]
	v_mfma_f32_16x16x32_bf16 v[90:93], v[196:199], v[212:215], v[98:101]
	v_mfma_f32_16x16x32_bf16 v[58:61], v[192:195], v[208:211], v[58:61]
	v_mfma_f32_16x16x32_bf16 v[62:65], v[200:203], v[208:211], v[62:65]
	v_mfma_f32_16x16x32_bf16 v[208:211], v[200:203], v[216:219], v[90:93]
	v_mfma_f32_16x16x32_bf16 v[90:93], v[188:191], v[220:223], v[122:125]
	v_mfma_f32_16x16x32_bf16 v[212:215], v[192:195], v[224:227], v[90:93]
	v_mfma_f32_16x16x32_bf16 v[90:93], v[196:199], v[220:223], v[126:129]
	v_mfma_f32_16x16x32_bf16 v[216:219], v[200:203], v[224:227], v[90:93]
	v_mfma_f32_16x16x32_bf16 v[90:93], v[188:191], v[228:231], v[102:105]
	v_mfma_f32_16x16x32_bf16 v[220:223], v[192:195], v[232:235], v[90:93]
	v_mfma_f32_16x16x32_bf16 v[90:93], v[196:199], v[228:231], v[94:97]
	v_mfma_f32_16x16x32_bf16 v[224:227], v[200:203], v[232:235], v[90:93]
	s_setprio 0
	s_barrier
	s_mov_b32 m0, s19
	s_nop 3
	ds_read_b128 v[90:93], v252 offset:16384
	ds_read_b128 v[94:97], v252 offset:17408
	ds_read_b128 v[98:101], v252 offset:18432
	ds_read_b128 v[102:105], v252 offset:19456
	ds_read_b128 v[106:109], v252 offset:20480
	ds_read_b128 v[110:113], v252 offset:21504
	ds_read_b128 v[122:125], v252 offset:22528
	ds_read_b128 v[126:129], v252 offset:23552
	global_load_lds_dwordx4 v[156:157], off
	s_mov_b32 m0, s24
	s_nop 0
	global_load_lds_dwordx4 v[158:159], off
	s_mov_b32 m0, s18
	s_nop 0
	global_load_lds_dwordx4 v[160:161], off
	s_mov_b32 m0, s28
	s_nop 0
	global_load_lds_dwordx4 v[162:163], off
	s_mov_b32 m0, s22
	s_nop 0
	global_load_lds_dwordx4 v[164:165], off
	s_mov_b32 m0, s21
	s_nop 0
	global_load_lds_dwordx4 v[166:167], off
	s_waitcnt vmcnt(8)
	s_waitcnt lgkmcnt(0)
	s_barrier
	s_setprio 1
	v_mfma_f32_16x16x32_bf16 v[46:49], v[172:175], v[98:101], v[46:49]
	v_mfma_f32_16x16x32_bf16 v[30:33], v[172:175], v[106:109], v[30:33]
	v_mfma_f32_16x16x32_bf16 v[14:17], v[172:175], v[122:125], v[14:17]
	v_mfma_f32_16x16x32_bf16 v[78:81], v[172:175], v[90:93], v[78:81]
	v_mfma_f32_16x16x32_bf16 v[74:77], v[180:183], v[90:93], v[74:77]
	v_mfma_f32_16x16x32_bf16 v[46:49], v[176:179], v[102:105], v[46:49]
	v_mfma_f32_16x16x32_bf16 v[42:45], v[180:183], v[98:101], v[42:45]
	v_mfma_f32_16x16x32_bf16 v[30:33], v[176:179], v[110:113], v[30:33]
	v_mfma_f32_16x16x32_bf16 v[26:29], v[180:183], v[106:109], v[26:29]
	v_mfma_f32_16x16x32_bf16 v[14:17], v[176:179], v[126:129], v[14:17]
	v_mfma_f32_16x16x32_bf16 v[10:13], v[180:183], v[122:125], v[10:13]
	v_mfma_f32_16x16x32_bf16 v[156:159], v[176:179], v[94:97], v[78:81]
	v_mfma_f32_16x16x32_bf16 v[160:163], v[184:187], v[94:97], v[74:77]
	v_mfma_f32_16x16x32_bf16 v[164:167], v[184:187], v[102:105], v[42:45]
	v_mfma_f32_16x16x32_bf16 v[228:231], v[184:187], v[110:113], v[26:29]
	v_mfma_f32_16x16x32_bf16 v[172:175], v[184:187], v[126:129], v[10:13]
	v_mfma_f32_16x16x32_bf16 v[10:13], v[188:191], v[90:93], v[70:73]
	v_mfma_f32_16x16x32_bf16 v[176:179], v[192:195], v[94:97], v[10:13]
	v_mfma_f32_16x16x32_bf16 v[10:13], v[196:199], v[90:93], v[66:69]
	v_mfma_f32_16x16x32_bf16 v[180:183], v[200:203], v[94:97], v[10:13]
	v_mfma_f32_16x16x32_bf16 v[10:13], v[188:191], v[98:101], v[38:41]
	v_mfma_f32_16x16x32_bf16 v[38:41], v[192:195], v[102:105], v[10:13]
	v_mfma_f32_16x16x32_bf16 v[10:13], v[196:199], v[98:101], v[34:37]
	v_mfma_f32_16x16x32_bf16 v[184:187], v[200:203], v[102:105], v[10:13]
	v_mfma_f32_16x16x32_bf16 v[10:13], v[188:191], v[106:109], v[22:25]
	v_mfma_f32_16x16x32_bf16 v[6:9], v[188:191], v[122:125], v[6:9]
	v_mfma_f32_16x16x32_bf16 v[2:5], v[196:199], v[122:125], v[2:5]
	v_mfma_f32_16x16x32_bf16 v[22:25], v[192:195], v[110:113], v[10:13]
	v_mfma_f32_16x16x32_bf16 v[10:13], v[196:199], v[106:109], v[18:21]
	v_mfma_f32_16x16x32_bf16 v[6:9], v[192:195], v[126:129], v[6:9]
	v_mfma_f32_16x16x32_bf16 v[2:5], v[200:203], v[126:129], v[2:5]
	v_mfma_f32_16x16x32_bf16 v[232:235], v[200:203], v[110:113], v[10:13]
	s_setprio 0
	s_barrier
	s_nop 2
	ds_read_b128 v[10:13], v240
	ds_read_b128 v[18:21], v240 offset:1024
	ds_read_b128 v[34:37], v240 offset:2048
	ds_read_b128 v[188:191], v240 offset:3072
	ds_read_b128 v[192:195], v139
	ds_read_b128 v[196:199], v139 offset:1024
	ds_read_b128 v[200:203], v139 offset:2048
	ds_read_b128 v[240:243], v139 offset:3072
	s_mov_b32 m0, s17
	ds_read_b128 v[26:29], v252 offset:32768
	ds_read_b128 v[42:45], v252 offset:33792
	ds_read_b128 v[66:69], v252 offset:34816
	ds_read_b128 v[70:73], v252 offset:35840
	ds_read_b128 v[244:247], v252 offset:36864
	ds_read_b128 v[248:251], v252 offset:37888
	ds_read_b128 v[74:77], v252 offset:38912
	ds_read_b128 v[78:81], v252 offset:39936
	global_load_lds_dwordx4 v[152:153], off
	s_mov_b32 m0, s20
	s_nop 0
	global_load_lds_dwordx4 v[154:155], off
	s_waitcnt vmcnt(8)
	s_waitcnt lgkmcnt(0)
	s_barrier
	s_setprio 1
	v_mfma_f32_16x16x32_bf16 v[50:53], v[10:13], v[26:29], v[50:53]
	v_mfma_f32_16x16x32_bf16 v[122:125], v[18:21], v[42:45], v[50:53]
	v_mfma_f32_16x16x32_bf16 v[50:53], v[34:37], v[26:29], v[54:57]
	v_mfma_f32_16x16x32_bf16 v[126:129], v[188:191], v[42:45], v[50:53]
	v_mfma_f32_16x16x32_bf16 v[50:53], v[10:13], v[66:69], v[82:85]
	v_mfma_f32_16x16x32_bf16 v[106:109], v[18:21], v[70:73], v[50:53]
	v_mfma_f32_16x16x32_bf16 v[50:53], v[34:37], v[66:69], v[86:89]
	v_mfma_f32_16x16x32_bf16 v[110:113], v[188:191], v[70:73], v[50:53]
	v_mfma_f32_16x16x32_bf16 v[50:53], v[10:13], v[244:247], v[114:117]
	v_mfma_f32_16x16x32_bf16 v[90:93], v[18:21], v[248:251], v[50:53]
	v_mfma_f32_16x16x32_bf16 v[50:53], v[34:37], v[244:247], v[118:121]
	v_mfma_f32_16x16x32_bf16 v[94:97], v[188:191], v[248:251], v[50:53]
	v_mfma_f32_16x16x32_bf16 v[50:53], v[10:13], v[74:77], v[132:135]
	v_mfma_f32_16x16x32_bf16 v[152:155], v[18:21], v[78:81], v[50:53]
	v_mfma_f32_16x16x32_bf16 v[50:53], v[34:37], v[74:77], v[236:239]
	v_mfma_f32_16x16x32_bf16 v[236:239], v[188:191], v[78:81], v[50:53]
	v_mfma_f32_16x16x32_bf16 v[50:53], v[192:195], v[26:29], v[58:61]
	v_mfma_f32_16x16x32_bf16 v[26:29], v[200:203], v[26:29], v[62:65]
	v_mfma_f32_16x16x32_bf16 v[118:121], v[240:243], v[42:45], v[26:29]
	v_mfma_f32_16x16x32_bf16 v[26:29], v[192:195], v[66:69], v[204:207]
	v_mfma_f32_16x16x32_bf16 v[98:101], v[196:199], v[70:73], v[26:29]
	v_mfma_f32_16x16x32_bf16 v[26:29], v[200:203], v[66:69], v[208:211]
	v_mfma_f32_16x16x32_bf16 v[102:105], v[240:243], v[70:73], v[26:29]
	v_mfma_f32_16x16x32_bf16 v[26:29], v[192:195], v[244:247], v[212:215]
	v_mfma_f32_16x16x32_bf16 v[82:85], v[196:199], v[248:251], v[26:29]
	v_mfma_f32_16x16x32_bf16 v[26:29], v[200:203], v[244:247], v[216:219]
	v_mfma_f32_16x16x32_bf16 v[86:89], v[240:243], v[248:251], v[26:29]
	v_mfma_f32_16x16x32_bf16 v[26:29], v[192:195], v[74:77], v[220:223]
	v_mfma_f32_16x16x32_bf16 v[66:69], v[196:199], v[78:81], v[26:29]
	v_mfma_f32_16x16x32_bf16 v[26:29], v[200:203], v[74:77], v[224:227]
	v_mfma_f32_16x16x32_bf16 v[114:117], v[196:199], v[42:45], v[50:53]
	v_mfma_f32_16x16x32_bf16 v[70:73], v[240:243], v[78:81], v[26:29]
	s_setprio 0
	s_barrier
	s_mov_b32 m0, s11
	ds_read_b128 v[54:57], v252 offset:49152
	ds_read_b128 v[74:77], v252 offset:50176
	ds_read_b128 v[78:81], v252 offset:51200
	ds_read_b128 v[132:135], v252 offset:52224
	ds_read_b128 v[204:207], v252 offset:53248
	ds_read_b128 v[208:211], v252 offset:54272
	ds_read_b128 v[212:215], v252 offset:55296
	ds_read_b128 v[216:219], v252 offset:56320
	global_load_lds_dwordx4 v[142:143], off
	s_mov_b32 m0, s13
	s_nop 0
	global_load_lds_dwordx4 v[144:145], off
	s_mov_b32 m0, s15
	s_nop 0
	global_load_lds_dwordx4 v[148:149], off
	s_mov_b32 m0, s16
	s_nop 0
	global_load_lds_dwordx4 v[150:151], off
	s_mov_b32 m0, s12
	s_nop 0
	global_load_lds_dwordx4 v[130:131], off
	s_mov_b32 m0, s14
	s_nop 0
	global_load_lds_dwordx4 v[146:147], off
	s_waitcnt vmcnt(8)
	s_waitcnt lgkmcnt(0)
	s_barrier
	s_setprio 1
	v_mfma_f32_16x16x32_bf16 v[26:29], v[10:13], v[54:57], v[156:159]
	v_mfma_f32_16x16x32_bf16 v[58:61], v[18:21], v[74:77], v[26:29]
	v_mfma_f32_16x16x32_bf16 v[26:29], v[34:37], v[54:57], v[160:163]
	v_mfma_f32_16x16x32_bf16 v[62:65], v[188:191], v[74:77], v[26:29]
	v_mfma_f32_16x16x32_bf16 v[26:29], v[10:13], v[78:81], v[46:49]
	v_mfma_f32_16x16x32_bf16 v[42:45], v[18:21], v[132:135], v[26:29]
	v_mfma_f32_16x16x32_bf16 v[26:29], v[34:37], v[78:81], v[164:167]
	v_mfma_f32_16x16x32_bf16 v[46:49], v[188:191], v[132:135], v[26:29]
	v_mfma_f32_16x16x32_bf16 v[26:29], v[10:13], v[204:207], v[30:33]
	v_mfma_f32_16x16x32_bf16 v[30:33], v[34:37], v[204:207], v[228:231]
	v_mfma_f32_16x16x32_bf16 v[10:13], v[10:13], v[212:215], v[14:17]
	v_mfma_f32_16x16x32_bf16 v[14:17], v[34:37], v[212:215], v[172:175]
	v_mfma_f32_16x16x32_bf16 v[26:29], v[18:21], v[208:211], v[26:29]
	v_mfma_f32_16x16x32_bf16 v[30:33], v[188:191], v[208:211], v[30:33]
	v_mfma_f32_16x16x32_bf16 v[10:13], v[18:21], v[216:219], v[10:13]
	v_mfma_f32_16x16x32_bf16 v[14:17], v[188:191], v[216:219], v[14:17]
	v_mfma_f32_16x16x32_bf16 v[18:21], v[192:195], v[54:57], v[176:179]
	v_mfma_f32_16x16x32_bf16 v[50:53], v[196:199], v[74:77], v[18:21]
	v_mfma_f32_16x16x32_bf16 v[18:21], v[200:203], v[54:57], v[180:183]
	v_mfma_f32_16x16x32_bf16 v[54:57], v[240:243], v[74:77], v[18:21]
	v_mfma_f32_16x16x32_bf16 v[18:21], v[192:195], v[78:81], v[38:41]
	v_mfma_f32_16x16x32_bf16 v[34:37], v[196:199], v[132:135], v[18:21]
	v_mfma_f32_16x16x32_bf16 v[18:21], v[200:203], v[78:81], v[184:187]
	v_mfma_f32_16x16x32_bf16 v[38:41], v[240:243], v[132:135], v[18:21]
	v_mfma_f32_16x16x32_bf16 v[18:21], v[192:195], v[204:207], v[22:25]
	v_mfma_f32_16x16x32_bf16 v[22:25], v[200:203], v[204:207], v[232:235]
	v_mfma_f32_16x16x32_bf16 v[6:9], v[192:195], v[212:215], v[6:9]
	v_mfma_f32_16x16x32_bf16 v[2:5], v[200:203], v[212:215], v[2:5]
	v_mfma_f32_16x16x32_bf16 v[18:21], v[196:199], v[208:211], v[18:21]
	v_mfma_f32_16x16x32_bf16 v[22:25], v[240:243], v[208:211], v[22:25]
	v_mfma_f32_16x16x32_bf16 v[6:9], v[196:199], v[216:219], v[6:9]
	v_mfma_f32_16x16x32_bf16 v[2:5], v[240:243], v[216:219], v[2:5]
	s_setprio 0
	s_barrier
	s_cmpk_gt_u32 s8, 0xff
	s_cbranch_scc1 .LBB0_1694
	s_barrier

.LBB0_1786:
	v_add_u32_e32 v155, s48, v153
	ds_read_b128 v[156:159], v155
	ds_read_b128 v[160:163], v155 offset:1024
	ds_read_b128 v[164:167], v155 offset:2048
	ds_read_b128 v[168:171], v155 offset:3072
	v_add_u32_e32 v155, s49, v153
	s_add_u32 s28, s10, s38
	ds_read_b128 v[172:175], v155
	ds_read_b128 v[176:179], v155 offset:1024
	ds_read_b128 v[180:183], v155 offset:2048
	ds_read_b128 v[184:187], v155 offset:3072
	s_addc_u32 s29, s11, s39
	s_add_u32 s28, s28, 0x100
	s_addc_u32 s29, s29, 0
	s_add_u32 s54, s21, s38
	s_addc_u32 s55, s50, s39
	s_cmpk_eq_i32 s38, 0x700
	s_cselect_b32 s31, s17, s29
	s_cselect_b32 s30, s51, s28
	s_cselect_b32 s29, s15, s55
	s_cselect_b32 s28, s52, s54
	v_lshl_add_u64 v[220:221], v[148:149], 0, s[38:39]
	s_add_i32 m0, s1, 0xc000
	ds_read_b128 v[188:191], v154
	ds_read_b128 v[192:195], v154 offset:1024
	ds_read_b128 v[196:199], v154 offset:2048
	ds_read_b128 v[200:203], v154 offset:3072
	ds_read_b128 v[204:207], v154 offset:4096
	ds_read_b128 v[208:211], v154 offset:5120
	ds_read_b128 v[212:215], v154 offset:6144
	ds_read_b128 v[216:219], v154 offset:7168
	global_load_lds_dwordx4 v[220:221], off
	v_lshl_add_u64 v[220:221], v[150:151], 0, s[38:39]
	s_add_i32 m0, s1, 0xe000
	s_nop 0
	global_load_lds_dwordx4 v[220:221], off
	s_waitcnt vmcnt(8)
	s_waitcnt lgkmcnt(0)
	s_barrier
	s_setprio 1
	v_mfma_f32_16x16x32_bf16 v[126:129], v[156:159], v[188:191], v[126:129]
	v_mfma_f32_16x16x32_bf16 v[122:125], v[164:167], v[188:191], v[122:125]
	v_mfma_f32_16x16x32_bf16 v[110:113], v[156:159], v[196:199], v[110:113]
	v_mfma_f32_16x16x32_bf16 v[106:109], v[164:167], v[196:199], v[106:109]
	v_mfma_f32_16x16x32_bf16 v[94:97], v[156:159], v[204:207], v[94:97]
	v_mfma_f32_16x16x32_bf16 v[90:93], v[164:167], v[204:207], v[90:93]
	v_mfma_f32_16x16x32_bf16 v[78:81], v[156:159], v[212:215], v[78:81]
	v_mfma_f32_16x16x32_bf16 v[74:77], v[164:167], v[212:215], v[74:77]
	v_mfma_f32_16x16x32_bf16 v[126:129], v[160:163], v[192:195], v[126:129]
	v_mfma_f32_16x16x32_bf16 v[122:125], v[168:171], v[192:195], v[122:125]
	v_mfma_f32_16x16x32_bf16 v[110:113], v[160:163], v[200:203], v[110:113]
	v_mfma_f32_16x16x32_bf16 v[106:109], v[168:171], v[200:203], v[106:109]
	v_mfma_f32_16x16x32_bf16 v[94:97], v[160:163], v[208:211], v[94:97]
	v_mfma_f32_16x16x32_bf16 v[90:93], v[168:171], v[208:211], v[90:93]
	v_mfma_f32_16x16x32_bf16 v[78:81], v[160:163], v[216:219], v[78:81]
	v_mfma_f32_16x16x32_bf16 v[74:77], v[168:171], v[216:219], v[74:77]
	v_mfma_f32_16x16x32_bf16 v[118:121], v[172:175], v[188:191], v[118:121]
	v_mfma_f32_16x16x32_bf16 v[114:117], v[180:183], v[188:191], v[114:117]
	v_mfma_f32_16x16x32_bf16 v[102:105], v[172:175], v[196:199], v[102:105]
	v_mfma_f32_16x16x32_bf16 v[98:101], v[180:183], v[196:199], v[98:101]
	v_mfma_f32_16x16x32_bf16 v[86:89], v[172:175], v[204:207], v[86:89]
	v_mfma_f32_16x16x32_bf16 v[82:85], v[180:183], v[204:207], v[82:85]
	v_mfma_f32_16x16x32_bf16 v[70:73], v[172:175], v[212:215], v[70:73]
	v_mfma_f32_16x16x32_bf16 v[66:69], v[180:183], v[212:215], v[66:69]
	v_mfma_f32_16x16x32_bf16 v[118:121], v[176:179], v[192:195], v[118:121]
	v_mfma_f32_16x16x32_bf16 v[114:117], v[184:187], v[192:195], v[114:117]
	v_mfma_f32_16x16x32_bf16 v[102:105], v[176:179], v[200:203], v[102:105]
	v_mfma_f32_16x16x32_bf16 v[98:101], v[184:187], v[200:203], v[98:101]
	v_mfma_f32_16x16x32_bf16 v[86:89], v[176:179], v[208:211], v[86:89]
	v_mfma_f32_16x16x32_bf16 v[82:85], v[184:187], v[208:211], v[82:85]
	v_mfma_f32_16x16x32_bf16 v[70:73], v[176:179], v[216:219], v[70:73]
	v_mfma_f32_16x16x32_bf16 v[66:69], v[184:187], v[216:219], v[66:69]
	s_setprio 0
	s_barrier
	s_add_i32 s54, s48, s41
	s_mov_b32 m0, s54
	ds_read_b128 v[188:191], v154 offset:16384
	ds_read_b128 v[192:195], v154 offset:17408
	ds_read_b128 v[196:199], v154 offset:18432
	ds_read_b128 v[200:203], v154 offset:19456
	ds_read_b128 v[204:207], v154 offset:20480
	ds_read_b128 v[208:211], v154 offset:21504
	ds_read_b128 v[212:215], v154 offset:22528
	ds_read_b128 v[216:219], v154 offset:23552
	global_load_lds_dwordx4 v132, s[28:29]
	s_add_i32 m0, s54, 0x2000
	s_add_u32 s54, s28, 0x40000
	s_addc_u32 s55, s29, 0
	s_add_i32 s56, s49, s41
	global_load_lds_dwordx4 v136, s[28:29]
	s_mov_b32 m0, s56
	s_nop 0
	global_load_lds_dwordx4 v132, s[54:55]
	s_add_i32 m0, s56, 0x2000
	s_nop 0
	global_load_lds_dwordx4 v136, s[54:55]
	s_mov_b32 m0, s1
	s_nop 0
	global_load_lds_dwordx4 v130, s[30:31]
	s_mov_b32 m0, s42
	s_nop 0
	global_load_lds_dwordx4 v134, s[30:31]
	s_waitcnt vmcnt(8)
	s_waitcnt lgkmcnt(0)
	s_barrier
	s_setprio 1
	v_mfma_f32_16x16x32_bf16 v[62:65], v[156:159], v[188:191], v[62:65]
	v_mfma_f32_16x16x32_bf16 v[58:61], v[164:167], v[188:191], v[58:61]
	v_mfma_f32_16x16x32_bf16 v[46:49], v[156:159], v[196:199], v[46:49]
	v_mfma_f32_16x16x32_bf16 v[42:45], v[164:167], v[196:199], v[42:45]
	v_mfma_f32_16x16x32_bf16 v[30:33], v[156:159], v[204:207], v[30:33]
	v_mfma_f32_16x16x32_bf16 v[26:29], v[164:167], v[204:207], v[26:29]
	v_mfma_f32_16x16x32_bf16 v[14:17], v[156:159], v[212:215], v[14:17]
	v_mfma_f32_16x16x32_bf16 v[10:13], v[164:167], v[212:215], v[10:13]
	v_mfma_f32_16x16x32_bf16 v[62:65], v[160:163], v[192:195], v[62:65]
	v_mfma_f32_16x16x32_bf16 v[58:61], v[168:171], v[192:195], v[58:61]
	v_mfma_f32_16x16x32_bf16 v[46:49], v[160:163], v[200:203], v[46:49]
	v_mfma_f32_16x16x32_bf16 v[42:45], v[168:171], v[200:203], v[42:45]
	v_mfma_f32_16x16x32_bf16 v[30:33], v[160:163], v[208:211], v[30:33]
	v_mfma_f32_16x16x32_bf16 v[26:29], v[168:171], v[208:211], v[26:29]
	v_mfma_f32_16x16x32_bf16 v[14:17], v[160:163], v[216:219], v[14:17]
	v_mfma_f32_16x16x32_bf16 v[10:13], v[168:171], v[216:219], v[10:13]
	v_mfma_f32_16x16x32_bf16 v[54:57], v[172:175], v[188:191], v[54:57]
	v_mfma_f32_16x16x32_bf16 v[50:53], v[180:183], v[188:191], v[50:53]
	v_mfma_f32_16x16x32_bf16 v[38:41], v[172:175], v[196:199], v[38:41]
	v_mfma_f32_16x16x32_bf16 v[34:37], v[180:183], v[196:199], v[34:37]
	v_mfma_f32_16x16x32_bf16 v[22:25], v[172:175], v[204:207], v[22:25]
	v_mfma_f32_16x16x32_bf16 v[18:21], v[180:183], v[204:207], v[18:21]
	v_mfma_f32_16x16x32_bf16 v[6:9], v[172:175], v[212:215], v[6:9]
	v_mfma_f32_16x16x32_bf16 v[2:5], v[180:183], v[212:215], v[2:5]
	v_mfma_f32_16x16x32_bf16 v[54:57], v[176:179], v[192:195], v[54:57]
	v_mfma_f32_16x16x32_bf16 v[50:53], v[184:187], v[192:195], v[50:53]
	v_mfma_f32_16x16x32_bf16 v[38:41], v[176:179], v[200:203], v[38:41]
	v_mfma_f32_16x16x32_bf16 v[34:37], v[184:187], v[200:203], v[34:37]
	v_mfma_f32_16x16x32_bf16 v[22:25], v[176:179], v[208:211], v[22:25]
	v_mfma_f32_16x16x32_bf16 v[18:21], v[184:187], v[208:211], v[18:21]
	v_mfma_f32_16x16x32_bf16 v[6:9], v[176:179], v[216:219], v[6:9]
	v_mfma_f32_16x16x32_bf16 v[2:5], v[184:187], v[216:219], v[2:5]
	s_setprio 0
	s_barrier
	s_add_i32 s54, 0, 0x18000
	v_add_u32_e32 v155, s54, v153
	s_add_i32 s55, 0, 0x1c000
	ds_read_b128 v[156:159], v155
	ds_read_b128 v[160:163], v155 offset:1024
	ds_read_b128 v[164:167], v155 offset:2048
	ds_read_b128 v[168:171], v155 offset:3072
	v_add_u32_e32 v155, s55, v153
	ds_read_b128 v[172:175], v155
	ds_read_b128 v[176:179], v155 offset:1024
	ds_read_b128 v[180:183], v155 offset:2048
	ds_read_b128 v[184:187], v155 offset:3072
	s_add_u32 s98, s30, 0x40000
	s_addc_u32 s99, s31, 0
	s_mov_b32 m0, s43
	ds_read_b128 v[188:191], v154 offset:32768
	ds_read_b128 v[192:195], v154 offset:33792
	ds_read_b128 v[196:199], v154 offset:34816
	ds_read_b128 v[200:203], v154 offset:35840
	ds_read_b128 v[204:207], v154 offset:36864
	ds_read_b128 v[208:211], v154 offset:37888
	ds_read_b128 v[212:215], v154 offset:38912
	ds_read_b128 v[216:219], v154 offset:39936
	global_load_lds_dwordx4 v130, s[98:99]
	s_mov_b32 m0, s44
	s_nop 0
	global_load_lds_dwordx4 v134, s[98:99]
	s_waitcnt vmcnt(8)
	s_waitcnt lgkmcnt(0)
	s_barrier
	s_setprio 1
	v_mfma_f32_16x16x32_bf16 v[126:129], v[156:159], v[188:191], v[126:129]
	v_mfma_f32_16x16x32_bf16 v[122:125], v[164:167], v[188:191], v[122:125]
	v_mfma_f32_16x16x32_bf16 v[110:113], v[156:159], v[196:199], v[110:113]
	v_mfma_f32_16x16x32_bf16 v[106:109], v[164:167], v[196:199], v[106:109]
	v_mfma_f32_16x16x32_bf16 v[94:97], v[156:159], v[204:207], v[94:97]
	v_mfma_f32_16x16x32_bf16 v[90:93], v[164:167], v[204:207], v[90:93]
	v_mfma_f32_16x16x32_bf16 v[78:81], v[156:159], v[212:215], v[78:81]
	v_mfma_f32_16x16x32_bf16 v[74:77], v[164:167], v[212:215], v[74:77]
	v_mfma_f32_16x16x32_bf16 v[126:129], v[160:163], v[192:195], v[126:129]
	v_mfma_f32_16x16x32_bf16 v[122:125], v[168:171], v[192:195], v[122:125]
	v_mfma_f32_16x16x32_bf16 v[110:113], v[160:163], v[200:203], v[110:113]
	v_mfma_f32_16x16x32_bf16 v[106:109], v[168:171], v[200:203], v[106:109]
	v_mfma_f32_16x16x32_bf16 v[94:97], v[160:163], v[208:211], v[94:97]
	v_mfma_f32_16x16x32_bf16 v[90:93], v[168:171], v[208:211], v[90:93]
	v_mfma_f32_16x16x32_bf16 v[78:81], v[160:163], v[216:219], v[78:81]
	v_mfma_f32_16x16x32_bf16 v[74:77], v[168:171], v[216:219], v[74:77]
	v_mfma_f32_16x16x32_bf16 v[118:121], v[172:175], v[188:191], v[118:121]
	v_mfma_f32_16x16x32_bf16 v[114:117], v[180:183], v[188:191], v[114:117]
	v_mfma_f32_16x16x32_bf16 v[102:105], v[172:175], v[196:199], v[102:105]
	v_mfma_f32_16x16x32_bf16 v[98:101], v[180:183], v[196:199], v[98:101]
	v_mfma_f32_16x16x32_bf16 v[86:89], v[172:175], v[204:207], v[86:89]
	v_mfma_f32_16x16x32_bf16 v[82:85], v[180:183], v[204:207], v[82:85]
	v_mfma_f32_16x16x32_bf16 v[70:73], v[172:175], v[212:215], v[70:73]
	v_mfma_f32_16x16x32_bf16 v[66:69], v[180:183], v[212:215], v[66:69]
	v_mfma_f32_16x16x32_bf16 v[118:121], v[176:179], v[192:195], v[118:121]
	v_mfma_f32_16x16x32_bf16 v[114:117], v[184:187], v[192:195], v[114:117]
	v_mfma_f32_16x16x32_bf16 v[102:105], v[176:179], v[200:203], v[102:105]
	v_mfma_f32_16x16x32_bf16 v[98:101], v[184:187], v[200:203], v[98:101]
	v_mfma_f32_16x16x32_bf16 v[86:89], v[176:179], v[208:211], v[86:89]
	v_mfma_f32_16x16x32_bf16 v[82:85], v[184:187], v[208:211], v[82:85]
	v_mfma_f32_16x16x32_bf16 v[70:73], v[176:179], v[216:219], v[70:73]
	v_mfma_f32_16x16x32_bf16 v[66:69], v[184:187], v[216:219], v[66:69]
	s_setprio 0
	s_barrier
	s_add_i32 s98, s54, s41
	s_add_i32 m0, s98, 0xffffff80
	ds_read_b128 v[188:191], v154 offset:49152
	ds_read_b128 v[192:195], v154 offset:50176
	ds_read_b128 v[196:199], v154 offset:51200
	ds_read_b128 v[200:203], v154 offset:52224
	ds_read_b128 v[204:207], v154 offset:53248
	ds_read_b128 v[208:211], v154 offset:54272
	ds_read_b128 v[212:215], v154 offset:55296
	ds_read_b128 v[216:219], v154 offset:56320
	global_load_lds_dwordx4 v132, s[28:29] offset:128
	s_add_i32 m0, s98, 0x1f80
	s_add_i32 s98, s55, s41
	global_load_lds_dwordx4 v136, s[28:29] offset:128
	s_add_u32 s28, s28, 0x40080
	s_addc_u32 s29, s29, 0
	s_mov_b32 m0, s98
	s_nop 0
	global_load_lds_dwordx4 v132, s[28:29]
	s_add_i32 m0, s98, 0x2000
	s_nop 0
	global_load_lds_dwordx4 v136, s[28:29]
	s_add_i32 m0, s46, 0xffffff80
	s_nop 0
	global_load_lds_dwordx4 v130, s[30:31] offset:128
	s_add_i32 m0, s47, 0xffffff80
	s_nop 0
	global_load_lds_dwordx4 v134, s[30:31] offset:128
	s_waitcnt vmcnt(8)
	s_waitcnt lgkmcnt(0)
	s_barrier
	s_setprio 1
	v_mfma_f32_16x16x32_bf16 v[62:65], v[156:159], v[188:191], v[62:65]
	v_mfma_f32_16x16x32_bf16 v[58:61], v[164:167], v[188:191], v[58:61]
	v_mfma_f32_16x16x32_bf16 v[46:49], v[156:159], v[196:199], v[46:49]
	v_mfma_f32_16x16x32_bf16 v[42:45], v[164:167], v[196:199], v[42:45]
	v_mfma_f32_16x16x32_bf16 v[30:33], v[156:159], v[204:207], v[30:33]
	v_mfma_f32_16x16x32_bf16 v[26:29], v[164:167], v[204:207], v[26:29]
	v_mfma_f32_16x16x32_bf16 v[14:17], v[156:159], v[212:215], v[14:17]
	v_mfma_f32_16x16x32_bf16 v[10:13], v[164:167], v[212:215], v[10:13]
	v_mfma_f32_16x16x32_bf16 v[62:65], v[160:163], v[192:195], v[62:65]
	v_mfma_f32_16x16x32_bf16 v[58:61], v[168:171], v[192:195], v[58:61]
	v_mfma_f32_16x16x32_bf16 v[46:49], v[160:163], v[200:203], v[46:49]
	v_mfma_f32_16x16x32_bf16 v[42:45], v[168:171], v[200:203], v[42:45]
	v_mfma_f32_16x16x32_bf16 v[30:33], v[160:163], v[208:211], v[30:33]
	v_mfma_f32_16x16x32_bf16 v[26:29], v[168:171], v[208:211], v[26:29]
	v_mfma_f32_16x16x32_bf16 v[14:17], v[160:163], v[216:219], v[14:17]
	v_mfma_f32_16x16x32_bf16 v[10:13], v[168:171], v[216:219], v[10:13]
	v_mfma_f32_16x16x32_bf16 v[54:57], v[172:175], v[188:191], v[54:57]
	v_mfma_f32_16x16x32_bf16 v[50:53], v[180:183], v[188:191], v[50:53]
	v_mfma_f32_16x16x32_bf16 v[38:41], v[172:175], v[196:199], v[38:41]
	v_mfma_f32_16x16x32_bf16 v[34:37], v[180:183], v[196:199], v[34:37]
	v_mfma_f32_16x16x32_bf16 v[22:25], v[172:175], v[204:207], v[22:25]
	v_mfma_f32_16x16x32_bf16 v[18:21], v[180:183], v[204:207], v[18:21]
	v_mfma_f32_16x16x32_bf16 v[6:9], v[172:175], v[212:215], v[6:9]
	v_mfma_f32_16x16x32_bf16 v[2:5], v[180:183], v[212:215], v[2:5]
	v_mfma_f32_16x16x32_bf16 v[54:57], v[176:179], v[192:195], v[54:57]
	v_mfma_f32_16x16x32_bf16 v[50:53], v[184:187], v[192:195], v[50:53]
	v_mfma_f32_16x16x32_bf16 v[38:41], v[176:179], v[200:203], v[38:41]
	v_mfma_f32_16x16x32_bf16 v[34:37], v[184:187], v[200:203], v[34:37]
	v_mfma_f32_16x16x32_bf16 v[22:25], v[176:179], v[208:211], v[22:25]
	v_mfma_f32_16x16x32_bf16 v[18:21], v[184:187], v[208:211], v[18:21]
	v_mfma_f32_16x16x32_bf16 v[6:9], v[176:179], v[216:219], v[6:9]
	v_mfma_f32_16x16x32_bf16 v[2:5], v[184:187], v[216:219], v[2:5]
	s_setprio 0
	s_barrier
	s_add_i32 s53, s53, 2
	s_add_u32 s38, s38, 0x100
	s_addc_u32 s39, s39, 0
	s_cmp_gt_u32 s53, 13
	s_cbranch_scc0 .LBB0_1786
	s_add_u32 s28, s21, 0xffffff00
	s_addc_u32 s29, s50, -1
	s_andn2_b64 vcc, exec, s[4:5]
	s_cbranch_vccnz .LBB0_1789
	v_mov_b32_e32 v2, 0
	v_mov_b32_e32 v3, 0
	v_mov_b64_e32 v[4:5], v[2:3]
	v_mov_b64_e32 v[6:7], v[2:3]
	v_mov_b64_e32 v[8:9], v[2:3]
	v_mov_b64_e32 v[10:11], v[2:3]
	v_mov_b64_e32 v[12:13], v[2:3]
	v_mov_b64_e32 v[14:15], v[2:3]
	v_mov_b64_e32 v[16:17], v[2:3]
	v_mov_b64_e32 v[18:19], v[2:3]
	v_mov_b64_e32 v[20:21], v[2:3]
	v_mov_b64_e32 v[22:23], v[2:3]
	v_mov_b64_e32 v[24:25], v[2:3]
	v_mov_b64_e32 v[26:27], v[2:3]
	v_mov_b64_e32 v[28:29], v[2:3]
	v_mov_b64_e32 v[30:31], v[2:3]
	v_mov_b64_e32 v[32:33], v[2:3]
	v_mov_b64_e32 v[34:35], v[2:3]
	v_mov_b64_e32 v[36:37], v[2:3]
	v_mov_b64_e32 v[38:39], v[2:3]
	v_mov_b64_e32 v[40:41], v[2:3]
	v_mov_b64_e32 v[42:43], v[2:3]
	v_mov_b64_e32 v[44:45], v[2:3]
	v_mov_b64_e32 v[46:47], v[2:3]
	v_mov_b64_e32 v[48:49], v[2:3]
	v_mov_b64_e32 v[50:51], v[2:3]
	v_mov_b64_e32 v[52:53], v[2:3]
	v_mov_b64_e32 v[54:55], v[2:3]
	v_mov_b64_e32 v[56:57], v[2:3]
	v_mov_b64_e32 v[58:59], v[2:3]
	v_mov_b64_e32 v[60:61], v[2:3]
	v_mov_b64_e32 v[62:63], v[2:3]
	v_mov_b64_e32 v[64:65], v[2:3]
	v_mov_b64_e32 v[66:67], v[2:3]
	v_mov_b64_e32 v[68:69], v[2:3]
	v_mov_b64_e32 v[70:71], v[2:3]
	v_mov_b64_e32 v[72:73], v[2:3]
	v_mov_b64_e32 v[74:75], v[2:3]
	v_mov_b64_e32 v[76:77], v[2:3]
	v_mov_b64_e32 v[78:79], v[2:3]
	v_mov_b64_e32 v[80:81], v[2:3]
	v_mov_b64_e32 v[82:83], v[2:3]
	v_mov_b64_e32 v[84:85], v[2:3]
	v_mov_b64_e32 v[86:87], v[2:3]
	v_mov_b64_e32 v[88:89], v[2:3]
	v_mov_b64_e32 v[90:91], v[2:3]
	v_mov_b64_e32 v[92:93], v[2:3]
	v_mov_b64_e32 v[94:95], v[2:3]
	v_mov_b64_e32 v[96:97], v[2:3]
	v_mov_b64_e32 v[98:99], v[2:3]
	v_mov_b64_e32 v[100:101], v[2:3]
	v_mov_b64_e32 v[102:103], v[2:3]
	v_mov_b64_e32 v[104:105], v[2:3]
	v_mov_b64_e32 v[106:107], v[2:3]
	v_mov_b64_e32 v[108:109], v[2:3]
	v_mov_b64_e32 v[110:111], v[2:3]
	v_mov_b64_e32 v[112:113], v[2:3]
	v_mov_b64_e32 v[114:115], v[2:3]
	v_mov_b64_e32 v[116:117], v[2:3]
	v_mov_b64_e32 v[118:119], v[2:3]
	v_mov_b64_e32 v[120:121], v[2:3]
	v_mov_b64_e32 v[122:123], v[2:3]
	v_mov_b64_e32 v[124:125], v[2:3]
	v_mov_b64_e32 v[126:127], v[2:3]
	v_mov_b64_e32 v[128:129], v[2:3]
	s_mov_b32 s6, s14
	s_mov_b32 s0, s16
	s_mov_b64 s[10:11], s[36:37]
	s_mov_b32 s45, s20
	s_andn2_b64 vcc, exec, s[2:3]
	s_cbranch_vccnz .LBB0_1790
	s_branch .LBB0_1791

.LBB0_1905:
	ds_read_b128 v[148:151], v165
	ds_read_b128 v[152:155], v165 offset:1024
	ds_read_b128 v[156:159], v165 offset:2048
	ds_read_b128 v[160:163], v165 offset:3072
	ds_read_b128 v[170:173], v166
	ds_read_b128 v[174:177], v166 offset:1024
	ds_read_b128 v[178:181], v166 offset:2048
	ds_read_b128 v[182:185], v166 offset:3072
	s_add_u32 s28, s58, 0xfffc0080
	s_addc_u32 s29, s59, -1
	s_cmp_eq_u32 s74, 12
	s_cselect_b32 s31, s51, s29
	s_cselect_b32 s30, s60, s28
	s_cselect_b32 s29, s49, s73
	s_cselect_b32 s28, s61, s72
	s_add_i32 m0, s33, 0xc000
	ds_read_b128 v[186:189], v167
	ds_read_b128 v[190:193], v167 offset:1024
	ds_read_b128 v[194:197], v167 offset:2048
	ds_read_b128 v[198:201], v167 offset:3072
	ds_read_b128 v[202:205], v167 offset:4096
	ds_read_b128 v[206:209], v167 offset:5120
	ds_read_b128 v[210:213], v167 offset:6144
	ds_read_b128 v[214:217], v167 offset:7168
	global_load_lds_dwordx4 v140, s[58:59]
	s_add_i32 m0, s33, 0xe000
	s_nop 0
	global_load_lds_dwordx4 v142, s[58:59]
	s_waitcnt vmcnt(8)
	s_waitcnt lgkmcnt(0)
	s_barrier
	s_setprio 1
	v_mfma_f32_16x16x32_bf16 v[126:129], v[148:151], v[186:189], v[126:129]
	v_mfma_f32_16x16x32_bf16 v[118:121], v[156:159], v[186:189], v[118:121]
	v_mfma_f32_16x16x32_bf16 v[110:113], v[148:151], v[194:197], v[110:113]
	v_mfma_f32_16x16x32_bf16 v[102:105], v[156:159], v[194:197], v[102:105]
	v_mfma_f32_16x16x32_bf16 v[94:97], v[148:151], v[202:205], v[94:97]
	v_mfma_f32_16x16x32_bf16 v[86:89], v[156:159], v[202:205], v[86:89]
	v_mfma_f32_16x16x32_bf16 v[78:81], v[148:151], v[210:213], v[78:81]
	v_mfma_f32_16x16x32_bf16 v[70:73], v[156:159], v[210:213], v[70:73]
	v_mfma_f32_16x16x32_bf16 v[126:129], v[152:155], v[190:193], v[126:129]
	v_mfma_f32_16x16x32_bf16 v[118:121], v[160:163], v[190:193], v[118:121]
	v_mfma_f32_16x16x32_bf16 v[110:113], v[152:155], v[198:201], v[110:113]
	v_mfma_f32_16x16x32_bf16 v[102:105], v[160:163], v[198:201], v[102:105]
	v_mfma_f32_16x16x32_bf16 v[94:97], v[152:155], v[206:209], v[94:97]
	v_mfma_f32_16x16x32_bf16 v[86:89], v[160:163], v[206:209], v[86:89]
	v_mfma_f32_16x16x32_bf16 v[78:81], v[152:155], v[214:217], v[78:81]
	v_mfma_f32_16x16x32_bf16 v[70:73], v[160:163], v[214:217], v[70:73]
	v_mfma_f32_16x16x32_bf16 v[122:125], v[170:173], v[186:189], v[122:125]
	v_mfma_f32_16x16x32_bf16 v[114:117], v[178:181], v[186:189], v[114:117]
	v_mfma_f32_16x16x32_bf16 v[106:109], v[170:173], v[194:197], v[106:109]
	v_mfma_f32_16x16x32_bf16 v[98:101], v[178:181], v[194:197], v[98:101]
	v_mfma_f32_16x16x32_bf16 v[90:93], v[170:173], v[202:205], v[90:93]
	v_mfma_f32_16x16x32_bf16 v[82:85], v[178:181], v[202:205], v[82:85]
	v_mfma_f32_16x16x32_bf16 v[74:77], v[170:173], v[210:213], v[74:77]
	v_mfma_f32_16x16x32_bf16 v[66:69], v[178:181], v[210:213], v[66:69]
	v_mfma_f32_16x16x32_bf16 v[122:125], v[174:177], v[190:193], v[122:125]
	v_mfma_f32_16x16x32_bf16 v[114:117], v[182:185], v[190:193], v[114:117]
	v_mfma_f32_16x16x32_bf16 v[106:109], v[174:177], v[198:201], v[106:109]
	v_mfma_f32_16x16x32_bf16 v[98:101], v[182:185], v[198:201], v[98:101]
	v_mfma_f32_16x16x32_bf16 v[90:93], v[174:177], v[206:209], v[90:93]
	v_mfma_f32_16x16x32_bf16 v[82:85], v[182:185], v[206:209], v[82:85]
	v_mfma_f32_16x16x32_bf16 v[74:77], v[174:177], v[214:217], v[74:77]
	v_mfma_f32_16x16x32_bf16 v[66:69], v[182:185], v[214:217], v[66:69]
	s_setprio 0
	s_barrier
	s_add_i32 s75, s67, s23
	s_mov_b32 m0, s75
	ds_read_b128 v[186:189], v167 offset:16384
	ds_read_b128 v[190:193], v167 offset:17408
	ds_read_b128 v[194:197], v167 offset:18432
	ds_read_b128 v[198:201], v167 offset:19456
	ds_read_b128 v[202:205], v167 offset:20480
	ds_read_b128 v[206:209], v167 offset:21504
	ds_read_b128 v[210:213], v167 offset:22528
	ds_read_b128 v[214:217], v167 offset:23552
	global_load_lds_dwordx4 v132, s[28:29]
	s_add_i32 m0, s75, 0x2000
	s_add_u32 s76, s28, 0x40000
	s_addc_u32 s77, s29, 0
	s_add_i32 s75, s68, s23
	global_load_lds_dwordx4 v136, s[28:29]
	s_mov_b32 m0, s75
	s_nop 0
	global_load_lds_dwordx4 v132, s[76:77]
	s_add_i32 m0, s75, 0x2000
	s_nop 0
	global_load_lds_dwordx4 v136, s[76:77]
	s_mov_b32 m0, s33
	s_nop 0
	global_load_lds_dwordx4 v130, s[30:31]
	s_mov_b32 m0, s34
	s_nop 0
	global_load_lds_dwordx4 v134, s[30:31]
	s_waitcnt vmcnt(8)
	s_waitcnt lgkmcnt(0)
	s_barrier
	s_setprio 1
	v_mfma_f32_16x16x32_bf16 v[62:65], v[148:151], v[186:189], v[62:65]
	v_mfma_f32_16x16x32_bf16 v[54:57], v[156:159], v[186:189], v[54:57]
	v_mfma_f32_16x16x32_bf16 v[46:49], v[148:151], v[194:197], v[46:49]
	v_mfma_f32_16x16x32_bf16 v[38:41], v[156:159], v[194:197], v[38:41]
	v_mfma_f32_16x16x32_bf16 v[30:33], v[148:151], v[202:205], v[30:33]
	v_mfma_f32_16x16x32_bf16 v[22:25], v[156:159], v[202:205], v[22:25]
	v_mfma_f32_16x16x32_bf16 v[14:17], v[148:151], v[210:213], v[14:17]
	v_mfma_f32_16x16x32_bf16 v[6:9], v[156:159], v[210:213], v[6:9]
	v_mfma_f32_16x16x32_bf16 v[62:65], v[152:155], v[190:193], v[62:65]
	v_mfma_f32_16x16x32_bf16 v[54:57], v[160:163], v[190:193], v[54:57]
	v_mfma_f32_16x16x32_bf16 v[46:49], v[152:155], v[198:201], v[46:49]
	v_mfma_f32_16x16x32_bf16 v[38:41], v[160:163], v[198:201], v[38:41]
	v_mfma_f32_16x16x32_bf16 v[30:33], v[152:155], v[206:209], v[30:33]
	v_mfma_f32_16x16x32_bf16 v[22:25], v[160:163], v[206:209], v[22:25]
	v_mfma_f32_16x16x32_bf16 v[14:17], v[152:155], v[214:217], v[14:17]
	v_mfma_f32_16x16x32_bf16 v[6:9], v[160:163], v[214:217], v[6:9]
	v_mfma_f32_16x16x32_bf16 v[58:61], v[170:173], v[186:189], v[58:61]
	v_mfma_f32_16x16x32_bf16 v[50:53], v[178:181], v[186:189], v[50:53]
	v_mfma_f32_16x16x32_bf16 v[42:45], v[170:173], v[194:197], v[42:45]
	v_mfma_f32_16x16x32_bf16 v[34:37], v[178:181], v[194:197], v[34:37]
	v_mfma_f32_16x16x32_bf16 v[26:29], v[170:173], v[202:205], v[26:29]
	v_mfma_f32_16x16x32_bf16 v[18:21], v[178:181], v[202:205], v[18:21]
	v_mfma_f32_16x16x32_bf16 v[10:13], v[170:173], v[210:213], v[10:13]
	v_mfma_f32_16x16x32_bf16 v[2:5], v[178:181], v[210:213], v[2:5]
	v_mfma_f32_16x16x32_bf16 v[58:61], v[174:177], v[190:193], v[58:61]
	v_mfma_f32_16x16x32_bf16 v[50:53], v[182:185], v[190:193], v[50:53]
	v_mfma_f32_16x16x32_bf16 v[42:45], v[174:177], v[198:201], v[42:45]
	v_mfma_f32_16x16x32_bf16 v[34:37], v[182:185], v[198:201], v[34:37]
	v_mfma_f32_16x16x32_bf16 v[26:29], v[174:177], v[206:209], v[26:29]
	v_mfma_f32_16x16x32_bf16 v[18:21], v[182:185], v[206:209], v[18:21]
	v_mfma_f32_16x16x32_bf16 v[10:13], v[174:177], v[214:217], v[10:13]
	v_mfma_f32_16x16x32_bf16 v[2:5], v[182:185], v[214:217], v[2:5]
	s_setprio 0
	s_barrier
	s_add_i32 s75, 0, 0x18000
	s_add_i32 s76, 0, 0x1c000
	v_add_u32_e32 v160, s75, v139
	v_add_u32_e32 v169, s76, v139
	ds_read_b128 v[148:151], v160
	ds_read_b128 v[152:155], v160 offset:1024
	ds_read_b128 v[156:159], v160 offset:2048
	ds_read_b128 v[160:163], v160 offset:3072
	ds_read_b128 v[170:173], v169
	ds_read_b128 v[174:177], v169 offset:1024
	ds_read_b128 v[178:181], v169 offset:2048
	ds_read_b128 v[182:185], v169 offset:3072
	s_add_u32 s98, s30, 0x40000
	s_addc_u32 s99, s31, 0
	s_mov_b32 m0, s35
	ds_read_b128 v[186:189], v167 offset:32768
	ds_read_b128 v[190:193], v167 offset:33792
	ds_read_b128 v[194:197], v167 offset:34816
	ds_read_b128 v[198:201], v167 offset:35840
	ds_read_b128 v[202:205], v167 offset:36864
	ds_read_b128 v[206:209], v167 offset:37888
	ds_read_b128 v[210:213], v167 offset:38912
	ds_read_b128 v[214:217], v167 offset:39936
	global_load_lds_dwordx4 v130, s[98:99]
	s_mov_b32 m0, s57
	s_nop 0
	global_load_lds_dwordx4 v134, s[98:99]
	s_waitcnt vmcnt(8)
	s_waitcnt lgkmcnt(0)
	s_barrier
	s_setprio 1
	v_mfma_f32_16x16x32_bf16 v[126:129], v[148:151], v[186:189], v[126:129]
	v_mfma_f32_16x16x32_bf16 v[118:121], v[156:159], v[186:189], v[118:121]
	v_mfma_f32_16x16x32_bf16 v[110:113], v[148:151], v[194:197], v[110:113]
	v_mfma_f32_16x16x32_bf16 v[102:105], v[156:159], v[194:197], v[102:105]
	v_mfma_f32_16x16x32_bf16 v[94:97], v[148:151], v[202:205], v[94:97]
	v_mfma_f32_16x16x32_bf16 v[86:89], v[156:159], v[202:205], v[86:89]
	v_mfma_f32_16x16x32_bf16 v[78:81], v[148:151], v[210:213], v[78:81]
	v_mfma_f32_16x16x32_bf16 v[70:73], v[156:159], v[210:213], v[70:73]
	v_mfma_f32_16x16x32_bf16 v[126:129], v[152:155], v[190:193], v[126:129]
	v_mfma_f32_16x16x32_bf16 v[118:121], v[160:163], v[190:193], v[118:121]
	v_mfma_f32_16x16x32_bf16 v[110:113], v[152:155], v[198:201], v[110:113]
	v_mfma_f32_16x16x32_bf16 v[102:105], v[160:163], v[198:201], v[102:105]
	v_mfma_f32_16x16x32_bf16 v[94:97], v[152:155], v[206:209], v[94:97]
	v_mfma_f32_16x16x32_bf16 v[86:89], v[160:163], v[206:209], v[86:89]
	v_mfma_f32_16x16x32_bf16 v[78:81], v[152:155], v[214:217], v[78:81]
	v_mfma_f32_16x16x32_bf16 v[70:73], v[160:163], v[214:217], v[70:73]
	v_mfma_f32_16x16x32_bf16 v[122:125], v[170:173], v[186:189], v[122:125]
	v_mfma_f32_16x16x32_bf16 v[114:117], v[178:181], v[186:189], v[114:117]
	v_mfma_f32_16x16x32_bf16 v[106:109], v[170:173], v[194:197], v[106:109]
	v_mfma_f32_16x16x32_bf16 v[98:101], v[178:181], v[194:197], v[98:101]
	v_mfma_f32_16x16x32_bf16 v[90:93], v[170:173], v[202:205], v[90:93]
	v_mfma_f32_16x16x32_bf16 v[82:85], v[178:181], v[202:205], v[82:85]
	v_mfma_f32_16x16x32_bf16 v[74:77], v[170:173], v[210:213], v[74:77]
	v_mfma_f32_16x16x32_bf16 v[66:69], v[178:181], v[210:213], v[66:69]
	v_mfma_f32_16x16x32_bf16 v[122:125], v[174:177], v[190:193], v[122:125]
	v_mfma_f32_16x16x32_bf16 v[114:117], v[182:185], v[190:193], v[114:117]
	v_mfma_f32_16x16x32_bf16 v[106:109], v[174:177], v[198:201], v[106:109]
	v_mfma_f32_16x16x32_bf16 v[98:101], v[182:185], v[198:201], v[98:101]
	v_mfma_f32_16x16x32_bf16 v[90:93], v[174:177], v[206:209], v[90:93]
	v_mfma_f32_16x16x32_bf16 v[82:85], v[182:185], v[206:209], v[82:85]
	v_mfma_f32_16x16x32_bf16 v[74:77], v[174:177], v[214:217], v[74:77]
	v_mfma_f32_16x16x32_bf16 v[66:69], v[182:185], v[214:217], v[66:69]
	s_setprio 0
	s_barrier
	s_add_i32 s98, s75, s23
	s_add_i32 m0, s98, 0xffffff80
	ds_read_b128 v[186:189], v167 offset:49152
	ds_read_b128 v[190:193], v167 offset:50176
	ds_read_b128 v[194:197], v167 offset:51200
	ds_read_b128 v[198:201], v167 offset:52224
	ds_read_b128 v[202:205], v167 offset:53248
	ds_read_b128 v[206:209], v167 offset:54272
	ds_read_b128 v[210:213], v167 offset:55296
	ds_read_b128 v[214:217], v167 offset:56320
	global_load_lds_dwordx4 v132, s[28:29] offset:128
	s_add_i32 m0, s98, 0x1f80
	s_add_i32 s98, s76, s23
	global_load_lds_dwordx4 v136, s[28:29] offset:128
	s_add_u32 s28, s28, 0x40080
	s_addc_u32 s29, s29, 0
	s_mov_b32 m0, s98
	s_nop 0
	global_load_lds_dwordx4 v132, s[28:29]
	s_add_i32 m0, s98, 0x2000
	s_nop 0
	global_load_lds_dwordx4 v136, s[28:29]
	s_add_i32 m0, s62, 0xffffff80
	s_nop 0
	global_load_lds_dwordx4 v130, s[30:31] offset:128
	s_add_i32 m0, s63, 0xffffff80
	s_nop 0
	global_load_lds_dwordx4 v134, s[30:31] offset:128
	s_waitcnt vmcnt(8)
	s_waitcnt lgkmcnt(0)
	s_barrier
	s_setprio 1
	v_mfma_f32_16x16x32_bf16 v[62:65], v[148:151], v[186:189], v[62:65]
	v_mfma_f32_16x16x32_bf16 v[54:57], v[156:159], v[186:189], v[54:57]
	v_mfma_f32_16x16x32_bf16 v[46:49], v[148:151], v[194:197], v[46:49]
	v_mfma_f32_16x16x32_bf16 v[38:41], v[156:159], v[194:197], v[38:41]
	v_mfma_f32_16x16x32_bf16 v[30:33], v[148:151], v[202:205], v[30:33]
	v_mfma_f32_16x16x32_bf16 v[22:25], v[156:159], v[202:205], v[22:25]
	v_mfma_f32_16x16x32_bf16 v[14:17], v[148:151], v[210:213], v[14:17]
	v_mfma_f32_16x16x32_bf16 v[6:9], v[156:159], v[210:213], v[6:9]
	v_mfma_f32_16x16x32_bf16 v[62:65], v[152:155], v[190:193], v[62:65]
	v_mfma_f32_16x16x32_bf16 v[54:57], v[160:163], v[190:193], v[54:57]
	v_mfma_f32_16x16x32_bf16 v[46:49], v[152:155], v[198:201], v[46:49]
	v_mfma_f32_16x16x32_bf16 v[38:41], v[160:163], v[198:201], v[38:41]
	v_mfma_f32_16x16x32_bf16 v[30:33], v[152:155], v[206:209], v[30:33]
	v_mfma_f32_16x16x32_bf16 v[22:25], v[160:163], v[206:209], v[22:25]
	v_mfma_f32_16x16x32_bf16 v[14:17], v[152:155], v[214:217], v[14:17]
	v_mfma_f32_16x16x32_bf16 v[6:9], v[160:163], v[214:217], v[6:9]
	v_mfma_f32_16x16x32_bf16 v[58:61], v[170:173], v[186:189], v[58:61]
	v_mfma_f32_16x16x32_bf16 v[50:53], v[178:181], v[186:189], v[50:53]
	v_mfma_f32_16x16x32_bf16 v[42:45], v[170:173], v[194:197], v[42:45]
	v_mfma_f32_16x16x32_bf16 v[34:37], v[178:181], v[194:197], v[34:37]
	v_mfma_f32_16x16x32_bf16 v[26:29], v[170:173], v[202:205], v[26:29]
	v_mfma_f32_16x16x32_bf16 v[18:21], v[178:181], v[202:205], v[18:21]
	v_mfma_f32_16x16x32_bf16 v[10:13], v[170:173], v[210:213], v[10:13]
	v_mfma_f32_16x16x32_bf16 v[2:5], v[178:181], v[210:213], v[2:5]
	v_mfma_f32_16x16x32_bf16 v[58:61], v[174:177], v[190:193], v[58:61]
	v_mfma_f32_16x16x32_bf16 v[50:53], v[182:185], v[190:193], v[50:53]
	v_mfma_f32_16x16x32_bf16 v[42:45], v[174:177], v[198:201], v[42:45]
	v_mfma_f32_16x16x32_bf16 v[34:37], v[182:185], v[198:201], v[34:37]
	v_mfma_f32_16x16x32_bf16 v[26:29], v[174:177], v[206:209], v[26:29]
	v_mfma_f32_16x16x32_bf16 v[18:21], v[182:185], v[206:209], v[18:21]
	v_mfma_f32_16x16x32_bf16 v[10:13], v[174:177], v[214:217], v[10:13]
	v_mfma_f32_16x16x32_bf16 v[2:5], v[182:185], v[214:217], v[2:5]
	s_setprio 0
	s_barrier
	s_add_i32 s74, s74, 2
	s_add_u32 s58, s58, 0x100
	s_addc_u32 s59, s59, 0
	s_add_u32 s72, s72, 0x100
	s_addc_u32 s73, s73, 0
	s_cmp_gt_u32 s74, 13
	s_cbranch_scc0 .LBB0_1905
	s_and_b64 vcc, exec, s[42:43]
	s_cbranch_vccz .LBB0_1908
	s_barrier

.LBB0_2031:
	v_add_u32_e32 v155, s48, v153
	ds_read_b128 v[156:159], v155
	ds_read_b128 v[160:163], v155 offset:1024
	ds_read_b128 v[164:167], v155 offset:2048
	ds_read_b128 v[168:171], v155 offset:3072
	v_add_u32_e32 v155, s49, v153
	s_add_u32 s28, s12, s20
	ds_read_b128 v[172:175], v155
	ds_read_b128 v[176:179], v155 offset:1024
	ds_read_b128 v[180:183], v155 offset:2048
	ds_read_b128 v[184:187], v155 offset:3072
	s_addc_u32 s29, s13, s21
	s_add_u32 s28, s28, 0x100
	s_addc_u32 s29, s29, 0
	s_add_u32 s54, s17, s20
	s_addc_u32 s55, s52, s21
	s_cmpk_eq_i32 s20, 0x1500
	s_cselect_b32 s31, s19, s29
	s_cselect_b32 s30, s18, s28
	s_cselect_b32 s29, s1, s55
	s_cselect_b32 s28, s0, s54
	v_lshl_add_u64 v[220:221], v[148:149], 0, s[20:21]
	s_add_i32 m0, s41, 0xc000
	ds_read_b128 v[188:191], v154
	ds_read_b128 v[192:195], v154 offset:1024
	ds_read_b128 v[196:199], v154 offset:2048
	ds_read_b128 v[200:203], v154 offset:3072
	ds_read_b128 v[204:207], v154 offset:4096
	ds_read_b128 v[208:211], v154 offset:5120
	ds_read_b128 v[212:215], v154 offset:6144
	ds_read_b128 v[216:219], v154 offset:7168
	global_load_lds_dwordx4 v[220:221], off
	v_lshl_add_u64 v[220:221], v[150:151], 0, s[20:21]
	s_add_i32 m0, s41, 0xe000
	s_nop 0
	global_load_lds_dwordx4 v[220:221], off
	s_waitcnt vmcnt(8)
	s_waitcnt lgkmcnt(0)
	s_barrier
	s_setprio 1
	v_mfma_f32_16x16x32_bf16 v[126:129], v[156:159], v[188:191], v[126:129]
	v_mfma_f32_16x16x32_bf16 v[122:125], v[164:167], v[188:191], v[122:125]
	v_mfma_f32_16x16x32_bf16 v[110:113], v[156:159], v[196:199], v[110:113]
	v_mfma_f32_16x16x32_bf16 v[106:109], v[164:167], v[196:199], v[106:109]
	v_mfma_f32_16x16x32_bf16 v[94:97], v[156:159], v[204:207], v[94:97]
	v_mfma_f32_16x16x32_bf16 v[90:93], v[164:167], v[204:207], v[90:93]
	v_mfma_f32_16x16x32_bf16 v[78:81], v[156:159], v[212:215], v[78:81]
	v_mfma_f32_16x16x32_bf16 v[74:77], v[164:167], v[212:215], v[74:77]
	v_mfma_f32_16x16x32_bf16 v[126:129], v[160:163], v[192:195], v[126:129]
	v_mfma_f32_16x16x32_bf16 v[122:125], v[168:171], v[192:195], v[122:125]
	v_mfma_f32_16x16x32_bf16 v[110:113], v[160:163], v[200:203], v[110:113]
	v_mfma_f32_16x16x32_bf16 v[106:109], v[168:171], v[200:203], v[106:109]
	v_mfma_f32_16x16x32_bf16 v[94:97], v[160:163], v[208:211], v[94:97]
	v_mfma_f32_16x16x32_bf16 v[90:93], v[168:171], v[208:211], v[90:93]
	v_mfma_f32_16x16x32_bf16 v[78:81], v[160:163], v[216:219], v[78:81]
	v_mfma_f32_16x16x32_bf16 v[74:77], v[168:171], v[216:219], v[74:77]
	v_mfma_f32_16x16x32_bf16 v[118:121], v[172:175], v[188:191], v[118:121]
	v_mfma_f32_16x16x32_bf16 v[114:117], v[180:183], v[188:191], v[114:117]
	v_mfma_f32_16x16x32_bf16 v[102:105], v[172:175], v[196:199], v[102:105]
	v_mfma_f32_16x16x32_bf16 v[98:101], v[180:183], v[196:199], v[98:101]
	v_mfma_f32_16x16x32_bf16 v[86:89], v[172:175], v[204:207], v[86:89]
	v_mfma_f32_16x16x32_bf16 v[82:85], v[180:183], v[204:207], v[82:85]
	v_mfma_f32_16x16x32_bf16 v[70:73], v[172:175], v[212:215], v[70:73]
	v_mfma_f32_16x16x32_bf16 v[66:69], v[180:183], v[212:215], v[66:69]
	v_mfma_f32_16x16x32_bf16 v[118:121], v[176:179], v[192:195], v[118:121]
	v_mfma_f32_16x16x32_bf16 v[114:117], v[184:187], v[192:195], v[114:117]
	v_mfma_f32_16x16x32_bf16 v[102:105], v[176:179], v[200:203], v[102:105]
	v_mfma_f32_16x16x32_bf16 v[98:101], v[184:187], v[200:203], v[98:101]
	v_mfma_f32_16x16x32_bf16 v[86:89], v[176:179], v[208:211], v[86:89]
	v_mfma_f32_16x16x32_bf16 v[82:85], v[184:187], v[208:211], v[82:85]
	v_mfma_f32_16x16x32_bf16 v[70:73], v[176:179], v[216:219], v[70:73]
	v_mfma_f32_16x16x32_bf16 v[66:69], v[184:187], v[216:219], v[66:69]
	s_setprio 0
	s_barrier
	s_add_i32 s54, s48, s35
	s_mov_b32 m0, s54
	ds_read_b128 v[188:191], v154 offset:16384
	ds_read_b128 v[192:195], v154 offset:17408
	ds_read_b128 v[196:199], v154 offset:18432
	ds_read_b128 v[200:203], v154 offset:19456
	ds_read_b128 v[204:207], v154 offset:20480
	ds_read_b128 v[208:211], v154 offset:21504
	ds_read_b128 v[212:215], v154 offset:22528
	ds_read_b128 v[216:219], v154 offset:23552
	global_load_lds_dwordx4 v132, s[28:29]
	s_add_i32 m0, s54, 0x2000
	s_add_u32 s54, s28, 0xb0000
	s_addc_u32 s55, s29, 0
	s_add_i32 s56, s49, s35
	global_load_lds_dwordx4 v136, s[28:29]
	s_mov_b32 m0, s56
	s_nop 0
	global_load_lds_dwordx4 v132, s[54:55]
	s_add_i32 m0, s56, 0x2000
	s_nop 0
	global_load_lds_dwordx4 v136, s[54:55]
	s_mov_b32 m0, s41
	s_nop 0
	global_load_lds_dwordx4 v130, s[30:31]
	s_mov_b32 m0, s42
	s_nop 0
	global_load_lds_dwordx4 v134, s[30:31]
	s_waitcnt vmcnt(8)
	s_waitcnt lgkmcnt(0)
	s_barrier
	s_setprio 1
	v_mfma_f32_16x16x32_bf16 v[62:65], v[156:159], v[188:191], v[62:65]
	v_mfma_f32_16x16x32_bf16 v[58:61], v[164:167], v[188:191], v[58:61]
	v_mfma_f32_16x16x32_bf16 v[46:49], v[156:159], v[196:199], v[46:49]
	v_mfma_f32_16x16x32_bf16 v[42:45], v[164:167], v[196:199], v[42:45]
	v_mfma_f32_16x16x32_bf16 v[30:33], v[156:159], v[204:207], v[30:33]
	v_mfma_f32_16x16x32_bf16 v[26:29], v[164:167], v[204:207], v[26:29]
	v_mfma_f32_16x16x32_bf16 v[14:17], v[156:159], v[212:215], v[14:17]
	v_mfma_f32_16x16x32_bf16 v[10:13], v[164:167], v[212:215], v[10:13]
	v_mfma_f32_16x16x32_bf16 v[62:65], v[160:163], v[192:195], v[62:65]
	v_mfma_f32_16x16x32_bf16 v[58:61], v[168:171], v[192:195], v[58:61]
	v_mfma_f32_16x16x32_bf16 v[46:49], v[160:163], v[200:203], v[46:49]
	v_mfma_f32_16x16x32_bf16 v[42:45], v[168:171], v[200:203], v[42:45]
	v_mfma_f32_16x16x32_bf16 v[30:33], v[160:163], v[208:211], v[30:33]
	v_mfma_f32_16x16x32_bf16 v[26:29], v[168:171], v[208:211], v[26:29]
	v_mfma_f32_16x16x32_bf16 v[14:17], v[160:163], v[216:219], v[14:17]
	v_mfma_f32_16x16x32_bf16 v[10:13], v[168:171], v[216:219], v[10:13]
	v_mfma_f32_16x16x32_bf16 v[54:57], v[172:175], v[188:191], v[54:57]
	v_mfma_f32_16x16x32_bf16 v[50:53], v[180:183], v[188:191], v[50:53]
	v_mfma_f32_16x16x32_bf16 v[38:41], v[172:175], v[196:199], v[38:41]
	v_mfma_f32_16x16x32_bf16 v[34:37], v[180:183], v[196:199], v[34:37]
	v_mfma_f32_16x16x32_bf16 v[22:25], v[172:175], v[204:207], v[22:25]
	v_mfma_f32_16x16x32_bf16 v[18:21], v[180:183], v[204:207], v[18:21]
	v_mfma_f32_16x16x32_bf16 v[6:9], v[172:175], v[212:215], v[6:9]
	v_mfma_f32_16x16x32_bf16 v[2:5], v[180:183], v[212:215], v[2:5]
	v_mfma_f32_16x16x32_bf16 v[54:57], v[176:179], v[192:195], v[54:57]
	v_mfma_f32_16x16x32_bf16 v[50:53], v[184:187], v[192:195], v[50:53]
	v_mfma_f32_16x16x32_bf16 v[38:41], v[176:179], v[200:203], v[38:41]
	v_mfma_f32_16x16x32_bf16 v[34:37], v[184:187], v[200:203], v[34:37]
	v_mfma_f32_16x16x32_bf16 v[22:25], v[176:179], v[208:211], v[22:25]
	v_mfma_f32_16x16x32_bf16 v[18:21], v[184:187], v[208:211], v[18:21]
	v_mfma_f32_16x16x32_bf16 v[6:9], v[176:179], v[216:219], v[6:9]
	v_mfma_f32_16x16x32_bf16 v[2:5], v[184:187], v[216:219], v[2:5]
	s_setprio 0
	s_barrier
	s_add_i32 s54, 0, 0x18000
	v_add_u32_e32 v155, s54, v153
	s_add_i32 s55, 0, 0x1c000
	ds_read_b128 v[156:159], v155
	ds_read_b128 v[160:163], v155 offset:1024
	ds_read_b128 v[164:167], v155 offset:2048
	ds_read_b128 v[168:171], v155 offset:3072
	v_add_u32_e32 v155, s55, v153
	ds_read_b128 v[172:175], v155
	ds_read_b128 v[176:179], v155 offset:1024
	ds_read_b128 v[180:183], v155 offset:2048
	ds_read_b128 v[184:187], v155 offset:3072
	s_add_u32 s98, s30, 0xb0000
	s_addc_u32 s99, s31, 0
	s_mov_b32 m0, s43
	ds_read_b128 v[188:191], v154 offset:32768
	ds_read_b128 v[192:195], v154 offset:33792
	ds_read_b128 v[196:199], v154 offset:34816
	ds_read_b128 v[200:203], v154 offset:35840
	ds_read_b128 v[204:207], v154 offset:36864
	ds_read_b128 v[208:211], v154 offset:37888
	ds_read_b128 v[212:215], v154 offset:38912
	ds_read_b128 v[216:219], v154 offset:39936
	global_load_lds_dwordx4 v130, s[98:99]
	s_mov_b32 m0, s44
	s_nop 0
	global_load_lds_dwordx4 v134, s[98:99]
	s_waitcnt vmcnt(8)
	s_waitcnt lgkmcnt(0)
	s_barrier
	s_setprio 1
	v_mfma_f32_16x16x32_bf16 v[126:129], v[156:159], v[188:191], v[126:129]
	v_mfma_f32_16x16x32_bf16 v[122:125], v[164:167], v[188:191], v[122:125]
	v_mfma_f32_16x16x32_bf16 v[110:113], v[156:159], v[196:199], v[110:113]
	v_mfma_f32_16x16x32_bf16 v[106:109], v[164:167], v[196:199], v[106:109]
	v_mfma_f32_16x16x32_bf16 v[94:97], v[156:159], v[204:207], v[94:97]
	v_mfma_f32_16x16x32_bf16 v[90:93], v[164:167], v[204:207], v[90:93]
	v_mfma_f32_16x16x32_bf16 v[78:81], v[156:159], v[212:215], v[78:81]
	v_mfma_f32_16x16x32_bf16 v[74:77], v[164:167], v[212:215], v[74:77]
	v_mfma_f32_16x16x32_bf16 v[126:129], v[160:163], v[192:195], v[126:129]
	v_mfma_f32_16x16x32_bf16 v[122:125], v[168:171], v[192:195], v[122:125]
	v_mfma_f32_16x16x32_bf16 v[110:113], v[160:163], v[200:203], v[110:113]
	v_mfma_f32_16x16x32_bf16 v[106:109], v[168:171], v[200:203], v[106:109]
	v_mfma_f32_16x16x32_bf16 v[94:97], v[160:163], v[208:211], v[94:97]
	v_mfma_f32_16x16x32_bf16 v[90:93], v[168:171], v[208:211], v[90:93]
	v_mfma_f32_16x16x32_bf16 v[78:81], v[160:163], v[216:219], v[78:81]
	v_mfma_f32_16x16x32_bf16 v[74:77], v[168:171], v[216:219], v[74:77]
	v_mfma_f32_16x16x32_bf16 v[118:121], v[172:175], v[188:191], v[118:121]
	v_mfma_f32_16x16x32_bf16 v[114:117], v[180:183], v[188:191], v[114:117]
	v_mfma_f32_16x16x32_bf16 v[102:105], v[172:175], v[196:199], v[102:105]
	v_mfma_f32_16x16x32_bf16 v[98:101], v[180:183], v[196:199], v[98:101]
	v_mfma_f32_16x16x32_bf16 v[86:89], v[172:175], v[204:207], v[86:89]
	v_mfma_f32_16x16x32_bf16 v[82:85], v[180:183], v[204:207], v[82:85]
	v_mfma_f32_16x16x32_bf16 v[70:73], v[172:175], v[212:215], v[70:73]
	v_mfma_f32_16x16x32_bf16 v[66:69], v[180:183], v[212:215], v[66:69]
	v_mfma_f32_16x16x32_bf16 v[118:121], v[176:179], v[192:195], v[118:121]
	v_mfma_f32_16x16x32_bf16 v[114:117], v[184:187], v[192:195], v[114:117]
	v_mfma_f32_16x16x32_bf16 v[102:105], v[176:179], v[200:203], v[102:105]
	v_mfma_f32_16x16x32_bf16 v[98:101], v[184:187], v[200:203], v[98:101]
	v_mfma_f32_16x16x32_bf16 v[86:89], v[176:179], v[208:211], v[86:89]
	v_mfma_f32_16x16x32_bf16 v[82:85], v[184:187], v[208:211], v[82:85]
	v_mfma_f32_16x16x32_bf16 v[70:73], v[176:179], v[216:219], v[70:73]
	v_mfma_f32_16x16x32_bf16 v[66:69], v[184:187], v[216:219], v[66:69]
	s_setprio 0
	s_barrier
	s_add_i32 s98, s54, s35
	s_add_i32 m0, s98, 0xffffff80
	ds_read_b128 v[188:191], v154 offset:49152
	ds_read_b128 v[192:195], v154 offset:50176
	ds_read_b128 v[196:199], v154 offset:51200
	ds_read_b128 v[200:203], v154 offset:52224
	ds_read_b128 v[204:207], v154 offset:53248
	ds_read_b128 v[208:211], v154 offset:54272
	ds_read_b128 v[212:215], v154 offset:55296
	ds_read_b128 v[216:219], v154 offset:56320
	global_load_lds_dwordx4 v132, s[28:29] offset:128
	s_add_i32 m0, s98, 0x1f80
	s_add_i32 s98, s55, s35
	global_load_lds_dwordx4 v136, s[28:29] offset:128
	s_add_u32 s28, s28, 0xb0080
	s_addc_u32 s29, s29, 0
	s_mov_b32 m0, s98
	s_nop 0
	global_load_lds_dwordx4 v132, s[28:29]
	s_add_i32 m0, s98, 0x2000
	s_nop 0
	global_load_lds_dwordx4 v136, s[28:29]
	s_add_i32 m0, s46, 0xffffff80
	s_nop 0
	global_load_lds_dwordx4 v130, s[30:31] offset:128
	s_add_i32 m0, s47, 0xffffff80
	s_nop 0
	global_load_lds_dwordx4 v134, s[30:31] offset:128
	s_waitcnt vmcnt(8)
	s_waitcnt lgkmcnt(0)
	s_barrier
	s_setprio 1
	v_mfma_f32_16x16x32_bf16 v[62:65], v[156:159], v[188:191], v[62:65]
	v_mfma_f32_16x16x32_bf16 v[58:61], v[164:167], v[188:191], v[58:61]
	v_mfma_f32_16x16x32_bf16 v[46:49], v[156:159], v[196:199], v[46:49]
	v_mfma_f32_16x16x32_bf16 v[42:45], v[164:167], v[196:199], v[42:45]
	v_mfma_f32_16x16x32_bf16 v[30:33], v[156:159], v[204:207], v[30:33]
	v_mfma_f32_16x16x32_bf16 v[26:29], v[164:167], v[204:207], v[26:29]
	v_mfma_f32_16x16x32_bf16 v[14:17], v[156:159], v[212:215], v[14:17]
	v_mfma_f32_16x16x32_bf16 v[10:13], v[164:167], v[212:215], v[10:13]
	v_mfma_f32_16x16x32_bf16 v[62:65], v[160:163], v[192:195], v[62:65]
	v_mfma_f32_16x16x32_bf16 v[58:61], v[168:171], v[192:195], v[58:61]
	v_mfma_f32_16x16x32_bf16 v[46:49], v[160:163], v[200:203], v[46:49]
	v_mfma_f32_16x16x32_bf16 v[42:45], v[168:171], v[200:203], v[42:45]
	v_mfma_f32_16x16x32_bf16 v[30:33], v[160:163], v[208:211], v[30:33]
	v_mfma_f32_16x16x32_bf16 v[26:29], v[168:171], v[208:211], v[26:29]
	v_mfma_f32_16x16x32_bf16 v[14:17], v[160:163], v[216:219], v[14:17]
	v_mfma_f32_16x16x32_bf16 v[10:13], v[168:171], v[216:219], v[10:13]
	v_mfma_f32_16x16x32_bf16 v[54:57], v[172:175], v[188:191], v[54:57]
	v_mfma_f32_16x16x32_bf16 v[50:53], v[180:183], v[188:191], v[50:53]
	v_mfma_f32_16x16x32_bf16 v[38:41], v[172:175], v[196:199], v[38:41]
	v_mfma_f32_16x16x32_bf16 v[34:37], v[180:183], v[196:199], v[34:37]
	v_mfma_f32_16x16x32_bf16 v[22:25], v[172:175], v[204:207], v[22:25]
	v_mfma_f32_16x16x32_bf16 v[18:21], v[180:183], v[204:207], v[18:21]
	v_mfma_f32_16x16x32_bf16 v[6:9], v[172:175], v[212:215], v[6:9]
	v_mfma_f32_16x16x32_bf16 v[2:5], v[180:183], v[212:215], v[2:5]
	v_mfma_f32_16x16x32_bf16 v[54:57], v[176:179], v[192:195], v[54:57]
	v_mfma_f32_16x16x32_bf16 v[50:53], v[184:187], v[192:195], v[50:53]
	v_mfma_f32_16x16x32_bf16 v[38:41], v[176:179], v[200:203], v[38:41]
	v_mfma_f32_16x16x32_bf16 v[34:37], v[184:187], v[200:203], v[34:37]
	v_mfma_f32_16x16x32_bf16 v[22:25], v[176:179], v[208:211], v[22:25]
	v_mfma_f32_16x16x32_bf16 v[18:21], v[184:187], v[208:211], v[18:21]
	v_mfma_f32_16x16x32_bf16 v[6:9], v[176:179], v[216:219], v[6:9]
	v_mfma_f32_16x16x32_bf16 v[2:5], v[184:187], v[216:219], v[2:5]
	s_setprio 0
	s_barrier
	s_add_i32 s53, s53, 2
	s_add_u32 s20, s20, 0x100
	s_addc_u32 s21, s21, 0
	s_cmp_gt_u32 s53, 41
	s_cbranch_scc0 .LBB0_2031
	s_add_u32 s20, s17, 0xffffff00
	s_addc_u32 s21, s52, -1
	s_and_b64 vcc, exec, s[4:5]
	s_cbranch_vccnz .LBB0_2034
	v_mov_b32_e32 v2, 0
	v_mov_b32_e32 v3, 0
	v_mov_b64_e32 v[4:5], v[2:3]
	v_mov_b64_e32 v[6:7], v[2:3]
	v_mov_b64_e32 v[8:9], v[2:3]
	v_mov_b64_e32 v[10:11], v[2:3]
	v_mov_b64_e32 v[12:13], v[2:3]
	v_mov_b64_e32 v[14:15], v[2:3]
	v_mov_b64_e32 v[16:17], v[2:3]
	v_mov_b64_e32 v[18:19], v[2:3]
	v_mov_b64_e32 v[20:21], v[2:3]
	v_mov_b64_e32 v[22:23], v[2:3]
	v_mov_b64_e32 v[24:25], v[2:3]
	v_mov_b64_e32 v[26:27], v[2:3]
	v_mov_b64_e32 v[28:29], v[2:3]
	v_mov_b64_e32 v[30:31], v[2:3]
	v_mov_b64_e32 v[32:33], v[2:3]
	v_mov_b64_e32 v[34:35], v[2:3]
	v_mov_b64_e32 v[36:37], v[2:3]
	v_mov_b64_e32 v[38:39], v[2:3]
	v_mov_b64_e32 v[40:41], v[2:3]
	v_mov_b64_e32 v[42:43], v[2:3]
	v_mov_b64_e32 v[44:45], v[2:3]
	v_mov_b64_e32 v[46:47], v[2:3]
	v_mov_b64_e32 v[48:49], v[2:3]
	v_mov_b64_e32 v[50:51], v[2:3]
	v_mov_b64_e32 v[52:53], v[2:3]
	v_mov_b64_e32 v[54:55], v[2:3]
	v_mov_b64_e32 v[56:57], v[2:3]
	v_mov_b64_e32 v[58:59], v[2:3]
	v_mov_b64_e32 v[60:61], v[2:3]
	v_mov_b64_e32 v[62:63], v[2:3]
	v_mov_b64_e32 v[64:65], v[2:3]
	v_mov_b64_e32 v[66:67], v[2:3]
	v_mov_b64_e32 v[68:69], v[2:3]
	v_mov_b64_e32 v[70:71], v[2:3]
	v_mov_b64_e32 v[72:73], v[2:3]
	v_mov_b64_e32 v[74:75], v[2:3]
	v_mov_b64_e32 v[76:77], v[2:3]
	v_mov_b64_e32 v[78:79], v[2:3]
	v_mov_b64_e32 v[80:81], v[2:3]
	v_mov_b64_e32 v[82:83], v[2:3]
	v_mov_b64_e32 v[84:85], v[2:3]
	v_mov_b64_e32 v[86:87], v[2:3]
	v_mov_b64_e32 v[88:89], v[2:3]
	v_mov_b64_e32 v[90:91], v[2:3]
	v_mov_b64_e32 v[92:93], v[2:3]
	v_mov_b64_e32 v[94:95], v[2:3]
	v_mov_b64_e32 v[96:97], v[2:3]
	v_mov_b64_e32 v[98:99], v[2:3]
	v_mov_b64_e32 v[100:101], v[2:3]
	v_mov_b64_e32 v[102:103], v[2:3]
	v_mov_b64_e32 v[104:105], v[2:3]
	v_mov_b64_e32 v[106:107], v[2:3]
	v_mov_b64_e32 v[108:109], v[2:3]
	v_mov_b64_e32 v[110:111], v[2:3]
	v_mov_b64_e32 v[112:113], v[2:3]
	v_mov_b64_e32 v[114:115], v[2:3]
	v_mov_b64_e32 v[116:117], v[2:3]
	v_mov_b64_e32 v[118:119], v[2:3]
	v_mov_b64_e32 v[120:121], v[2:3]
	v_mov_b64_e32 v[122:123], v[2:3]
	v_mov_b64_e32 v[124:125], v[2:3]
	v_mov_b64_e32 v[126:127], v[2:3]
	v_mov_b64_e32 v[128:129], v[2:3]
	s_mov_b32 s10, s50
	s_mov_b32 s23, s51
	s_mov_b64 s[12:13], s[18:19]
	s_mov_b32 s45, s16
	s_andn2_b64 vcc, exec, s[2:3]
	s_cbranch_vccnz .LBB0_2035
	s_branch .LBB0_2036

.LBB0_2133:
	ds_read_b128 v[154:157], v148
	ds_read_b128 v[158:161], v148 offset:1024
	ds_read_b128 v[162:165], v148 offset:2048
	ds_read_b128 v[166:169], v148 offset:3072
	ds_read_b128 v[170:173], v149
	ds_read_b128 v[174:177], v149 offset:1024
	ds_read_b128 v[178:181], v149 offset:2048
	ds_read_b128 v[182:185], v149 offset:3072
	s_add_u32 s28, s20, 0xfa94fc80
	s_addc_u32 s29, s21, -1
	s_cmp_lg_u32 s46, 32
	s_cselect_b32 s28, s28, 0
	s_cselect_b32 s29, s29, 0
	s_add_u32 s30, s4, s28
	s_addc_u32 s31, s5, s29
	s_add_u32 s28, s2, s28
	s_addc_u32 s29, s3, s29
	s_mov_b32 m0, s47
	v_lshl_add_u64 v[218:219], v[144:145], 0, s[20:21]
	ds_read_b128 v[186:189], v150
	ds_read_b128 v[190:193], v150 offset:1024
	ds_read_b128 v[194:197], v150 offset:2048
	ds_read_b128 v[198:201], v150 offset:3072
	ds_read_b128 v[202:205], v150 offset:4096
	ds_read_b128 v[206:209], v150 offset:5120
	ds_read_b128 v[210:213], v150 offset:6144
	ds_read_b128 v[214:217], v150 offset:7168
	global_load_lds_dwordx4 v[218:219], off
	v_lshl_add_u64 v[218:219], v[146:147], 0, s[20:21]
	s_mov_b32 m0, s48
	s_nop 0
	global_load_lds_dwordx4 v[218:219], off
	s_waitcnt vmcnt(8)
	s_waitcnt lgkmcnt(0)
	s_barrier
	s_setprio 1
	v_mfma_f32_16x16x32_bf16 v[58:61], v[154:157], v[186:189], v[58:61]
	v_mfma_f32_16x16x32_bf16 v[70:73], v[162:165], v[186:189], v[70:73]
	v_mfma_f32_16x16x32_bf16 v[42:45], v[154:157], v[194:197], v[42:45]
	v_mfma_f32_16x16x32_bf16 v[50:53], v[162:165], v[194:197], v[50:53]
	v_mfma_f32_16x16x32_bf16 v[34:37], v[154:157], v[202:205], v[34:37]
	v_mfma_f32_16x16x32_bf16 v[38:41], v[162:165], v[202:205], v[38:41]
	v_mfma_f32_16x16x32_bf16 v[26:29], v[154:157], v[210:213], v[26:29]
	v_mfma_f32_16x16x32_bf16 v[30:33], v[162:165], v[210:213], v[30:33]
	v_mfma_f32_16x16x32_bf16 v[58:61], v[158:161], v[190:193], v[58:61]
	v_mfma_f32_16x16x32_bf16 v[70:73], v[166:169], v[190:193], v[70:73]
	v_mfma_f32_16x16x32_bf16 v[42:45], v[158:161], v[198:201], v[42:45]
	v_mfma_f32_16x16x32_bf16 v[50:53], v[166:169], v[198:201], v[50:53]
	v_mfma_f32_16x16x32_bf16 v[34:37], v[158:161], v[206:209], v[34:37]
	v_mfma_f32_16x16x32_bf16 v[38:41], v[166:169], v[206:209], v[38:41]
	v_mfma_f32_16x16x32_bf16 v[26:29], v[158:161], v[214:217], v[26:29]
	v_mfma_f32_16x16x32_bf16 v[30:33], v[166:169], v[214:217], v[30:33]
	v_mfma_f32_16x16x32_bf16 v[106:109], v[170:173], v[186:189], v[106:109]
	v_mfma_f32_16x16x32_bf16 v[110:113], v[178:181], v[186:189], v[110:113]
	v_mfma_f32_16x16x32_bf16 v[98:101], v[170:173], v[194:197], v[98:101]
	v_mfma_f32_16x16x32_bf16 v[102:105], v[178:181], v[194:197], v[102:105]
	v_mfma_f32_16x16x32_bf16 v[90:93], v[170:173], v[202:205], v[90:93]
	v_mfma_f32_16x16x32_bf16 v[94:97], v[178:181], v[202:205], v[94:97]
	v_mfma_f32_16x16x32_bf16 v[82:85], v[170:173], v[210:213], v[82:85]
	v_mfma_f32_16x16x32_bf16 v[86:89], v[178:181], v[210:213], v[86:89]
	v_mfma_f32_16x16x32_bf16 v[106:109], v[174:177], v[190:193], v[106:109]
	v_mfma_f32_16x16x32_bf16 v[110:113], v[182:185], v[190:193], v[110:113]
	v_mfma_f32_16x16x32_bf16 v[98:101], v[174:177], v[198:201], v[98:101]
	v_mfma_f32_16x16x32_bf16 v[102:105], v[182:185], v[198:201], v[102:105]
	v_mfma_f32_16x16x32_bf16 v[90:93], v[174:177], v[206:209], v[90:93]
	v_mfma_f32_16x16x32_bf16 v[94:97], v[182:185], v[206:209], v[94:97]
	v_mfma_f32_16x16x32_bf16 v[82:85], v[174:177], v[214:217], v[82:85]
	v_mfma_f32_16x16x32_bf16 v[86:89], v[182:185], v[214:217], v[86:89]
	s_setprio 0
	s_barrier
	s_mov_b32 m0, s49
	s_add_u32 s58, s28, 0xb0000
	ds_read_b128 v[186:189], v150 offset:16384
	ds_read_b128 v[190:193], v150 offset:17408
	ds_read_b128 v[194:197], v150 offset:18432
	ds_read_b128 v[198:201], v150 offset:19456
	ds_read_b128 v[202:205], v150 offset:20480
	ds_read_b128 v[206:209], v150 offset:21504
	ds_read_b128 v[210:213], v150 offset:22528
	ds_read_b128 v[214:217], v150 offset:23552
	global_load_lds_dwordx4 v116, s[28:29]
	s_mov_b32 m0, s50
	s_addc_u32 s59, s29, 0
	global_load_lds_dwordx4 v124, s[28:29]
	s_mov_b32 m0, s51
	s_nop 0
	global_load_lds_dwordx4 v116, s[58:59]
	s_mov_b32 m0, s52
	s_nop 0
	global_load_lds_dwordx4 v124, s[58:59]
	s_mov_b32 m0, s25
	s_nop 0
	global_load_lds_dwordx4 v114, s[30:31]
	s_mov_b32 m0, s35
	s_nop 0
	global_load_lds_dwordx4 v122, s[30:31]
	s_waitcnt vmcnt(8)
	s_waitcnt lgkmcnt(0)
	s_barrier
	s_setprio 1
	v_mfma_f32_16x16x32_bf16 v[18:21], v[154:157], v[186:189], v[18:21]
	v_mfma_f32_16x16x32_bf16 v[22:25], v[162:165], v[186:189], v[22:25]
	v_mfma_f32_16x16x32_bf16 v[10:13], v[154:157], v[194:197], v[10:13]
	v_mfma_f32_16x16x32_bf16 v[14:17], v[162:165], v[194:197], v[14:17]
	v_mfma_f32_16x16x32_bf16 v[2:5], v[154:157], v[202:205], v[2:5]
	v_mfma_f32_16x16x32_bf16 v[6:9], v[162:165], v[202:205], v[6:9]
	v_mfma_f32_16x16x32_bf16 v[62:65], v[154:157], v[210:213], v[62:65]
	v_mfma_f32_16x16x32_bf16 v[74:77], v[162:165], v[210:213], v[74:77]
	v_mfma_f32_16x16x32_bf16 v[18:21], v[158:161], v[190:193], v[18:21]
	v_mfma_f32_16x16x32_bf16 v[22:25], v[166:169], v[190:193], v[22:25]
	v_mfma_f32_16x16x32_bf16 v[10:13], v[158:161], v[198:201], v[10:13]
	v_mfma_f32_16x16x32_bf16 v[14:17], v[166:169], v[198:201], v[14:17]
	v_mfma_f32_16x16x32_bf16 v[2:5], v[158:161], v[206:209], v[2:5]
	v_mfma_f32_16x16x32_bf16 v[6:9], v[166:169], v[206:209], v[6:9]
	v_mfma_f32_16x16x32_bf16 v[62:65], v[158:161], v[214:217], v[62:65]
	v_mfma_f32_16x16x32_bf16 v[74:77], v[166:169], v[214:217], v[74:77]
	v_mfma_f32_16x16x32_bf16 v[66:69], v[170:173], v[186:189], v[66:69]
	v_mfma_f32_16x16x32_bf16 v[78:81], v[178:181], v[186:189], v[78:81]
	v_mfma_f32_16x16x32_bf16 v[46:49], v[170:173], v[194:197], v[46:49]
	v_mfma_f32_16x16x32_bf16 v[54:57], v[178:181], v[194:197], v[54:57]
	v_mfma_f32_16x16x32_bf16 v[118:121], v[170:173], v[202:205], v[118:121]
	v_mfma_f32_16x16x32_bf16 v[126:129], v[178:181], v[202:205], v[126:129]
	v_mfma_f32_16x16x32_bf16 v[130:133], v[170:173], v[210:213], v[130:133]
	v_mfma_f32_16x16x32_bf16 v[134:137], v[178:181], v[210:213], v[134:137]
	v_mfma_f32_16x16x32_bf16 v[66:69], v[174:177], v[190:193], v[66:69]
	v_mfma_f32_16x16x32_bf16 v[78:81], v[182:185], v[190:193], v[78:81]
	v_mfma_f32_16x16x32_bf16 v[46:49], v[174:177], v[198:201], v[46:49]
	v_mfma_f32_16x16x32_bf16 v[54:57], v[182:185], v[198:201], v[54:57]
	v_mfma_f32_16x16x32_bf16 v[118:121], v[174:177], v[206:209], v[118:121]
	v_mfma_f32_16x16x32_bf16 v[126:129], v[182:185], v[206:209], v[126:129]
	v_mfma_f32_16x16x32_bf16 v[130:133], v[174:177], v[214:217], v[130:133]
	v_mfma_f32_16x16x32_bf16 v[134:137], v[182:185], v[214:217], v[134:137]
	s_setprio 0
	s_barrier
	ds_read_b128 v[154:157], v151
	ds_read_b128 v[158:161], v151 offset:1024
	ds_read_b128 v[162:165], v151 offset:2048
	ds_read_b128 v[166:169], v151 offset:3072
	ds_read_b128 v[170:173], v152
	ds_read_b128 v[174:177], v152 offset:1024
	ds_read_b128 v[178:181], v152 offset:2048
	ds_read_b128 v[182:185], v152 offset:3072
	s_add_u32 s98, s30, 0xb0000
	s_addc_u32 s99, s31, 0
	s_mov_b32 m0, s42
	ds_read_b128 v[186:189], v150 offset:32768
	ds_read_b128 v[190:193], v150 offset:33792
	ds_read_b128 v[194:197], v150 offset:34816
	ds_read_b128 v[198:201], v150 offset:35840
	ds_read_b128 v[202:205], v150 offset:36864
	ds_read_b128 v[206:209], v150 offset:37888
	ds_read_b128 v[210:213], v150 offset:38912
	ds_read_b128 v[214:217], v150 offset:39936
	global_load_lds_dwordx4 v114, s[98:99]
	s_mov_b32 m0, s43
	s_nop 0
	global_load_lds_dwordx4 v122, s[98:99]
	s_waitcnt vmcnt(8)
	s_waitcnt lgkmcnt(0)
	s_barrier
	s_setprio 1
	v_mfma_f32_16x16x32_bf16 v[58:61], v[154:157], v[186:189], v[58:61]
	v_mfma_f32_16x16x32_bf16 v[70:73], v[162:165], v[186:189], v[70:73]
	v_mfma_f32_16x16x32_bf16 v[42:45], v[154:157], v[194:197], v[42:45]
	v_mfma_f32_16x16x32_bf16 v[50:53], v[162:165], v[194:197], v[50:53]
	v_mfma_f32_16x16x32_bf16 v[34:37], v[154:157], v[202:205], v[34:37]
	v_mfma_f32_16x16x32_bf16 v[38:41], v[162:165], v[202:205], v[38:41]
	v_mfma_f32_16x16x32_bf16 v[26:29], v[154:157], v[210:213], v[26:29]
	v_mfma_f32_16x16x32_bf16 v[30:33], v[162:165], v[210:213], v[30:33]
	v_mfma_f32_16x16x32_bf16 v[58:61], v[158:161], v[190:193], v[58:61]
	v_mfma_f32_16x16x32_bf16 v[70:73], v[166:169], v[190:193], v[70:73]
	v_mfma_f32_16x16x32_bf16 v[42:45], v[158:161], v[198:201], v[42:45]
	v_mfma_f32_16x16x32_bf16 v[50:53], v[166:169], v[198:201], v[50:53]
	v_mfma_f32_16x16x32_bf16 v[34:37], v[158:161], v[206:209], v[34:37]
	v_mfma_f32_16x16x32_bf16 v[38:41], v[166:169], v[206:209], v[38:41]
	v_mfma_f32_16x16x32_bf16 v[26:29], v[158:161], v[214:217], v[26:29]
	v_mfma_f32_16x16x32_bf16 v[30:33], v[166:169], v[214:217], v[30:33]
	v_mfma_f32_16x16x32_bf16 v[106:109], v[170:173], v[186:189], v[106:109]
	v_mfma_f32_16x16x32_bf16 v[110:113], v[178:181], v[186:189], v[110:113]
	v_mfma_f32_16x16x32_bf16 v[98:101], v[170:173], v[194:197], v[98:101]
	v_mfma_f32_16x16x32_bf16 v[102:105], v[178:181], v[194:197], v[102:105]
	v_mfma_f32_16x16x32_bf16 v[90:93], v[170:173], v[202:205], v[90:93]
	v_mfma_f32_16x16x32_bf16 v[94:97], v[178:181], v[202:205], v[94:97]
	v_mfma_f32_16x16x32_bf16 v[82:85], v[170:173], v[210:213], v[82:85]
	v_mfma_f32_16x16x32_bf16 v[86:89], v[178:181], v[210:213], v[86:89]
	v_mfma_f32_16x16x32_bf16 v[106:109], v[174:177], v[190:193], v[106:109]
	v_mfma_f32_16x16x32_bf16 v[110:113], v[182:185], v[190:193], v[110:113]
	v_mfma_f32_16x16x32_bf16 v[98:101], v[174:177], v[198:201], v[98:101]
	v_mfma_f32_16x16x32_bf16 v[102:105], v[182:185], v[198:201], v[102:105]
	v_mfma_f32_16x16x32_bf16 v[90:93], v[174:177], v[206:209], v[90:93]
	v_mfma_f32_16x16x32_bf16 v[94:97], v[182:185], v[206:209], v[94:97]
	v_mfma_f32_16x16x32_bf16 v[82:85], v[174:177], v[214:217], v[82:85]
	v_mfma_f32_16x16x32_bf16 v[86:89], v[182:185], v[214:217], v[86:89]
	s_setprio 0
	s_barrier
	s_add_i32 m0, s53, 0xffffff80
	ds_read_b128 v[186:189], v150 offset:49152
	ds_read_b128 v[190:193], v150 offset:50176
	ds_read_b128 v[194:197], v150 offset:51200
	ds_read_b128 v[198:201], v150 offset:52224
	ds_read_b128 v[202:205], v150 offset:53248
	ds_read_b128 v[206:209], v150 offset:54272
	ds_read_b128 v[210:213], v150 offset:55296
	ds_read_b128 v[214:217], v150 offset:56320
	global_load_lds_dwordx4 v116, s[28:29] offset:128
	s_add_i32 m0, s54, 0xffffff80
	s_nop 0
	global_load_lds_dwordx4 v124, s[28:29] offset:128
	s_add_u32 s28, s28, 0xb0080
	s_addc_u32 s29, s29, 0
	s_mov_b32 m0, s55
	s_nop 0
	global_load_lds_dwordx4 v116, s[28:29]
	s_mov_b32 m0, s56
	s_nop 0
	global_load_lds_dwordx4 v124, s[28:29]
	s_add_i32 m0, s44, 0xffffff80
	s_nop 0
	global_load_lds_dwordx4 v114, s[30:31] offset:128
	s_add_i32 m0, s45, 0xffffff80
	s_nop 0
	global_load_lds_dwordx4 v122, s[30:31] offset:128
	s_waitcnt vmcnt(8)
	s_waitcnt lgkmcnt(0)
	s_barrier
	s_setprio 1
	v_mfma_f32_16x16x32_bf16 v[18:21], v[154:157], v[186:189], v[18:21]
	v_mfma_f32_16x16x32_bf16 v[22:25], v[162:165], v[186:189], v[22:25]
	v_mfma_f32_16x16x32_bf16 v[10:13], v[154:157], v[194:197], v[10:13]
	v_mfma_f32_16x16x32_bf16 v[14:17], v[162:165], v[194:197], v[14:17]
	v_mfma_f32_16x16x32_bf16 v[2:5], v[154:157], v[202:205], v[2:5]
	v_mfma_f32_16x16x32_bf16 v[6:9], v[162:165], v[202:205], v[6:9]
	v_mfma_f32_16x16x32_bf16 v[62:65], v[154:157], v[210:213], v[62:65]
	v_mfma_f32_16x16x32_bf16 v[74:77], v[162:165], v[210:213], v[74:77]
	v_mfma_f32_16x16x32_bf16 v[18:21], v[158:161], v[190:193], v[18:21]
	v_mfma_f32_16x16x32_bf16 v[22:25], v[166:169], v[190:193], v[22:25]
	v_mfma_f32_16x16x32_bf16 v[10:13], v[158:161], v[198:201], v[10:13]
	v_mfma_f32_16x16x32_bf16 v[14:17], v[166:169], v[198:201], v[14:17]
	v_mfma_f32_16x16x32_bf16 v[2:5], v[158:161], v[206:209], v[2:5]
	v_mfma_f32_16x16x32_bf16 v[6:9], v[166:169], v[206:209], v[6:9]
	v_mfma_f32_16x16x32_bf16 v[62:65], v[158:161], v[214:217], v[62:65]
	v_mfma_f32_16x16x32_bf16 v[74:77], v[166:169], v[214:217], v[74:77]
	v_mfma_f32_16x16x32_bf16 v[66:69], v[170:173], v[186:189], v[66:69]
	v_mfma_f32_16x16x32_bf16 v[78:81], v[178:181], v[186:189], v[78:81]
	v_mfma_f32_16x16x32_bf16 v[46:49], v[170:173], v[194:197], v[46:49]
	v_mfma_f32_16x16x32_bf16 v[54:57], v[178:181], v[194:197], v[54:57]
	v_mfma_f32_16x16x32_bf16 v[118:121], v[170:173], v[202:205], v[118:121]
	v_mfma_f32_16x16x32_bf16 v[126:129], v[178:181], v[202:205], v[126:129]
	v_mfma_f32_16x16x32_bf16 v[130:133], v[170:173], v[210:213], v[130:133]
	v_mfma_f32_16x16x32_bf16 v[134:137], v[178:181], v[210:213], v[134:137]
	v_mfma_f32_16x16x32_bf16 v[66:69], v[174:177], v[190:193], v[66:69]
	v_mfma_f32_16x16x32_bf16 v[78:81], v[182:185], v[190:193], v[78:81]
	v_mfma_f32_16x16x32_bf16 v[46:49], v[174:177], v[198:201], v[46:49]
	v_mfma_f32_16x16x32_bf16 v[54:57], v[182:185], v[198:201], v[54:57]
	v_mfma_f32_16x16x32_bf16 v[118:121], v[174:177], v[206:209], v[118:121]
	v_mfma_f32_16x16x32_bf16 v[126:129], v[182:185], v[206:209], v[126:129]
	v_mfma_f32_16x16x32_bf16 v[130:133], v[174:177], v[214:217], v[130:133]
	v_mfma_f32_16x16x32_bf16 v[134:137], v[182:185], v[214:217], v[134:137]
	s_setprio 0
	s_barrier
	s_add_i32 s46, s46, 2
	s_add_u32 s20, s20, 0x100
	s_addc_u32 s21, s21, 0
	s_cmp_lt_u32 s46, 34
	s_cbranch_scc1 .LBB0_2133
	s_waitcnt vmcnt(0)
	s_cmpk_gt_u32 s22, 0xff
	s_cbranch_scc1 .LBB0_2136
	s_barrier

.LBB0_2205:
	ds_read_b128 v[158:161], v152
	ds_read_b128 v[162:165], v152 offset:1024
	ds_read_b128 v[166:169], v152 offset:2048
	ds_read_b128 v[170:173], v152 offset:3072
	ds_read_b128 v[174:177], v153
	ds_read_b128 v[178:181], v153 offset:1024
	ds_read_b128 v[182:185], v153 offset:2048
	ds_read_b128 v[186:189], v153 offset:3072
	s_add_u32 s20, s26, s45
	s_addc_u32 s21, s27, s46
	s_add_u32 s60, s26, s47
	s_addc_u32 s61, s27, s48
	s_cmp_eq_u32 s49, 4
	s_cselect_b32 s25, s3, s21
	s_cselect_b32 s24, s2, s20
	s_cselect_b32 s21, s1, s61
	s_cselect_b32 s20, s0, s60
	s_mov_b32 m0, s50
	v_lshl_add_u64 v[222:223], s[26:27], 0, v[146:147]
	ds_read_b128 v[190:193], v154
	ds_read_b128 v[194:197], v154 offset:1024
	ds_read_b128 v[198:201], v154 offset:2048
	ds_read_b128 v[202:205], v154 offset:3072
	ds_read_b128 v[206:209], v154 offset:4096
	ds_read_b128 v[210:213], v154 offset:5120
	ds_read_b128 v[214:217], v154 offset:6144
	ds_read_b128 v[218:221], v154 offset:7168
	global_load_lds_dwordx4 v[222:223], off
	v_lshl_add_u64 v[222:223], s[26:27], 0, v[148:149]
	s_mov_b32 m0, s51
	s_nop 0
	global_load_lds_dwordx4 v[222:223], off
	s_waitcnt vmcnt(8)
	s_waitcnt lgkmcnt(0)
	s_barrier
	s_setprio 1
	v_mfma_f32_16x16x32_bf16 v[126:129], v[158:161], v[190:193], v[126:129]
	v_mfma_f32_16x16x32_bf16 v[122:125], v[166:169], v[190:193], v[122:125]
	v_mfma_f32_16x16x32_bf16 v[118:121], v[158:161], v[198:201], v[118:121]
	v_mfma_f32_16x16x32_bf16 v[114:117], v[166:169], v[198:201], v[114:117]
	v_mfma_f32_16x16x32_bf16 v[110:113], v[158:161], v[206:209], v[110:113]
	v_mfma_f32_16x16x32_bf16 v[106:109], v[166:169], v[206:209], v[106:109]
	v_mfma_f32_16x16x32_bf16 v[102:105], v[158:161], v[214:217], v[102:105]
	v_mfma_f32_16x16x32_bf16 v[98:101], v[166:169], v[214:217], v[98:101]
	v_mfma_f32_16x16x32_bf16 v[126:129], v[162:165], v[194:197], v[126:129]
	v_mfma_f32_16x16x32_bf16 v[122:125], v[170:173], v[194:197], v[122:125]
	v_mfma_f32_16x16x32_bf16 v[118:121], v[162:165], v[202:205], v[118:121]
	v_mfma_f32_16x16x32_bf16 v[114:117], v[170:173], v[202:205], v[114:117]
	v_mfma_f32_16x16x32_bf16 v[110:113], v[162:165], v[210:213], v[110:113]
	v_mfma_f32_16x16x32_bf16 v[106:109], v[170:173], v[210:213], v[106:109]
	v_mfma_f32_16x16x32_bf16 v[102:105], v[162:165], v[218:221], v[102:105]
	v_mfma_f32_16x16x32_bf16 v[98:101], v[170:173], v[218:221], v[98:101]
	v_mfma_f32_16x16x32_bf16 v[94:97], v[174:177], v[190:193], v[94:97]
	v_mfma_f32_16x16x32_bf16 v[90:93], v[182:185], v[190:193], v[90:93]
	v_mfma_f32_16x16x32_bf16 v[86:89], v[174:177], v[198:201], v[86:89]
	v_mfma_f32_16x16x32_bf16 v[82:85], v[182:185], v[198:201], v[82:85]
	v_mfma_f32_16x16x32_bf16 v[78:81], v[174:177], v[206:209], v[78:81]
	v_mfma_f32_16x16x32_bf16 v[74:77], v[182:185], v[206:209], v[74:77]
	v_mfma_f32_16x16x32_bf16 v[70:73], v[174:177], v[214:217], v[70:73]
	v_mfma_f32_16x16x32_bf16 v[66:69], v[182:185], v[214:217], v[66:69]
	v_mfma_f32_16x16x32_bf16 v[94:97], v[178:181], v[194:197], v[94:97]
	v_mfma_f32_16x16x32_bf16 v[90:93], v[186:189], v[194:197], v[90:93]
	v_mfma_f32_16x16x32_bf16 v[86:89], v[178:181], v[202:205], v[86:89]
	v_mfma_f32_16x16x32_bf16 v[82:85], v[186:189], v[202:205], v[82:85]
	v_mfma_f32_16x16x32_bf16 v[78:81], v[178:181], v[210:213], v[78:81]
	v_mfma_f32_16x16x32_bf16 v[74:77], v[186:189], v[210:213], v[74:77]
	v_mfma_f32_16x16x32_bf16 v[70:73], v[178:181], v[218:221], v[70:73]
	v_mfma_f32_16x16x32_bf16 v[66:69], v[186:189], v[218:221], v[66:69]
	s_setprio 0
	s_barrier
	s_mov_b32 m0, s52
	s_add_u32 s60, s20, 0xb0000
	ds_read_b128 v[190:193], v154 offset:16384
	ds_read_b128 v[194:197], v154 offset:17408
	ds_read_b128 v[198:201], v154 offset:18432
	ds_read_b128 v[202:205], v154 offset:19456
	ds_read_b128 v[206:209], v154 offset:20480
	ds_read_b128 v[210:213], v154 offset:21504
	ds_read_b128 v[214:217], v154 offset:22528
	ds_read_b128 v[218:221], v154 offset:23552
	global_load_lds_dwordx4 v132, s[20:21]
	s_mov_b32 m0, s53
	s_addc_u32 s61, s21, 0
	global_load_lds_dwordx4 v136, s[20:21]
	s_mov_b32 m0, s54
	s_nop 0
	global_load_lds_dwordx4 v132, s[60:61]
	s_mov_b32 m0, s55
	s_nop 0
	global_load_lds_dwordx4 v136, s[60:61]
	s_mov_b32 m0, s31
	s_nop 0
	global_load_lds_dwordx4 v130, s[24:25]
	s_mov_b32 m0, s34
	s_nop 0
	global_load_lds_dwordx4 v134, s[24:25]
	s_waitcnt vmcnt(8)
	s_waitcnt lgkmcnt(0)
	s_barrier
	s_setprio 1
	v_mfma_f32_16x16x32_bf16 v[62:65], v[158:161], v[190:193], v[62:65]
	v_mfma_f32_16x16x32_bf16 v[58:61], v[166:169], v[190:193], v[58:61]
	v_mfma_f32_16x16x32_bf16 v[54:57], v[158:161], v[198:201], v[54:57]
	v_mfma_f32_16x16x32_bf16 v[50:53], v[166:169], v[198:201], v[50:53]
	v_mfma_f32_16x16x32_bf16 v[46:49], v[158:161], v[206:209], v[46:49]
	v_mfma_f32_16x16x32_bf16 v[42:45], v[166:169], v[206:209], v[42:45]
	v_mfma_f32_16x16x32_bf16 v[38:41], v[158:161], v[214:217], v[38:41]
	v_mfma_f32_16x16x32_bf16 v[34:37], v[166:169], v[214:217], v[34:37]
	v_mfma_f32_16x16x32_bf16 v[62:65], v[162:165], v[194:197], v[62:65]
	v_mfma_f32_16x16x32_bf16 v[58:61], v[170:173], v[194:197], v[58:61]
	v_mfma_f32_16x16x32_bf16 v[54:57], v[162:165], v[202:205], v[54:57]
	v_mfma_f32_16x16x32_bf16 v[50:53], v[170:173], v[202:205], v[50:53]
	v_mfma_f32_16x16x32_bf16 v[46:49], v[162:165], v[210:213], v[46:49]
	v_mfma_f32_16x16x32_bf16 v[42:45], v[170:173], v[210:213], v[42:45]
	v_mfma_f32_16x16x32_bf16 v[38:41], v[162:165], v[218:221], v[38:41]
	v_mfma_f32_16x16x32_bf16 v[34:37], v[170:173], v[218:221], v[34:37]
	v_mfma_f32_16x16x32_bf16 v[30:33], v[174:177], v[190:193], v[30:33]
	v_mfma_f32_16x16x32_bf16 v[26:29], v[182:185], v[190:193], v[26:29]
	v_mfma_f32_16x16x32_bf16 v[22:25], v[174:177], v[198:201], v[22:25]
	v_mfma_f32_16x16x32_bf16 v[18:21], v[182:185], v[198:201], v[18:21]
	v_mfma_f32_16x16x32_bf16 v[14:17], v[174:177], v[206:209], v[14:17]
	v_mfma_f32_16x16x32_bf16 v[10:13], v[182:185], v[206:209], v[10:13]
	v_mfma_f32_16x16x32_bf16 v[6:9], v[174:177], v[214:217], v[6:9]
	v_mfma_f32_16x16x32_bf16 v[2:5], v[182:185], v[214:217], v[2:5]
	v_mfma_f32_16x16x32_bf16 v[30:33], v[178:181], v[194:197], v[30:33]
	v_mfma_f32_16x16x32_bf16 v[26:29], v[186:189], v[194:197], v[26:29]
	v_mfma_f32_16x16x32_bf16 v[22:25], v[178:181], v[202:205], v[22:25]
	v_mfma_f32_16x16x32_bf16 v[18:21], v[186:189], v[202:205], v[18:21]
	v_mfma_f32_16x16x32_bf16 v[14:17], v[178:181], v[210:213], v[14:17]
	v_mfma_f32_16x16x32_bf16 v[10:13], v[186:189], v[210:213], v[10:13]
	v_mfma_f32_16x16x32_bf16 v[6:9], v[178:181], v[218:221], v[6:9]
	v_mfma_f32_16x16x32_bf16 v[2:5], v[186:189], v[218:221], v[2:5]
	s_setprio 0
	s_barrier
	ds_read_b128 v[158:161], v155
	ds_read_b128 v[162:165], v155 offset:1024
	ds_read_b128 v[166:169], v155 offset:2048
	ds_read_b128 v[170:173], v155 offset:3072
	ds_read_b128 v[174:177], v156
	ds_read_b128 v[178:181], v156 offset:1024
	ds_read_b128 v[182:185], v156 offset:2048
	ds_read_b128 v[186:189], v156 offset:3072
	s_add_u32 s98, s24, 0xb0000
	s_addc_u32 s99, s25, 0
	s_mov_b32 m0, s35
	ds_read_b128 v[190:193], v154 offset:32768
	ds_read_b128 v[194:197], v154 offset:33792
	ds_read_b128 v[198:201], v154 offset:34816
	ds_read_b128 v[202:205], v154 offset:35840
	ds_read_b128 v[206:209], v154 offset:36864
	ds_read_b128 v[210:213], v154 offset:37888
	ds_read_b128 v[214:217], v154 offset:38912
	ds_read_b128 v[218:221], v154 offset:39936
	global_load_lds_dwordx4 v130, s[98:99]
	s_mov_b32 m0, s42
	s_nop 0
	global_load_lds_dwordx4 v134, s[98:99]
	s_waitcnt vmcnt(8)
	s_waitcnt lgkmcnt(0)
	s_barrier
	s_setprio 1
	v_mfma_f32_16x16x32_bf16 v[126:129], v[158:161], v[190:193], v[126:129]
	v_mfma_f32_16x16x32_bf16 v[122:125], v[166:169], v[190:193], v[122:125]
	v_mfma_f32_16x16x32_bf16 v[118:121], v[158:161], v[198:201], v[118:121]
	v_mfma_f32_16x16x32_bf16 v[114:117], v[166:169], v[198:201], v[114:117]
	v_mfma_f32_16x16x32_bf16 v[110:113], v[158:161], v[206:209], v[110:113]
	v_mfma_f32_16x16x32_bf16 v[106:109], v[166:169], v[206:209], v[106:109]
	v_mfma_f32_16x16x32_bf16 v[102:105], v[158:161], v[214:217], v[102:105]
	v_mfma_f32_16x16x32_bf16 v[98:101], v[166:169], v[214:217], v[98:101]
	v_mfma_f32_16x16x32_bf16 v[126:129], v[162:165], v[194:197], v[126:129]
	v_mfma_f32_16x16x32_bf16 v[122:125], v[170:173], v[194:197], v[122:125]
	v_mfma_f32_16x16x32_bf16 v[118:121], v[162:165], v[202:205], v[118:121]
	v_mfma_f32_16x16x32_bf16 v[114:117], v[170:173], v[202:205], v[114:117]
	v_mfma_f32_16x16x32_bf16 v[110:113], v[162:165], v[210:213], v[110:113]
	v_mfma_f32_16x16x32_bf16 v[106:109], v[170:173], v[210:213], v[106:109]
	v_mfma_f32_16x16x32_bf16 v[102:105], v[162:165], v[218:221], v[102:105]
	v_mfma_f32_16x16x32_bf16 v[98:101], v[170:173], v[218:221], v[98:101]
	v_mfma_f32_16x16x32_bf16 v[94:97], v[174:177], v[190:193], v[94:97]
	v_mfma_f32_16x16x32_bf16 v[90:93], v[182:185], v[190:193], v[90:93]
	v_mfma_f32_16x16x32_bf16 v[86:89], v[174:177], v[198:201], v[86:89]
	v_mfma_f32_16x16x32_bf16 v[82:85], v[182:185], v[198:201], v[82:85]
	v_mfma_f32_16x16x32_bf16 v[78:81], v[174:177], v[206:209], v[78:81]
	v_mfma_f32_16x16x32_bf16 v[74:77], v[182:185], v[206:209], v[74:77]
	v_mfma_f32_16x16x32_bf16 v[70:73], v[174:177], v[214:217], v[70:73]
	v_mfma_f32_16x16x32_bf16 v[66:69], v[182:185], v[214:217], v[66:69]
	v_mfma_f32_16x16x32_bf16 v[94:97], v[178:181], v[194:197], v[94:97]
	v_mfma_f32_16x16x32_bf16 v[90:93], v[186:189], v[194:197], v[90:93]
	v_mfma_f32_16x16x32_bf16 v[86:89], v[178:181], v[202:205], v[86:89]
	v_mfma_f32_16x16x32_bf16 v[82:85], v[186:189], v[202:205], v[82:85]
	v_mfma_f32_16x16x32_bf16 v[78:81], v[178:181], v[210:213], v[78:81]
	v_mfma_f32_16x16x32_bf16 v[74:77], v[186:189], v[210:213], v[74:77]
	v_mfma_f32_16x16x32_bf16 v[70:73], v[178:181], v[218:221], v[70:73]
	v_mfma_f32_16x16x32_bf16 v[66:69], v[186:189], v[218:221], v[66:69]
	s_setprio 0
	s_barrier
	s_add_i32 m0, s56, 0xffffff80
	ds_read_b128 v[190:193], v154 offset:49152
	ds_read_b128 v[194:197], v154 offset:50176
	ds_read_b128 v[198:201], v154 offset:51200
	ds_read_b128 v[202:205], v154 offset:52224
	ds_read_b128 v[206:209], v154 offset:53248
	ds_read_b128 v[210:213], v154 offset:54272
	ds_read_b128 v[214:217], v154 offset:55296
	ds_read_b128 v[218:221], v154 offset:56320
	global_load_lds_dwordx4 v132, s[20:21] offset:128
	s_add_i32 m0, s57, 0xffffff80
	s_nop 0
	global_load_lds_dwordx4 v136, s[20:21] offset:128
	s_add_u32 s20, s20, 0xb0080
	s_addc_u32 s21, s21, 0
	s_mov_b32 m0, s58
	s_nop 0
	global_load_lds_dwordx4 v132, s[20:21]
	s_mov_b32 m0, s59
	s_nop 0
	global_load_lds_dwordx4 v136, s[20:21]
	s_add_i32 m0, s43, 0xffffff80
	s_nop 0
	global_load_lds_dwordx4 v130, s[24:25] offset:128
	s_add_i32 m0, s44, 0xffffff80
	s_nop 0
	global_load_lds_dwordx4 v134, s[24:25] offset:128
	s_waitcnt vmcnt(8)
	s_waitcnt lgkmcnt(0)
	s_barrier
	s_setprio 1
	v_mfma_f32_16x16x32_bf16 v[62:65], v[158:161], v[190:193], v[62:65]
	v_mfma_f32_16x16x32_bf16 v[58:61], v[166:169], v[190:193], v[58:61]
	v_mfma_f32_16x16x32_bf16 v[54:57], v[158:161], v[198:201], v[54:57]
	v_mfma_f32_16x16x32_bf16 v[50:53], v[166:169], v[198:201], v[50:53]
	v_mfma_f32_16x16x32_bf16 v[46:49], v[158:161], v[206:209], v[46:49]
	v_mfma_f32_16x16x32_bf16 v[42:45], v[166:169], v[206:209], v[42:45]
	v_mfma_f32_16x16x32_bf16 v[38:41], v[158:161], v[214:217], v[38:41]
	v_mfma_f32_16x16x32_bf16 v[34:37], v[166:169], v[214:217], v[34:37]
	v_mfma_f32_16x16x32_bf16 v[62:65], v[162:165], v[194:197], v[62:65]
	v_mfma_f32_16x16x32_bf16 v[58:61], v[170:173], v[194:197], v[58:61]
	v_mfma_f32_16x16x32_bf16 v[54:57], v[162:165], v[202:205], v[54:57]
	v_mfma_f32_16x16x32_bf16 v[50:53], v[170:173], v[202:205], v[50:53]
	v_mfma_f32_16x16x32_bf16 v[46:49], v[162:165], v[210:213], v[46:49]
	v_mfma_f32_16x16x32_bf16 v[42:45], v[170:173], v[210:213], v[42:45]
	v_mfma_f32_16x16x32_bf16 v[38:41], v[162:165], v[218:221], v[38:41]
	v_mfma_f32_16x16x32_bf16 v[34:37], v[170:173], v[218:221], v[34:37]
	v_mfma_f32_16x16x32_bf16 v[30:33], v[174:177], v[190:193], v[30:33]
	v_mfma_f32_16x16x32_bf16 v[26:29], v[182:185], v[190:193], v[26:29]
	v_mfma_f32_16x16x32_bf16 v[22:25], v[174:177], v[198:201], v[22:25]
	v_mfma_f32_16x16x32_bf16 v[18:21], v[182:185], v[198:201], v[18:21]
	v_mfma_f32_16x16x32_bf16 v[14:17], v[174:177], v[206:209], v[14:17]
	v_mfma_f32_16x16x32_bf16 v[10:13], v[182:185], v[206:209], v[10:13]
	v_mfma_f32_16x16x32_bf16 v[6:9], v[174:177], v[214:217], v[6:9]
	v_mfma_f32_16x16x32_bf16 v[2:5], v[182:185], v[214:217], v[2:5]
	v_mfma_f32_16x16x32_bf16 v[30:33], v[178:181], v[194:197], v[30:33]
	v_mfma_f32_16x16x32_bf16 v[26:29], v[186:189], v[194:197], v[26:29]
	v_mfma_f32_16x16x32_bf16 v[22:25], v[178:181], v[202:205], v[22:25]
	v_mfma_f32_16x16x32_bf16 v[18:21], v[186:189], v[202:205], v[18:21]
	v_mfma_f32_16x16x32_bf16 v[14:17], v[178:181], v[210:213], v[14:17]
	v_mfma_f32_16x16x32_bf16 v[10:13], v[186:189], v[210:213], v[10:13]
	v_mfma_f32_16x16x32_bf16 v[6:9], v[178:181], v[218:221], v[6:9]
	v_mfma_f32_16x16x32_bf16 v[2:5], v[186:189], v[218:221], v[2:5]
	s_setprio 0
	s_barrier
	s_add_i32 s49, s49, 2
	s_add_u32 s45, s45, 0x100
	s_addc_u32 s46, s46, 0
	s_add_u32 s47, s47, 0x100
	s_addc_u32 s48, s48, 0
	v_lshl_add_u64 v[146:147], v[146:147], 0, s[18:19]
	s_cmp_lt_u32 s49, 6
	v_lshl_add_u64 v[148:149], v[148:149], 0, s[18:19]
	s_cbranch_scc1 .LBB0_2205
	s_waitcnt vmcnt(0)
	s_cmpk_gt_u32 s30, 0xff
	s_cbranch_scc1 .LBB0_2208
	s_barrier

.LBB0_2214:
	ds_read_b128 v[152:155], v144
	ds_read_b128 v[156:159], v144 offset:1024
	ds_read_b128 v[160:163], v144 offset:2048
	ds_read_b128 v[164:167], v144 offset:3072
	ds_read_b128 v[168:171], v145
	ds_read_b128 v[172:175], v145 offset:1024
	ds_read_b128 v[176:179], v145 offset:2048
	ds_read_b128 v[180:183], v145 offset:3072
	s_add_u32 s20, s26, s40
	s_addc_u32 s21, s27, s42
	s_add_u32 s56, s26, s43
	s_addc_u32 s57, s27, s44
	s_cmp_eq_u32 s45, 36
	s_cselect_b32 s25, s5, s21
	s_cselect_b32 s24, s4, s20
	s_cselect_b32 s21, s1, s57
	s_cselect_b32 s20, s0, s56
	s_mov_b32 m0, s46
	v_lshl_add_u64 v[216:217], s[26:27], 0, v[140:141]
	ds_read_b128 v[184:187], v146
	ds_read_b128 v[188:191], v146 offset:1024
	ds_read_b128 v[192:195], v146 offset:2048
	ds_read_b128 v[196:199], v146 offset:3072
	ds_read_b128 v[200:203], v146 offset:4096
	ds_read_b128 v[204:207], v146 offset:5120
	ds_read_b128 v[208:211], v146 offset:6144
	ds_read_b128 v[212:215], v146 offset:7168
	global_load_lds_dwordx4 v[216:217], off
	v_lshl_add_u64 v[216:217], s[26:27], 0, v[142:143]
	s_mov_b32 m0, s47
	s_nop 0
	global_load_lds_dwordx4 v[216:217], off
	s_waitcnt vmcnt(8)
	s_waitcnt lgkmcnt(0)
	s_barrier
	s_setprio 1
	v_mfma_f32_16x16x32_bf16 v[126:129], v[152:155], v[184:187], v[126:129]
	v_mfma_f32_16x16x32_bf16 v[122:125], v[160:163], v[184:187], v[122:125]
	v_mfma_f32_16x16x32_bf16 v[118:121], v[152:155], v[192:195], v[118:121]
	v_mfma_f32_16x16x32_bf16 v[114:117], v[160:163], v[192:195], v[114:117]
	v_mfma_f32_16x16x32_bf16 v[94:97], v[152:155], v[200:203], v[94:97]
	v_mfma_f32_16x16x32_bf16 v[90:93], v[160:163], v[200:203], v[90:93]
	v_mfma_f32_16x16x32_bf16 v[78:81], v[152:155], v[208:211], v[78:81]
	v_mfma_f32_16x16x32_bf16 v[74:77], v[160:163], v[208:211], v[74:77]
	v_mfma_f32_16x16x32_bf16 v[126:129], v[156:159], v[188:191], v[126:129]
	v_mfma_f32_16x16x32_bf16 v[122:125], v[164:167], v[188:191], v[122:125]
	v_mfma_f32_16x16x32_bf16 v[118:121], v[156:159], v[196:199], v[118:121]
	v_mfma_f32_16x16x32_bf16 v[114:117], v[164:167], v[196:199], v[114:117]
	v_mfma_f32_16x16x32_bf16 v[94:97], v[156:159], v[204:207], v[94:97]
	v_mfma_f32_16x16x32_bf16 v[90:93], v[164:167], v[204:207], v[90:93]
	v_mfma_f32_16x16x32_bf16 v[78:81], v[156:159], v[212:215], v[78:81]
	v_mfma_f32_16x16x32_bf16 v[74:77], v[164:167], v[212:215], v[74:77]
	v_mfma_f32_16x16x32_bf16 v[110:113], v[168:171], v[184:187], v[110:113]
	v_mfma_f32_16x16x32_bf16 v[106:109], v[176:179], v[184:187], v[106:109]
	v_mfma_f32_16x16x32_bf16 v[102:105], v[168:171], v[192:195], v[102:105]
	v_mfma_f32_16x16x32_bf16 v[98:101], v[176:179], v[192:195], v[98:101]
	v_mfma_f32_16x16x32_bf16 v[86:89], v[168:171], v[200:203], v[86:89]
	v_mfma_f32_16x16x32_bf16 v[82:85], v[176:179], v[200:203], v[82:85]
	v_mfma_f32_16x16x32_bf16 v[70:73], v[168:171], v[208:211], v[70:73]
	v_mfma_f32_16x16x32_bf16 v[66:69], v[176:179], v[208:211], v[66:69]
	v_mfma_f32_16x16x32_bf16 v[110:113], v[172:175], v[188:191], v[110:113]
	v_mfma_f32_16x16x32_bf16 v[106:109], v[180:183], v[188:191], v[106:109]
	v_mfma_f32_16x16x32_bf16 v[102:105], v[172:175], v[196:199], v[102:105]
	v_mfma_f32_16x16x32_bf16 v[98:101], v[180:183], v[196:199], v[98:101]
	v_mfma_f32_16x16x32_bf16 v[86:89], v[172:175], v[204:207], v[86:89]
	v_mfma_f32_16x16x32_bf16 v[82:85], v[180:183], v[204:207], v[82:85]
	v_mfma_f32_16x16x32_bf16 v[70:73], v[172:175], v[212:215], v[70:73]
	v_mfma_f32_16x16x32_bf16 v[66:69], v[180:183], v[212:215], v[66:69]
	s_setprio 0
	s_barrier
	s_mov_b32 m0, s48
	s_add_u32 s56, s20, 0xb0000
	ds_read_b128 v[184:187], v146 offset:16384
	ds_read_b128 v[188:191], v146 offset:17408
	ds_read_b128 v[192:195], v146 offset:18432
	ds_read_b128 v[196:199], v146 offset:19456
	ds_read_b128 v[200:203], v146 offset:20480
	ds_read_b128 v[204:207], v146 offset:21504
	ds_read_b128 v[208:211], v146 offset:22528
	ds_read_b128 v[212:215], v146 offset:23552
	global_load_lds_dwordx4 v132, s[20:21]
	s_mov_b32 m0, s49
	s_addc_u32 s57, s21, 0
	global_load_lds_dwordx4 v136, s[20:21]
	s_mov_b32 m0, s50
	s_nop 0
	global_load_lds_dwordx4 v132, s[56:57]
	s_mov_b32 m0, s51
	s_nop 0
	global_load_lds_dwordx4 v136, s[56:57]
	s_mov_b32 m0, s31
	s_nop 0
	global_load_lds_dwordx4 v130, s[24:25]
	s_mov_b32 m0, s34
	s_nop 0
	global_load_lds_dwordx4 v134, s[24:25]
	s_waitcnt vmcnt(8)
	s_waitcnt lgkmcnt(0)
	s_barrier
	s_setprio 1
	v_mfma_f32_16x16x32_bf16 v[62:65], v[152:155], v[184:187], v[62:65]
	v_mfma_f32_16x16x32_bf16 v[58:61], v[160:163], v[184:187], v[58:61]
	v_mfma_f32_16x16x32_bf16 v[46:49], v[152:155], v[192:195], v[46:49]
	v_mfma_f32_16x16x32_bf16 v[42:45], v[160:163], v[192:195], v[42:45]
	v_mfma_f32_16x16x32_bf16 v[30:33], v[152:155], v[200:203], v[30:33]
	v_mfma_f32_16x16x32_bf16 v[26:29], v[160:163], v[200:203], v[26:29]
	v_mfma_f32_16x16x32_bf16 v[14:17], v[152:155], v[208:211], v[14:17]
	v_mfma_f32_16x16x32_bf16 v[10:13], v[160:163], v[208:211], v[10:13]
	v_mfma_f32_16x16x32_bf16 v[62:65], v[156:159], v[188:191], v[62:65]
	v_mfma_f32_16x16x32_bf16 v[58:61], v[164:167], v[188:191], v[58:61]
	v_mfma_f32_16x16x32_bf16 v[46:49], v[156:159], v[196:199], v[46:49]
	v_mfma_f32_16x16x32_bf16 v[42:45], v[164:167], v[196:199], v[42:45]
	v_mfma_f32_16x16x32_bf16 v[30:33], v[156:159], v[204:207], v[30:33]
	v_mfma_f32_16x16x32_bf16 v[26:29], v[164:167], v[204:207], v[26:29]
	v_mfma_f32_16x16x32_bf16 v[14:17], v[156:159], v[212:215], v[14:17]
	v_mfma_f32_16x16x32_bf16 v[10:13], v[164:167], v[212:215], v[10:13]
	v_mfma_f32_16x16x32_bf16 v[54:57], v[168:171], v[184:187], v[54:57]
	v_mfma_f32_16x16x32_bf16 v[50:53], v[176:179], v[184:187], v[50:53]
	v_mfma_f32_16x16x32_bf16 v[38:41], v[168:171], v[192:195], v[38:41]
	v_mfma_f32_16x16x32_bf16 v[34:37], v[176:179], v[192:195], v[34:37]
	v_mfma_f32_16x16x32_bf16 v[22:25], v[168:171], v[200:203], v[22:25]
	v_mfma_f32_16x16x32_bf16 v[18:21], v[176:179], v[200:203], v[18:21]
	v_mfma_f32_16x16x32_bf16 v[6:9], v[168:171], v[208:211], v[6:9]
	v_mfma_f32_16x16x32_bf16 v[2:5], v[176:179], v[208:211], v[2:5]
	v_mfma_f32_16x16x32_bf16 v[54:57], v[172:175], v[188:191], v[54:57]
	v_mfma_f32_16x16x32_bf16 v[50:53], v[180:183], v[188:191], v[50:53]
	v_mfma_f32_16x16x32_bf16 v[38:41], v[172:175], v[196:199], v[38:41]
	v_mfma_f32_16x16x32_bf16 v[34:37], v[180:183], v[196:199], v[34:37]
	v_mfma_f32_16x16x32_bf16 v[22:25], v[172:175], v[204:207], v[22:25]
	v_mfma_f32_16x16x32_bf16 v[18:21], v[180:183], v[204:207], v[18:21]
	v_mfma_f32_16x16x32_bf16 v[6:9], v[172:175], v[212:215], v[6:9]
	v_mfma_f32_16x16x32_bf16 v[2:5], v[180:183], v[212:215], v[2:5]
	s_setprio 0
	s_barrier
	ds_read_b128 v[152:155], v147
	ds_read_b128 v[156:159], v147 offset:1024
	ds_read_b128 v[160:163], v147 offset:2048
	ds_read_b128 v[164:167], v147 offset:3072
	ds_read_b128 v[168:171], v148
	ds_read_b128 v[172:175], v148 offset:1024
	ds_read_b128 v[176:179], v148 offset:2048
	ds_read_b128 v[180:183], v148 offset:3072
	s_add_u32 s98, s24, 0xb0000
	s_addc_u32 s99, s25, 0
	s_mov_b32 m0, s35
	ds_read_b128 v[184:187], v146 offset:32768
	ds_read_b128 v[188:191], v146 offset:33792
	ds_read_b128 v[192:195], v146 offset:34816
	ds_read_b128 v[196:199], v146 offset:35840
	ds_read_b128 v[200:203], v146 offset:36864
	ds_read_b128 v[204:207], v146 offset:37888
	ds_read_b128 v[208:211], v146 offset:38912
	ds_read_b128 v[212:215], v146 offset:39936
	global_load_lds_dwordx4 v130, s[98:99]
	s_mov_b32 m0, s37
	s_nop 0
	global_load_lds_dwordx4 v134, s[98:99]
	s_waitcnt vmcnt(8)
	s_waitcnt lgkmcnt(0)
	s_barrier
	s_setprio 1
	v_mfma_f32_16x16x32_bf16 v[126:129], v[152:155], v[184:187], v[126:129]
	v_mfma_f32_16x16x32_bf16 v[122:125], v[160:163], v[184:187], v[122:125]
	v_mfma_f32_16x16x32_bf16 v[118:121], v[152:155], v[192:195], v[118:121]
	v_mfma_f32_16x16x32_bf16 v[114:117], v[160:163], v[192:195], v[114:117]
	v_mfma_f32_16x16x32_bf16 v[94:97], v[152:155], v[200:203], v[94:97]
	v_mfma_f32_16x16x32_bf16 v[90:93], v[160:163], v[200:203], v[90:93]
	v_mfma_f32_16x16x32_bf16 v[78:81], v[152:155], v[208:211], v[78:81]
	v_mfma_f32_16x16x32_bf16 v[74:77], v[160:163], v[208:211], v[74:77]
	v_mfma_f32_16x16x32_bf16 v[126:129], v[156:159], v[188:191], v[126:129]
	v_mfma_f32_16x16x32_bf16 v[122:125], v[164:167], v[188:191], v[122:125]
	v_mfma_f32_16x16x32_bf16 v[118:121], v[156:159], v[196:199], v[118:121]
	v_mfma_f32_16x16x32_bf16 v[114:117], v[164:167], v[196:199], v[114:117]
	v_mfma_f32_16x16x32_bf16 v[94:97], v[156:159], v[204:207], v[94:97]
	v_mfma_f32_16x16x32_bf16 v[90:93], v[164:167], v[204:207], v[90:93]
	v_mfma_f32_16x16x32_bf16 v[78:81], v[156:159], v[212:215], v[78:81]
	v_mfma_f32_16x16x32_bf16 v[74:77], v[164:167], v[212:215], v[74:77]
	v_mfma_f32_16x16x32_bf16 v[110:113], v[168:171], v[184:187], v[110:113]
	v_mfma_f32_16x16x32_bf16 v[106:109], v[176:179], v[184:187], v[106:109]
	v_mfma_f32_16x16x32_bf16 v[102:105], v[168:171], v[192:195], v[102:105]
	v_mfma_f32_16x16x32_bf16 v[98:101], v[176:179], v[192:195], v[98:101]
	v_mfma_f32_16x16x32_bf16 v[86:89], v[168:171], v[200:203], v[86:89]
	v_mfma_f32_16x16x32_bf16 v[82:85], v[176:179], v[200:203], v[82:85]
	v_mfma_f32_16x16x32_bf16 v[70:73], v[168:171], v[208:211], v[70:73]
	v_mfma_f32_16x16x32_bf16 v[66:69], v[176:179], v[208:211], v[66:69]
	v_mfma_f32_16x16x32_bf16 v[110:113], v[172:175], v[188:191], v[110:113]
	v_mfma_f32_16x16x32_bf16 v[106:109], v[180:183], v[188:191], v[106:109]
	v_mfma_f32_16x16x32_bf16 v[102:105], v[172:175], v[196:199], v[102:105]
	v_mfma_f32_16x16x32_bf16 v[98:101], v[180:183], v[196:199], v[98:101]
	v_mfma_f32_16x16x32_bf16 v[86:89], v[172:175], v[204:207], v[86:89]
	v_mfma_f32_16x16x32_bf16 v[82:85], v[180:183], v[204:207], v[82:85]
	v_mfma_f32_16x16x32_bf16 v[70:73], v[172:175], v[212:215], v[70:73]
	v_mfma_f32_16x16x32_bf16 v[66:69], v[180:183], v[212:215], v[66:69]
	s_setprio 0
	s_barrier
	s_add_i32 m0, s52, 0xffffff80
	ds_read_b128 v[184:187], v146 offset:49152
	ds_read_b128 v[188:191], v146 offset:50176
	ds_read_b128 v[192:195], v146 offset:51200
	ds_read_b128 v[196:199], v146 offset:52224
	ds_read_b128 v[200:203], v146 offset:53248
	ds_read_b128 v[204:207], v146 offset:54272
	ds_read_b128 v[208:211], v146 offset:55296
	ds_read_b128 v[212:215], v146 offset:56320
	global_load_lds_dwordx4 v132, s[20:21] offset:128
	s_add_i32 m0, s53, 0xffffff80
	s_nop 0
	global_load_lds_dwordx4 v136, s[20:21] offset:128
	s_add_u32 s20, s20, 0xb0080
	s_addc_u32 s21, s21, 0
	s_mov_b32 m0, s54
	s_nop 0
	global_load_lds_dwordx4 v132, s[20:21]
	s_mov_b32 m0, s55
	s_nop 0
	global_load_lds_dwordx4 v136, s[20:21]
	s_add_i32 m0, s38, 0xffffff80
	s_nop 0
	global_load_lds_dwordx4 v130, s[24:25] offset:128
	s_add_i32 m0, s39, 0xffffff80
	s_nop 0
	global_load_lds_dwordx4 v134, s[24:25] offset:128
	s_waitcnt vmcnt(8)
	s_waitcnt lgkmcnt(0)
	s_barrier
	s_setprio 1
	v_mfma_f32_16x16x32_bf16 v[62:65], v[152:155], v[184:187], v[62:65]
	v_mfma_f32_16x16x32_bf16 v[58:61], v[160:163], v[184:187], v[58:61]
	v_mfma_f32_16x16x32_bf16 v[46:49], v[152:155], v[192:195], v[46:49]
	v_mfma_f32_16x16x32_bf16 v[42:45], v[160:163], v[192:195], v[42:45]
	v_mfma_f32_16x16x32_bf16 v[30:33], v[152:155], v[200:203], v[30:33]
	v_mfma_f32_16x16x32_bf16 v[26:29], v[160:163], v[200:203], v[26:29]
	v_mfma_f32_16x16x32_bf16 v[14:17], v[152:155], v[208:211], v[14:17]
	v_mfma_f32_16x16x32_bf16 v[10:13], v[160:163], v[208:211], v[10:13]
	v_mfma_f32_16x16x32_bf16 v[62:65], v[156:159], v[188:191], v[62:65]
	v_mfma_f32_16x16x32_bf16 v[58:61], v[164:167], v[188:191], v[58:61]
	v_mfma_f32_16x16x32_bf16 v[46:49], v[156:159], v[196:199], v[46:49]
	v_mfma_f32_16x16x32_bf16 v[42:45], v[164:167], v[196:199], v[42:45]
	v_mfma_f32_16x16x32_bf16 v[30:33], v[156:159], v[204:207], v[30:33]
	v_mfma_f32_16x16x32_bf16 v[26:29], v[164:167], v[204:207], v[26:29]
	v_mfma_f32_16x16x32_bf16 v[14:17], v[156:159], v[212:215], v[14:17]
	v_mfma_f32_16x16x32_bf16 v[10:13], v[164:167], v[212:215], v[10:13]
	v_mfma_f32_16x16x32_bf16 v[54:57], v[168:171], v[184:187], v[54:57]
	v_mfma_f32_16x16x32_bf16 v[50:53], v[176:179], v[184:187], v[50:53]
	v_mfma_f32_16x16x32_bf16 v[38:41], v[168:171], v[192:195], v[38:41]
	v_mfma_f32_16x16x32_bf16 v[34:37], v[176:179], v[192:195], v[34:37]
	v_mfma_f32_16x16x32_bf16 v[22:25], v[168:171], v[200:203], v[22:25]
	v_mfma_f32_16x16x32_bf16 v[18:21], v[176:179], v[200:203], v[18:21]
	v_mfma_f32_16x16x32_bf16 v[6:9], v[168:171], v[208:211], v[6:9]
	v_mfma_f32_16x16x32_bf16 v[2:5], v[176:179], v[208:211], v[2:5]
	v_mfma_f32_16x16x32_bf16 v[54:57], v[172:175], v[188:191], v[54:57]
	v_mfma_f32_16x16x32_bf16 v[50:53], v[180:183], v[188:191], v[50:53]
	v_mfma_f32_16x16x32_bf16 v[38:41], v[172:175], v[196:199], v[38:41]
	v_mfma_f32_16x16x32_bf16 v[34:37], v[180:183], v[196:199], v[34:37]
	v_mfma_f32_16x16x32_bf16 v[22:25], v[172:175], v[204:207], v[22:25]
	v_mfma_f32_16x16x32_bf16 v[18:21], v[180:183], v[204:207], v[18:21]
	v_mfma_f32_16x16x32_bf16 v[6:9], v[172:175], v[212:215], v[6:9]
	v_mfma_f32_16x16x32_bf16 v[2:5], v[180:183], v[212:215], v[2:5]
	s_setprio 0
	s_barrier
	s_add_i32 s45, s45, 2
	s_add_u32 s40, s40, 0x100
	s_addc_u32 s42, s42, 0
	s_add_u32 s43, s43, 0x100
	s_addc_u32 s44, s44, 0
	v_lshl_add_u64 v[140:141], v[140:141], 0, s[18:19]
	s_cmp_lt_u32 s45, 38
	v_lshl_add_u64 v[142:143], v[142:143], 0, s[18:19]
	s_cbranch_scc1 .LBB0_2214
	s_waitcnt vmcnt(0)
	s_cmpk_gt_u32 s30, 0xff
	s_cbranch_scc1 .LBB0_2217
	s_barrier

.LBB0_2235:
	ds_read_b128 v[144:147], v139
	ds_read_b128 v[148:151], v139 offset:1024
	ds_read_b128 v[158:161], v139 offset:2048
	ds_read_b128 v[162:165], v139 offset:3072
	ds_read_b128 v[166:169], v140
	ds_read_b128 v[170:173], v140 offset:1024
	ds_read_b128 v[174:177], v140 offset:2048
	ds_read_b128 v[178:181], v140 offset:3072
	s_add_i32 s18, s44, 0x100
	s_and_b64 s[16:17], s[16:17], exec
	s_cselect_b32 s16, 0, s18
	s_cselect_b32 s17, 0, 0
	s_add_u32 s18, s4, s16
	s_addc_u32 s19, s5, s17
	s_add_u32 s16, s0, s16
	s_addc_u32 s17, s1, s17
	s_add_u32 s44, s4, s44
	s_addc_u32 s45, s5, 0
	s_add_u32 s44, s44, 0xb0080
	s_addc_u32 s45, s45, 0
	s_mov_b32 m0, s38
	v_lshl_add_u64 v[154:155], s[44:45], 0, v[130:131]
	ds_read_b128 v[182:185], v141
	ds_read_b128 v[186:189], v141 offset:1024
	ds_read_b128 v[190:193], v141 offset:2048
	ds_read_b128 v[194:197], v141 offset:3072
	ds_read_b128 v[198:201], v141 offset:4096
	ds_read_b128 v[202:205], v141 offset:5120
	ds_read_b128 v[206:209], v141 offset:6144
	ds_read_b128 v[210:213], v141 offset:7168
	global_load_lds_dwordx4 v[154:155], off
	v_lshl_add_u64 v[154:155], s[44:45], 0, v[134:135]
	s_mov_b32 m0, s39
	s_nop 0
	global_load_lds_dwordx4 v[154:155], off
	s_waitcnt vmcnt(8)
	s_waitcnt lgkmcnt(0)
	s_barrier
	s_setprio 1
	v_mfma_f32_16x16x32_bf16 v[126:129], v[144:147], v[182:185], v[126:129]
	v_mfma_f32_16x16x32_bf16 v[122:125], v[158:161], v[182:185], v[122:125]
	v_mfma_f32_16x16x32_bf16 v[118:121], v[144:147], v[190:193], v[118:121]
	v_mfma_f32_16x16x32_bf16 v[114:117], v[158:161], v[190:193], v[114:117]
	v_mfma_f32_16x16x32_bf16 v[94:97], v[144:147], v[198:201], v[94:97]
	v_mfma_f32_16x16x32_bf16 v[90:93], v[158:161], v[198:201], v[90:93]
	v_mfma_f32_16x16x32_bf16 v[78:81], v[144:147], v[206:209], v[78:81]
	v_mfma_f32_16x16x32_bf16 v[74:77], v[158:161], v[206:209], v[74:77]
	v_mfma_f32_16x16x32_bf16 v[126:129], v[148:151], v[186:189], v[126:129]
	v_mfma_f32_16x16x32_bf16 v[122:125], v[162:165], v[186:189], v[122:125]
	v_mfma_f32_16x16x32_bf16 v[118:121], v[148:151], v[194:197], v[118:121]
	v_mfma_f32_16x16x32_bf16 v[114:117], v[162:165], v[194:197], v[114:117]
	v_mfma_f32_16x16x32_bf16 v[94:97], v[148:151], v[202:205], v[94:97]
	v_mfma_f32_16x16x32_bf16 v[90:93], v[162:165], v[202:205], v[90:93]
	v_mfma_f32_16x16x32_bf16 v[78:81], v[148:151], v[210:213], v[78:81]
	v_mfma_f32_16x16x32_bf16 v[74:77], v[162:165], v[210:213], v[74:77]
	v_mfma_f32_16x16x32_bf16 v[110:113], v[166:169], v[182:185], v[110:113]
	v_mfma_f32_16x16x32_bf16 v[106:109], v[174:177], v[182:185], v[106:109]
	v_mfma_f32_16x16x32_bf16 v[102:105], v[166:169], v[190:193], v[102:105]
	v_mfma_f32_16x16x32_bf16 v[98:101], v[174:177], v[190:193], v[98:101]
	v_mfma_f32_16x16x32_bf16 v[86:89], v[166:169], v[198:201], v[86:89]
	v_mfma_f32_16x16x32_bf16 v[82:85], v[174:177], v[198:201], v[82:85]
	v_mfma_f32_16x16x32_bf16 v[70:73], v[166:169], v[206:209], v[70:73]
	v_mfma_f32_16x16x32_bf16 v[66:69], v[174:177], v[206:209], v[66:69]
	v_mfma_f32_16x16x32_bf16 v[110:113], v[170:173], v[186:189], v[110:113]
	v_mfma_f32_16x16x32_bf16 v[106:109], v[178:181], v[186:189], v[106:109]
	v_mfma_f32_16x16x32_bf16 v[102:105], v[170:173], v[194:197], v[102:105]
	v_mfma_f32_16x16x32_bf16 v[98:101], v[178:181], v[194:197], v[98:101]
	v_mfma_f32_16x16x32_bf16 v[86:89], v[170:173], v[202:205], v[86:89]
	v_mfma_f32_16x16x32_bf16 v[82:85], v[178:181], v[202:205], v[82:85]
	v_mfma_f32_16x16x32_bf16 v[70:73], v[170:173], v[210:213], v[70:73]
	v_mfma_f32_16x16x32_bf16 v[66:69], v[178:181], v[210:213], v[66:69]
	s_setprio 0
	s_barrier
	s_mov_b32 m0, s22
	v_lshl_add_u64 v[154:155], s[16:17], 0, v[132:133]
	s_add_u32 s44, s16, 0xb0000
	ds_read_b128 v[182:185], v141 offset:16384
	ds_read_b128 v[186:189], v141 offset:17408
	ds_read_b128 v[190:193], v141 offset:18432
	ds_read_b128 v[194:197], v141 offset:19456
	ds_read_b128 v[198:201], v141 offset:20480
	ds_read_b128 v[202:205], v141 offset:21504
	ds_read_b128 v[206:209], v141 offset:22528
	ds_read_b128 v[210:213], v141 offset:23552
	global_load_lds_dwordx4 v[154:155], off
	v_lshl_add_u64 v[214:215], s[16:17], 0, v[136:137]
	s_mov_b32 m0, s40
	s_addc_u32 s45, s17, 0
	global_load_lds_dwordx4 v[214:215], off
	v_lshl_add_u64 v[216:217], s[44:45], 0, v[132:133]
	s_mov_b32 m0, s23
	v_lshl_add_u64 v[218:219], s[18:19], 0, v[134:135]
	global_load_lds_dwordx4 v[216:217], off
	v_lshl_add_u64 v[216:217], s[44:45], 0, v[136:137]
	s_mov_b32 m0, s41
	s_nop 0
	global_load_lds_dwordx4 v[216:217], off
	v_lshl_add_u64 v[216:217], s[18:19], 0, v[130:131]
	s_mov_b32 m0, s25
	s_nop 0
	global_load_lds_dwordx4 v[216:217], off
	s_mov_b32 m0, s30
	s_nop 0
	global_load_lds_dwordx4 v[218:219], off
	s_waitcnt vmcnt(8)
	s_waitcnt lgkmcnt(0)
	s_barrier
	s_setprio 1
	v_mfma_f32_16x16x32_bf16 v[62:65], v[144:147], v[182:185], v[62:65]
	v_mfma_f32_16x16x32_bf16 v[58:61], v[158:161], v[182:185], v[58:61]
	v_mfma_f32_16x16x32_bf16 v[46:49], v[144:147], v[190:193], v[46:49]
	v_mfma_f32_16x16x32_bf16 v[42:45], v[158:161], v[190:193], v[42:45]
	v_mfma_f32_16x16x32_bf16 v[30:33], v[144:147], v[198:201], v[30:33]
	v_mfma_f32_16x16x32_bf16 v[26:29], v[158:161], v[198:201], v[26:29]
	v_mfma_f32_16x16x32_bf16 v[14:17], v[144:147], v[206:209], v[14:17]
	v_mfma_f32_16x16x32_bf16 v[10:13], v[158:161], v[206:209], v[10:13]
	v_mfma_f32_16x16x32_bf16 v[62:65], v[148:151], v[186:189], v[62:65]
	v_mfma_f32_16x16x32_bf16 v[58:61], v[162:165], v[186:189], v[58:61]
	v_mfma_f32_16x16x32_bf16 v[46:49], v[148:151], v[194:197], v[46:49]
	v_mfma_f32_16x16x32_bf16 v[42:45], v[162:165], v[194:197], v[42:45]
	v_mfma_f32_16x16x32_bf16 v[30:33], v[148:151], v[202:205], v[30:33]
	v_mfma_f32_16x16x32_bf16 v[26:29], v[162:165], v[202:205], v[26:29]
	v_mfma_f32_16x16x32_bf16 v[14:17], v[148:151], v[210:213], v[14:17]
	v_mfma_f32_16x16x32_bf16 v[10:13], v[162:165], v[210:213], v[10:13]
	v_mfma_f32_16x16x32_bf16 v[54:57], v[166:169], v[182:185], v[54:57]
	v_mfma_f32_16x16x32_bf16 v[50:53], v[174:177], v[182:185], v[50:53]
	v_mfma_f32_16x16x32_bf16 v[38:41], v[166:169], v[190:193], v[38:41]
	v_mfma_f32_16x16x32_bf16 v[34:37], v[174:177], v[190:193], v[34:37]
	v_mfma_f32_16x16x32_bf16 v[22:25], v[166:169], v[198:201], v[22:25]
	v_mfma_f32_16x16x32_bf16 v[18:21], v[174:177], v[198:201], v[18:21]
	v_mfma_f32_16x16x32_bf16 v[6:9], v[166:169], v[206:209], v[6:9]
	v_mfma_f32_16x16x32_bf16 v[2:5], v[174:177], v[206:209], v[2:5]
	v_mfma_f32_16x16x32_bf16 v[54:57], v[170:173], v[186:189], v[54:57]
	v_mfma_f32_16x16x32_bf16 v[50:53], v[178:181], v[186:189], v[50:53]
	v_mfma_f32_16x16x32_bf16 v[38:41], v[170:173], v[194:197], v[38:41]
	v_mfma_f32_16x16x32_bf16 v[34:37], v[178:181], v[194:197], v[34:37]
	v_mfma_f32_16x16x32_bf16 v[22:25], v[170:173], v[202:205], v[22:25]
	v_mfma_f32_16x16x32_bf16 v[18:21], v[178:181], v[202:205], v[18:21]
	v_mfma_f32_16x16x32_bf16 v[6:9], v[170:173], v[210:213], v[6:9]
	v_mfma_f32_16x16x32_bf16 v[2:5], v[178:181], v[210:213], v[2:5]
	s_setprio 0
	s_barrier
	ds_read_b128 v[144:147], v142
	ds_read_b128 v[148:151], v142 offset:1024
	ds_read_b128 v[158:161], v142 offset:2048
	ds_read_b128 v[162:165], v142 offset:3072
	ds_read_b128 v[166:169], v143
	ds_read_b128 v[170:173], v143 offset:1024
	ds_read_b128 v[174:177], v143 offset:2048
	ds_read_b128 v[178:181], v143 offset:3072
	s_add_u32 s18, s18, 0xb0000
	s_addc_u32 s19, s19, 0
	s_mov_b32 m0, s31
	v_lshl_add_u64 v[220:221], s[18:19], 0, v[130:131]
	ds_read_b128 v[182:185], v141 offset:32768
	ds_read_b128 v[186:189], v141 offset:33792
	ds_read_b128 v[190:193], v141 offset:34816
	ds_read_b128 v[194:197], v141 offset:35840
	ds_read_b128 v[198:201], v141 offset:36864
	ds_read_b128 v[202:205], v141 offset:37888
	ds_read_b128 v[206:209], v141 offset:38912
	ds_read_b128 v[210:213], v141 offset:39936
	global_load_lds_dwordx4 v[220:221], off
	v_lshl_add_u64 v[220:221], s[18:19], 0, v[134:135]
	s_mov_b32 m0, s34
	s_nop 0
	global_load_lds_dwordx4 v[220:221], off
	s_waitcnt vmcnt(8)
	s_waitcnt lgkmcnt(0)
	s_barrier
	s_setprio 1
	v_mfma_f32_16x16x32_bf16 v[126:129], v[144:147], v[182:185], v[126:129]
	v_mfma_f32_16x16x32_bf16 v[122:125], v[158:161], v[182:185], v[122:125]
	v_mfma_f32_16x16x32_bf16 v[118:121], v[144:147], v[190:193], v[118:121]
	v_mfma_f32_16x16x32_bf16 v[114:117], v[158:161], v[190:193], v[114:117]
	v_mfma_f32_16x16x32_bf16 v[94:97], v[144:147], v[198:201], v[94:97]
	v_mfma_f32_16x16x32_bf16 v[90:93], v[158:161], v[198:201], v[90:93]
	v_mfma_f32_16x16x32_bf16 v[78:81], v[144:147], v[206:209], v[78:81]
	v_mfma_f32_16x16x32_bf16 v[74:77], v[158:161], v[206:209], v[74:77]
	v_mfma_f32_16x16x32_bf16 v[126:129], v[148:151], v[186:189], v[126:129]
	v_mfma_f32_16x16x32_bf16 v[122:125], v[162:165], v[186:189], v[122:125]
	v_mfma_f32_16x16x32_bf16 v[118:121], v[148:151], v[194:197], v[118:121]
	v_mfma_f32_16x16x32_bf16 v[114:117], v[162:165], v[194:197], v[114:117]
	v_mfma_f32_16x16x32_bf16 v[94:97], v[148:151], v[202:205], v[94:97]
	v_mfma_f32_16x16x32_bf16 v[90:93], v[162:165], v[202:205], v[90:93]
	v_mfma_f32_16x16x32_bf16 v[78:81], v[148:151], v[210:213], v[78:81]
	v_mfma_f32_16x16x32_bf16 v[74:77], v[162:165], v[210:213], v[74:77]
	v_mfma_f32_16x16x32_bf16 v[110:113], v[166:169], v[182:185], v[110:113]
	v_mfma_f32_16x16x32_bf16 v[106:109], v[174:177], v[182:185], v[106:109]
	v_mfma_f32_16x16x32_bf16 v[102:105], v[166:169], v[190:193], v[102:105]
	v_mfma_f32_16x16x32_bf16 v[98:101], v[174:177], v[190:193], v[98:101]
	v_mfma_f32_16x16x32_bf16 v[86:89], v[166:169], v[198:201], v[86:89]
	v_mfma_f32_16x16x32_bf16 v[82:85], v[174:177], v[198:201], v[82:85]
	v_mfma_f32_16x16x32_bf16 v[70:73], v[166:169], v[206:209], v[70:73]
	v_mfma_f32_16x16x32_bf16 v[66:69], v[174:177], v[206:209], v[66:69]
	v_mfma_f32_16x16x32_bf16 v[110:113], v[170:173], v[186:189], v[110:113]
	v_mfma_f32_16x16x32_bf16 v[106:109], v[178:181], v[186:189], v[106:109]
	v_mfma_f32_16x16x32_bf16 v[102:105], v[170:173], v[194:197], v[102:105]
	v_mfma_f32_16x16x32_bf16 v[98:101], v[178:181], v[194:197], v[98:101]
	v_mfma_f32_16x16x32_bf16 v[86:89], v[170:173], v[202:205], v[86:89]
	v_mfma_f32_16x16x32_bf16 v[82:85], v[178:181], v[202:205], v[82:85]
	v_mfma_f32_16x16x32_bf16 v[70:73], v[170:173], v[210:213], v[70:73]
	v_mfma_f32_16x16x32_bf16 v[66:69], v[178:181], v[210:213], v[66:69]
	s_setprio 0
	s_barrier
	s_mov_b32 m0, s28
	v_lshl_add_u64 v[154:155], v[154:155], 0, s[6:7]
	s_add_u32 s16, s16, 0xb0080
	ds_read_b128 v[182:185], v141 offset:49152
	ds_read_b128 v[186:189], v141 offset:50176
	ds_read_b128 v[190:193], v141 offset:51200
	ds_read_b128 v[194:197], v141 offset:52224
	ds_read_b128 v[198:201], v141 offset:53248
	ds_read_b128 v[202:205], v141 offset:54272
	ds_read_b128 v[206:209], v141 offset:55296
	ds_read_b128 v[210:213], v141 offset:56320
	global_load_lds_dwordx4 v[154:155], off
	v_lshl_add_u64 v[154:155], v[214:215], 0, s[6:7]
	s_mov_b32 m0, s42
	s_addc_u32 s17, s17, 0
	global_load_lds_dwordx4 v[154:155], off
	v_lshl_add_u64 v[154:155], s[16:17], 0, v[132:133]
	s_mov_b32 m0, s29
	s_nop 0
	global_load_lds_dwordx4 v[154:155], off
	v_lshl_add_u64 v[154:155], s[16:17], 0, v[136:137]
	s_mov_b32 m0, s43
	s_nop 0
	global_load_lds_dwordx4 v[154:155], off
	v_lshl_add_u64 v[154:155], v[216:217], 0, s[6:7]
	s_mov_b32 m0, s35
	s_nop 0
	global_load_lds_dwordx4 v[154:155], off
	v_lshl_add_u64 v[154:155], v[218:219], 0, s[6:7]
	s_mov_b32 m0, s37
	s_nop 0
	global_load_lds_dwordx4 v[154:155], off
	s_waitcnt vmcnt(8)
	s_waitcnt lgkmcnt(0)
	s_barrier
	s_setprio 1
	v_mfma_f32_16x16x32_bf16 v[62:65], v[144:147], v[182:185], v[62:65]
	v_mfma_f32_16x16x32_bf16 v[58:61], v[158:161], v[182:185], v[58:61]
	v_mfma_f32_16x16x32_bf16 v[46:49], v[144:147], v[190:193], v[46:49]
	v_mfma_f32_16x16x32_bf16 v[42:45], v[158:161], v[190:193], v[42:45]
	v_mfma_f32_16x16x32_bf16 v[30:33], v[144:147], v[198:201], v[30:33]
	v_mfma_f32_16x16x32_bf16 v[26:29], v[158:161], v[198:201], v[26:29]
	v_mfma_f32_16x16x32_bf16 v[14:17], v[144:147], v[206:209], v[14:17]
	v_mfma_f32_16x16x32_bf16 v[10:13], v[158:161], v[206:209], v[10:13]
	v_mfma_f32_16x16x32_bf16 v[62:65], v[148:151], v[186:189], v[62:65]
	v_mfma_f32_16x16x32_bf16 v[58:61], v[162:165], v[186:189], v[58:61]
	v_mfma_f32_16x16x32_bf16 v[46:49], v[148:151], v[194:197], v[46:49]
	v_mfma_f32_16x16x32_bf16 v[42:45], v[162:165], v[194:197], v[42:45]
	v_mfma_f32_16x16x32_bf16 v[30:33], v[148:151], v[202:205], v[30:33]
	v_mfma_f32_16x16x32_bf16 v[26:29], v[162:165], v[202:205], v[26:29]
	v_mfma_f32_16x16x32_bf16 v[14:17], v[148:151], v[210:213], v[14:17]
	v_mfma_f32_16x16x32_bf16 v[10:13], v[162:165], v[210:213], v[10:13]
	v_mfma_f32_16x16x32_bf16 v[54:57], v[166:169], v[182:185], v[54:57]
	v_mfma_f32_16x16x32_bf16 v[50:53], v[174:177], v[182:185], v[50:53]
	v_mfma_f32_16x16x32_bf16 v[38:41], v[166:169], v[190:193], v[38:41]
	v_mfma_f32_16x16x32_bf16 v[34:37], v[174:177], v[190:193], v[34:37]
	v_mfma_f32_16x16x32_bf16 v[22:25], v[166:169], v[198:201], v[22:25]
	v_mfma_f32_16x16x32_bf16 v[18:21], v[174:177], v[198:201], v[18:21]
	v_mfma_f32_16x16x32_bf16 v[6:9], v[166:169], v[206:209], v[6:9]
	v_mfma_f32_16x16x32_bf16 v[2:5], v[174:177], v[206:209], v[2:5]
	v_mfma_f32_16x16x32_bf16 v[54:57], v[170:173], v[186:189], v[54:57]
	v_mfma_f32_16x16x32_bf16 v[50:53], v[178:181], v[186:189], v[50:53]
	v_mfma_f32_16x16x32_bf16 v[38:41], v[170:173], v[194:197], v[38:41]
	v_mfma_f32_16x16x32_bf16 v[34:37], v[178:181], v[194:197], v[34:37]
	v_mfma_f32_16x16x32_bf16 v[22:25], v[170:173], v[202:205], v[22:25]
	v_mfma_f32_16x16x32_bf16 v[18:21], v[178:181], v[202:205], v[18:21]
	v_mfma_f32_16x16x32_bf16 v[6:9], v[170:173], v[210:213], v[6:9]
	v_mfma_f32_16x16x32_bf16 v[2:5], v[178:181], v[210:213], v[2:5]
	s_setprio 0
	s_barrier
	s_and_b64 vcc, exec, s[14:15]
	s_mov_b64 s[16:17], -1
	s_mov_b64 s[14:15], 0
	s_movk_i32 s44, 0x100
	s_cbranch_vccnz .LBB0_2235
	s_waitcnt vmcnt(0)
	s_cmpk_gt_u32 s20, 0xff
	s_cbranch_scc1 .LBB0_2238
	s_barrier
